# E1 epilogue: accumulator groups c and c+4 (adjacent 16-column blocks of one row block) stored as one 16-byte store per lane via v_permlane16_swap, in all three branches
# baseline (speedup 1.0000x reference)
; template <int MT, class Epi>
; DI void gemm_tile(const u16* __restrict__ X, long ldx, const u16* __restrict__ W, long ldw, int K, char* smem,
;                   int m0, int n0, const Epi& epi, bool pre = false, const u16* Xn = nullptr, const u16* Wn = nullptr) {
;     ...
;   if (!pre) {
;     __syncthreads();
;     GT_DMA(0u)
;   } else {
;     xe += 64; xo += 64; we += 64; wo += 64;
;   }
;   const int nk = K >> 6;
;   int kt = 0;
;   do {
;     asm volatile("s_waitcnt vmcnt(0)" ::: "memory");
;     __syncthreads();
;     if (kt + 1 < nk) GT_DMA((unsigned)((kt + 1) & 1) * 32768u)
;     else if (Xn != nullptr) { xe = Xn + oxe; xo = Xn + oxo; we = Wn + owe; wo = Wn + owo; GT_DMA(0u) }
;     const char* cur = smem + (kt & 1) * 32768;
; #pragma unroll
;     for (int ks = 0; ks < 2; ++ks) {
;       bf16x8 xf[MT], wf[4];
;       const int ch = ((ks * 4 + g) ^ rsw) << 4;
; #pragma unroll
;       for (int i = 0; i < MT; ++i) xf[i] = *(const bf16x8*)(cur + (wm * 16 * MT + i * 16 + lr) * 128 + ch);
; #pragma unroll
;       for (int i = 0; i < 4; ++i) wf[i] = *(const bf16x8*)(cur + 16384 + (wn * 64 + i * 16 + lr) * 128 + ch);
; #pragma unroll
;       for (int nt = 0; nt < 4; ++nt)
; #pragma unroll
;         for (int mt = 0; mt < MT; ++mt)
;           acc[nt][mt] = __builtin_amdgcn_mfma_f32_16x16x32_bf16(wf[nt], xf[mt], acc[nt][mt], 0, 0, 0);
;     }
;   } while (++kt < nk);
.LBB0_422:
	s_add_i32 s7, s8, 0x8000
	v_lshl_add_u64 v[124:125], v[76:77], 0, s[40:41]
	s_and_b32 s9, s7, 0x8000
	v_lshl_add_u64 v[122:123], v[74:75], 0, s[40:41]
	v_lshl_add_u64 v[126:127], v[124:125], 0, s[74:75]
	s_waitcnt vmcnt(0)
	s_barrier
	s_and_b32 s8, s8, 0x8000
	v_or_b32_e32 v162, s8, v85
	v_add3_u32 v163, v162, v81, v82
	v_add3_u32 v164, v162, v84, v82
	v_or_b32_e32 v165, s8, v83
	v_add3_u32 v166, v165, v81, v82
	v_add3_u32 v167, v165, v84, v82
	ds_read_b128 v[86:89], v163
	ds_read_b128 v[90:93], v163 offset:2048
	ds_read_b128 v[94:97], v163 offset:4096
	ds_read_b128 v[98:101], v163 offset:6144
	ds_read_b128 v[102:105], v164 offset:16384
	ds_read_b128 v[106:109], v164 offset:18432
	ds_read_b128 v[110:113], v164 offset:20480
	ds_read_b128 v[114:117], v164 offset:22528
	ds_read_b128 v[130:133], v166
	ds_read_b128 v[134:137], v166 offset:2048
	ds_read_b128 v[138:141], v166 offset:4096
	ds_read_b128 v[142:145], v166 offset:6144
	ds_read_b128 v[146:149], v167 offset:16384
	ds_read_b128 v[150:153], v167 offset:18432
	ds_read_b128 v[154:157], v167 offset:20480
	ds_read_b128 v[158:161], v167 offset:22528
	s_add_i32 s10, s9, s5
	s_mov_b32 m0, s10
	s_nop 0
	global_load_lds_dwordx4 v[126:127], off
	v_lshl_add_u64 v[126:127], v[122:123], 0, s[94:95]
	s_add_i32 s11, s10, 0x400
	s_mov_b32 m0, s11
	s_nop 0
	global_load_lds_dwordx4 v[126:127], off
	v_lshl_add_u64 v[124:125], v[124:125], 0, s[76:77]
	s_add_i32 s11, s10, 0x800
	s_mov_b32 m0, s11
	s_nop 0
	global_load_lds_dwordx4 v[124:125], off
	v_lshl_add_u64 v[120:121], v[72:73], 0, s[40:41]
	v_lshl_add_u64 v[122:123], v[122:123], 0, s[54:55]
	s_addk_i32 s10, 0xc00
	s_mov_b32 m0, s10
	s_nop 0
	global_load_lds_dwordx4 v[122:123], off
	v_lshl_add_u64 v[118:119], v[70:71], 0, s[40:41]
	v_lshl_add_u64 v[128:129], v[120:121], 0, s[28:29]
	s_add_i32 s9, s9, s6
	s_mov_b32 m0, s9
	s_nop 0
	global_load_lds_dwordx4 v[128:129], off
	v_lshl_add_u64 v[122:123], v[118:119], 0, s[94:95]
	s_add_i32 s10, s9, 0x400
	s_mov_b32 m0, s10
	s_nop 0
	global_load_lds_dwordx4 v[122:123], off
	v_lshl_add_u64 v[120:121], v[120:121], 0, s[78:79]
	s_add_i32 s10, s9, 0x800
	s_mov_b32 m0, s10
	s_nop 0
	global_load_lds_dwordx4 v[120:121], off
	v_lshl_add_u64 v[118:119], v[118:119], 0, s[54:55]
	s_addk_i32 s9, 0xc00
	s_mov_b32 m0, s9
	s_nop 0
	global_load_lds_dwordx4 v[118:119], off
	s_mov_b32 s8, s7
	s_add_u32 s40, s40, 0x80
	s_addc_u32 s41, s41, 0
	s_cmpk_lg_i32 s40, 0x780
	s_waitcnt lgkmcnt(11)
	v_mfma_f32_16x16x32_bf16 v[62:65], v[102:105], v[86:89], v[62:65]
	v_mfma_f32_16x16x32_bf16 v[58:61], v[102:105], v[90:93], v[58:61]
	v_mfma_f32_16x16x32_bf16 v[54:57], v[102:105], v[94:97], v[54:57]
	v_mfma_f32_16x16x32_bf16 v[50:53], v[102:105], v[98:101], v[50:53]
	s_waitcnt lgkmcnt(10)
	v_mfma_f32_16x16x32_bf16 v[34:37], v[106:109], v[98:101], v[34:37]
	s_waitcnt lgkmcnt(9)
	v_mfma_f32_16x16x32_bf16 v[18:21], v[110:113], v[98:101], v[18:21]
	s_waitcnt lgkmcnt(8)
	v_mfma_f32_16x16x32_bf16 v[14:17], v[114:117], v[86:89], v[14:17]
	v_mfma_f32_16x16x32_bf16 v[10:13], v[114:117], v[90:93], v[10:13]
	v_mfma_f32_16x16x32_bf16 v[6:9], v[114:117], v[94:97], v[6:9]
	v_mfma_f32_16x16x32_bf16 v[2:5], v[114:117], v[98:101], v[2:5]
	v_mfma_f32_16x16x32_bf16 v[46:49], v[106:109], v[86:89], v[46:49]
	v_mfma_f32_16x16x32_bf16 v[42:45], v[106:109], v[90:93], v[42:45]
	v_mfma_f32_16x16x32_bf16 v[38:41], v[106:109], v[94:97], v[38:41]
	v_mfma_f32_16x16x32_bf16 v[30:33], v[110:113], v[86:89], v[30:33]
	v_mfma_f32_16x16x32_bf16 v[26:29], v[110:113], v[90:93], v[26:29]
	v_mfma_f32_16x16x32_bf16 v[22:25], v[110:113], v[94:97], v[22:25]
	s_waitcnt lgkmcnt(3)
	v_mfma_f32_16x16x32_bf16 v[62:65], v[146:149], v[130:133], v[62:65]
	v_mfma_f32_16x16x32_bf16 v[58:61], v[146:149], v[134:137], v[58:61]
	v_mfma_f32_16x16x32_bf16 v[54:57], v[146:149], v[138:141], v[54:57]
	v_mfma_f32_16x16x32_bf16 v[50:53], v[146:149], v[142:145], v[50:53]
	s_waitcnt lgkmcnt(2)
	v_mfma_f32_16x16x32_bf16 v[46:49], v[150:153], v[130:133], v[46:49]
	v_mfma_f32_16x16x32_bf16 v[42:45], v[150:153], v[134:137], v[42:45]
	v_mfma_f32_16x16x32_bf16 v[38:41], v[150:153], v[138:141], v[38:41]
	v_mfma_f32_16x16x32_bf16 v[34:37], v[150:153], v[142:145], v[34:37]
	s_waitcnt lgkmcnt(1)
	v_mfma_f32_16x16x32_bf16 v[30:33], v[154:157], v[130:133], v[30:33]
	v_mfma_f32_16x16x32_bf16 v[26:29], v[154:157], v[134:137], v[26:29]
	v_mfma_f32_16x16x32_bf16 v[22:25], v[154:157], v[138:141], v[22:25]
	v_mfma_f32_16x16x32_bf16 v[18:21], v[154:157], v[142:145], v[18:21]
	s_waitcnt lgkmcnt(0)
	v_mfma_f32_16x16x32_bf16 v[14:17], v[158:161], v[130:133], v[14:17]
	v_mfma_f32_16x16x32_bf16 v[10:13], v[158:161], v[134:137], v[10:13]
	v_mfma_f32_16x16x32_bf16 v[6:9], v[158:161], v[138:141], v[6:9]
	v_mfma_f32_16x16x32_bf16 v[2:5], v[158:161], v[142:145], v[2:5]
	s_cbranch_scc1 .LBB0_422
; DI int get_bid() { int b = blockIdx.x; asm volatile("" : "+s"(b)); return b; }
; template <int MT, class Epi>
; DI void gemm_tile(const u16* __restrict__ X, long ldx, const u16* __restrict__ W, long ldw, int K, char* smem,
;                   int m0, int n0, const Epi& epi, bool pre = false, const u16* Xn = nullptr, const u16* Wn = nullptr) {
;     ...
;   const int nk = K >> 6;
;   int kt = 0;
;   do {
;     asm volatile("s_waitcnt vmcnt(0)" ::: "memory");
;     __syncthreads();
;     if (kt + 1 < nk) GT_DMA((unsigned)((kt + 1) & 1) * 32768u)
;     else if (Xn != nullptr) { xe = Xn + oxe; xo = Xn + oxo; we = Wn + owe; wo = Wn + owo; GT_DMA(0u) }
;     const char* cur = smem + (kt & 1) * 32768;
; #pragma unroll
;     for (int ks = 0; ks < 2; ++ks) {
;       bf16x8 xf[MT], wf[4];
;       const int ch = ((ks * 4 + g) ^ rsw) << 4;
; #pragma unroll
;       for (int i = 0; i < MT; ++i) xf[i] = *(const bf16x8*)(cur + (wm * 16 * MT + i * 16 + lr) * 128 + ch);
; #pragma unroll
;       for (int i = 0; i < 4; ++i) wf[i] = *(const bf16x8*)(cur + 16384 + (wn * 64 + i * 16 + lr) * 128 + ch);
; #pragma unroll
;       for (int nt = 0; nt < 4; ++nt)
; #pragma unroll
;         for (int mt = 0; mt < MT; ++mt)
;           acc[nt][mt] = __builtin_amdgcn_mfma_f32_16x16x32_bf16(wf[nt], xf[mt], acc[nt][mt], 0, 0, 0);
;     }
;   } while (++kt < nk);
;     ...
;   epi.run(acc, m0 + wm * 16 * MT + lr, n0 + wn * 64 + 4 * g);
; DI void phase_even(const Params& p, int e, int sub, char* smem) {
;     ...
;     for (int t = get_bid(); t < 132 * 40; t += gridDim.x) {
;       const int tm = t / 40, tn = t % 40;
;       const int t2 = t + gridDim.x, tm2 = t2 / 40, tn2 = t2 % 40;
;       const bool nx = t2 < 132 * 40;
;       gemm_tile<4>(hbuf + (size_t)tm * 128 * 1024, 1024, W + WE_IN + (size_t)tn * 128 * 1024, 1024, 1024, smem, tm * 128, tn * 128, epi, pre,
;                    nx ? hbuf + (size_t)tm2 * 128 * 1024 : nullptr, W + WE_IN + (size_t)tn2 * 128 * 1024);
;       pre = nx;
	v_bfe_u32 v154, v185, 4, 1
	v_mul_u32_u24_e32 v154, 24, v154
	v_mov_b32_e32 v155, 0
	v_mov_b32_e32 v170, 0x3f3504f3
	v_mov_b32_e32 v171, 0x3f3504f3
	v_mov_b32_e32 v172, 0xbfb8aa3b
	v_mov_b32_e32 v173, 0xbfb8aa3b
	v_mov_b32_e32 v174, 0x378e98ab
	v_mov_b32_e32 v175, 0x378e98ab
	v_mov_b32_e32 v176, 0xb9c68948
	v_mov_b32_e32 v177, 0xb9c68948
	v_mov_b32_e32 v178, 0x3b7cd369
	v_mov_b32_e32 v179, 0x3b7cd369
	v_mov_b32_e32 v180, 0xbcc618b2
	v_mov_b32_e32 v181, 0xbcc618b2
	v_mov_b32_e32 v186, 0x3dda74e4
	v_mov_b32_e32 v187, 0x3dda74e4
	v_mov_b32_e32 v188, 0x3f228afd
	v_mov_b32_e32 v189, 0x3f228afd
	v_mov_b32_e32 v190, 0x3e03c728
	v_mov_b32_e32 v191, 0x3e03c728
	v_mov_b32_e32 v192, 0xba1345e1
	v_mov_b32_e32 v193, 0xba1345e1
	v_mov_b32_e32 v194, 0x3ba10414
	v_mov_b32_e32 v195, 0x3ba10414
	v_mov_b32_e32 v196, 0xbcdac9b8
	v_mov_b32_e32 v197, 0xbcdac9b8
	v_mov_b32_e32 v224, 0x3de703be
	v_mov_b32_e32 v225, 0x3de703be
	v_mov_b32_e32 v226, 0xbec09330
	v_mov_b32_e32 v227, 0xbec09330
	v_mov_b32_e32 v228, 0x3e0375d0
	v_mov_b32_e32 v229, 0x3e0375d0
	v_mov_b32_e32 v230, 1.0
	v_mov_b32_e32 v231, 1.0
	v_mov_b32_e32 v232, 0.5
	v_mov_b32_e32 v233, 0.5
	v_mov_b32_e32 v234, -1.0
	v_mov_b32_e32 v235, -1.0
	v_readlane_b32 s8, v255, 5
	v_readlane_b32 s14, v255, 11
	s_add_i32 s4, s4, s14
	s_mul_hi_i32 s7, s4, 0x66666667
	s_lshr_b32 s8, s7, 31
	s_ashr_i32 s7, s7, 4
	s_add_i32 s46, s7, s8
	s_cmpk_gt_i32 s4, 0x149f
	v_readlane_b32 s9, v255, 6
	s_cselect_b64 s[44:45], -1, 0
	s_ashr_i32 s47, s46, 31
	s_lshl_b64 s[8:9], s[46:47], 18
	s_add_u32 s7, s0, s8
	s_addc_u32 s8, s1, s9
	s_cmpk_lt_i32 s4, 0x14a0
	s_waitcnt vmcnt(0)
	s_cselect_b32 s41, s8, 0
	s_cselect_b32 s40, s7, 0
	v_readlane_b32 s12, v255, 9
	v_readlane_b32 s13, v255, 10
	s_cmp_eq_u64 s[40:41], 0
	v_readlane_b32 s10, v255, 7
	v_readlane_b32 s11, v255, 8
	v_readlane_b32 s15, v255, 12
	s_barrier
	s_cbranch_scc1 .LBB0_425
	s_mul_i32 s7, s46, 40
	s_sub_i32 s8, s4, s7
	s_ashr_i32 s9, s8, 31
	s_lshl_b64 s[8:9], s[8:9], 18
	s_add_u32 s8, s12, s8
	s_addc_u32 s9, s13, s9
	v_lshl_add_u64 v[70:71], s[40:41], 0, v[68:69]
	v_lshl_add_u64 v[72:73], s[8:9], 0, v[66:67]
	v_lshl_add_u64 v[66:67], s[40:41], 0, v[66:67]
	s_mov_b32 m0, s5
	s_nop 0
	global_load_lds_dwordx4 v[70:71], off
	s_mov_b64 s[10:11], 0x4000
	v_lshl_add_u64 v[68:69], s[8:9], 0, v[68:69]
	v_lshl_add_u64 v[74:75], v[66:67], 0, s[10:11]
	s_add_i32 s7, s5, 0x400
	s_mov_b32 m0, s7
	s_nop 0
	global_load_lds_dwordx4 v[74:75], off
	s_mov_b64 s[12:13], 0x8000
	v_lshl_add_u64 v[70:71], v[70:71], 0, s[12:13]
	s_add_i32 s7, s5, 0x800
	s_mov_b32 m0, s7
	s_nop 0
	global_load_lds_dwordx4 v[70:71], off
	s_mov_b64 s[14:15], 0xc000
	v_lshl_add_u64 v[66:67], v[66:67], 0, s[14:15]
	s_add_i32 s7, s5, 0xc00
	s_mov_b32 m0, s7
	s_nop 0
	global_load_lds_dwordx4 v[66:67], off
	s_mov_b32 m0, s6
	s_nop 0
	global_load_lds_dwordx4 v[68:69], off
	v_lshl_add_u64 v[66:67], v[72:73], 0, s[10:11]
	s_add_i32 s6, s5, 0x4400
	s_mov_b32 m0, s6
	s_nop 0
	global_load_lds_dwordx4 v[66:67], off
	v_lshl_add_u64 v[66:67], v[68:69], 0, s[12:13]
	s_add_i32 s6, s5, 0x4800
	s_mov_b32 m0, s6
	s_nop 0
	global_load_lds_dwordx4 v[66:67], off
	v_lshl_add_u64 v[66:67], v[72:73], 0, s[14:15]
	s_addk_i32 s5, 0x4c00
	s_mov_b32 m0, s5
	s_nop 0
	global_load_lds_dwordx4 v[66:67], off
.LBB0_425:
	v_add3_u32 v94, v85, v84, v82
	ds_read_b128 v[66:69], v94 offset:49152
	v_add3_u32 v85, v85, v81, v82
	ds_read_b128 v[70:73], v85 offset:32768
	ds_read_b128 v[74:77], v85 offset:34816
	ds_read_b128 v[86:89], v85 offset:36864
	ds_read_b128 v[90:93], v85 offset:38912
	v_add3_u32 v81, v83, v81, v82
	s_lshl_b32 s6, s38, 7
	s_lshl_b32 s5, s42, 7
	s_waitcnt lgkmcnt(3)
	v_mfma_f32_16x16x32_bf16 v[62:65], v[66:69], v[70:73], v[62:65]
	v_lshl_or_b32 v1, v1, 6, s5
	s_movk_i32 s5, 0x3ff
	s_waitcnt lgkmcnt(2)
	v_mfma_f32_16x16x32_bf16 v[58:61], v[66:69], v[74:77], v[58:61]
	s_waitcnt lgkmcnt(1)
	v_mfma_f32_16x16x32_bf16 v[54:57], v[66:69], v[86:89], v[54:57]
	s_waitcnt lgkmcnt(0)
	v_mfma_f32_16x16x32_bf16 v[50:53], v[66:69], v[90:93], v[50:53]
	ds_read_b128 v[66:69], v94 offset:51200
	s_waitcnt lgkmcnt(0)
	v_mfma_f32_16x16x32_bf16 v[46:49], v[66:69], v[70:73], v[46:49]
	v_mfma_f32_16x16x32_bf16 v[42:45], v[66:69], v[74:77], v[42:45]
	v_mfma_f32_16x16x32_bf16 v[38:41], v[66:69], v[86:89], v[38:41]
	v_mfma_f32_16x16x32_bf16 v[34:37], v[66:69], v[90:93], v[34:37]
	ds_read_b128 v[66:69], v94 offset:53248
	s_waitcnt lgkmcnt(0)
	v_mfma_f32_16x16x32_bf16 v[30:33], v[66:69], v[70:73], v[30:33]
	v_mfma_f32_16x16x32_bf16 v[26:29], v[66:69], v[74:77], v[26:29]
	v_mfma_f32_16x16x32_bf16 v[22:25], v[66:69], v[86:89], v[22:25]
	v_mfma_f32_16x16x32_bf16 v[18:21], v[66:69], v[90:93], v[18:21]
	ds_read_b128 v[66:69], v94 offset:55296
	v_add3_u32 v94, v83, v84, v82
	ds_read_b128 v[82:85], v81 offset:36864
	s_waitcnt lgkmcnt(1)
	v_mfma_f32_16x16x32_bf16 v[14:17], v[66:69], v[70:73], v[14:17]
	ds_read_b128 v[70:73], v94 offset:49152
	v_mfma_f32_16x16x32_bf16 v[10:13], v[66:69], v[74:77], v[10:13]
	ds_read_b128 v[74:77], v81 offset:34816
	v_mfma_f32_16x16x32_bf16 v[6:9], v[66:69], v[86:89], v[6:9]
	ds_read_b128 v[86:89], v81 offset:38912
	v_mfma_f32_16x16x32_bf16 v[2:5], v[66:69], v[90:93], v[2:5]
	ds_read_b128 v[66:69], v81 offset:32768
	s_waitcnt lgkmcnt(0)
	v_mfma_f32_16x16x32_bf16 v[62:65], v[70:73], v[66:69], v[62:65]
	v_mfma_f32_16x16x32_bf16 v[58:61], v[70:73], v[74:77], v[58:61]
	v_mfma_f32_16x16x32_bf16 v[54:57], v[70:73], v[82:85], v[54:57]
	v_mfma_f32_16x16x32_bf16 v[50:53], v[70:73], v[86:89], v[50:53]
	ds_read_b128 v[70:73], v94 offset:51200
	s_waitcnt lgkmcnt(0)
	v_mfma_f32_16x16x32_bf16 v[46:49], v[70:73], v[66:69], v[46:49]
	v_mfma_f32_16x16x32_bf16 v[42:45], v[70:73], v[74:77], v[42:45]
	v_mfma_f32_16x16x32_bf16 v[38:41], v[70:73], v[82:85], v[38:41]
	v_mfma_f32_16x16x32_bf16 v[34:37], v[70:73], v[86:89], v[34:37]
	ds_read_b128 v[70:73], v94 offset:53248
	s_waitcnt lgkmcnt(0)
	v_mfma_f32_16x16x32_bf16 v[30:33], v[70:73], v[66:69], v[30:33]
	v_mfma_f32_16x16x32_bf16 v[26:29], v[70:73], v[74:77], v[26:29]
	v_mfma_f32_16x16x32_bf16 v[22:25], v[70:73], v[82:85], v[22:25]
	v_mfma_f32_16x16x32_bf16 v[18:21], v[70:73], v[86:89], v[18:21]
	ds_read_b128 v[70:73], v94 offset:55296
	s_waitcnt lgkmcnt(0)
	v_mfma_f32_16x16x32_bf16 v[14:17], v[70:73], v[66:69], v[14:17]
	v_lshl_add_u32 v67, v80, 6, s6
	v_lshl_or_b32 v182, v78, 2, v67
	v_or_b32_e32 v66, v1, v79
	v_mfma_f32_16x16x32_bf16 v[10:13], v[70:73], v[74:77], v[10:13]
	v_cmp_lt_i32_e64 s[40:41], s5, v182
	s_movk_i32 s5, 0xbff
	v_cmp_lt_u32_e64 s[38:39], s5, v67
	v_mfma_f32_16x16x32_bf16 v[6:9], v[70:73], v[82:85], v[6:9]
	v_ashrrev_i32_e32 v67, 31, v66
	v_mfma_f32_16x16x32_bf16 v[2:5], v[70:73], v[86:89], v[2:5]
	s_and_saveexec_b64 s[6:7], s[40:41]
	s_xor_b64 s[46:47], exec, s[6:7]
	s_cbranch_execz .LBB0_447
; DI void st_bf4(u16* p, float a, float b, float c, float d) { *(uint2*)p = make_uint2(pk2(a, b), pk2(c, d)); }
; DI float gelu_f(float x) { return 0.5f * x * (1.f + erff(x * 0.70710678118654752f)); }
; DI float silu_f(float x) { return x * __builtin_amdgcn_rcpf(1.f + __expf(-x)); }
;   template <int NT, int MT> DI void run(f32x4 (&acc)[NT][MT], int mb, int nb) const {
;     ...
;         } else if (n < 3072) {
;           st_bf4(uvbuf + (size_t)m * 2048 + (n - 1024), gelu_f(v[0]), gelu_f(v[1]), gelu_f(v[2]), gelu_f(v[3]));
;         } else {
;           st_bf4(gatebuf + (size_t)m * 2048 + (n - 3072), silu_f(v[0]), silu_f(v[1]), silu_f(v[2]), silu_f(v[3]));
	v_lshlrev_b64 v[68:69], 12, v[66:67]
	s_and_saveexec_b64 s[6:7], s[38:39]
	s_xor_b64 s[48:49], exec, s[6:7]
	s_cbranch_execz .LBB0_428
	v_mul_f32_e32 v70, 0xbfb8aa3b, v62
	v_mul_f32_e32 v71, 0xbfb8aa3b, v63
	v_exp_f32_e32 v70, v70
	v_exp_f32_e32 v71, v71
	v_readlane_b32 s6, v252, 35
	v_readlane_b32 s7, v252, 36
	v_add_f32_e32 v70, 1.0, v70
	v_add_f32_e32 v71, 1.0, v71
	v_rcp_f32_e32 v70, v70
	v_rcp_f32_e32 v71, v71
	v_lshl_add_u64 v[68:69], s[6:7], 0, v[68:69]
	v_lshl_add_u64 v[68:69], v[182:183], 1, v[68:69]
	v_pk_mul_f32 v[62:63], v[62:63], v[70:71]
	v_mul_f32_e32 v70, 0xbfb8aa3b, v64
	v_mul_f32_e32 v71, 0xbfb8aa3b, v65
	v_exp_f32_e32 v70, v70
	v_exp_f32_e32 v71, v71
	v_cvt_pk_bf16_f32 v62, v62, v63
	v_add_f32_e32 v70, 1.0, v70
	v_add_f32_e32 v71, 1.0, v71
	v_rcp_f32_e32 v70, v70
	v_rcp_f32_e32 v71, v71
	s_nop 0
	v_pk_mul_f32 v[64:65], v[64:65], v[70:71]
	s_nop 0
	v_cvt_pk_bf16_f32 v63, v64, v65
	v_add_co_u32_e32 v64, vcc, 0xfffff000, v68
	s_nop 1
	v_addc_co_u32_e32 v65, vcc, -1, v69, vcc
	v_mov_b32_e32 v236, v62
	v_mov_b32_e32 v237, v63
.LBB0_428:
	s_andn2_saveexec_b64 s[48:49], s[48:49]
	s_cbranch_execz .LBB0_446
	v_pk_mul_f32 v[130:131], v[62:63], v[170:171]
	v_pk_mul_f32 v[142:143], v[64:65], v[170:171]
	v_and_b32_e32 v132, 0x7fffffff, v130
	v_and_b32_e32 v144, 0x7fffffff, v142
	v_and_b32_e32 v133, 0x7fffffff, v131
	v_and_b32_e32 v145, 0x7fffffff, v143
	v_pk_fma_f32 v[134:135], v[132:133], v[174:175], v[176:177]
	v_pk_fma_f32 v[146:147], v[144:145], v[174:175], v[176:177]
	v_pk_fma_f32 v[134:135], v[132:133], v[134:135], v[178:179]
	v_pk_fma_f32 v[146:147], v[144:145], v[146:147], v[178:179]
	v_pk_fma_f32 v[134:135], v[132:133], v[134:135], v[180:181]
	v_pk_fma_f32 v[146:147], v[144:145], v[146:147], v[180:181]
	v_pk_fma_f32 v[134:135], v[132:133], v[134:135], v[186:187]
	v_pk_fma_f32 v[146:147], v[144:145], v[146:147], v[186:187]
	v_pk_fma_f32 v[134:135], v[132:133], v[134:135], v[188:189]
	v_pk_fma_f32 v[146:147], v[144:145], v[146:147], v[188:189]
	v_pk_fma_f32 v[134:135], v[132:133], v[134:135], v[190:191]
	v_pk_fma_f32 v[146:147], v[144:145], v[146:147], v[190:191]
	v_pk_fma_f32 v[134:135], v[132:133], v[134:135], v[132:133]
	v_pk_fma_f32 v[146:147], v[144:145], v[146:147], v[144:145]
	v_pk_mul_f32 v[134:135], v[134:135], v[172:173]
	v_pk_mul_f32 v[146:147], v[146:147], v[172:173]
	v_pk_mul_f32 v[136:137], v[130:131], v[130:131]
	v_pk_mul_f32 v[148:149], v[142:143], v[142:143]
	v_exp_f32_e32 v134, v134
	v_exp_f32_e32 v146, v146
	v_exp_f32_e32 v135, v135
	v_exp_f32_e32 v147, v147
	v_pk_fma_f32 v[138:139], v[136:137], v[192:193], v[194:195]
	v_pk_fma_f32 v[150:151], v[148:149], v[192:193], v[194:195]
	v_pk_fma_f32 v[138:139], v[136:137], v[138:139], v[196:197]
	v_pk_fma_f32 v[150:151], v[148:149], v[150:151], v[196:197]
	v_pk_fma_f32 v[138:139], v[136:137], v[138:139], v[224:225]
	v_pk_fma_f32 v[150:151], v[148:149], v[150:151], v[224:225]
	v_pk_fma_f32 v[138:139], v[136:137], v[138:139], v[226:227]
	v_pk_fma_f32 v[150:151], v[148:149], v[150:151], v[226:227]
	v_pk_fma_f32 v[138:139], v[136:137], v[138:139], v[228:229]
	v_pk_fma_f32 v[150:151], v[148:149], v[150:151], v[228:229]
	v_pk_fma_f32 v[134:135], v[134:135], v[234:235], v[230:231]
	v_pk_fma_f32 v[146:147], v[146:147], v[234:235], v[230:231]
	v_pk_fma_f32 v[138:139], v[132:133], v[138:139], v[132:133]
	v_pk_fma_f32 v[150:151], v[144:145], v[150:151], v[144:145]
	v_pk_mul_f32 v[140:141], v[62:63], v[232:233]
	v_pk_mul_f32 v[152:153], v[64:65], v[232:233]
	v_cmp_ngt_f32_e32 vcc, 1.0, v132
	v_cmp_ngt_f32_e64 s[8:9], 1.0, v133
	v_readlane_b32 s6, v252, 33
	v_readlane_b32 s7, v252, 34
	v_cndmask_b32_e32 v138, v138, v134, vcc
	v_cndmask_b32_e64 v139, v139, v135, s[8:9]
	v_cmp_ngt_f32_e32 vcc, 1.0, v144
	v_cmp_ngt_f32_e64 s[8:9], 1.0, v145
	v_bfi_b32 v138, s37, v138, v130
	v_bfi_b32 v139, s37, v139, v131
	v_cndmask_b32_e32 v150, v150, v146, vcc
	v_cndmask_b32_e64 v151, v151, v147, s[8:9]
	v_pk_add_f32 v[138:139], v[138:139], v[230:231]
	v_bfi_b32 v150, s37, v150, v142
	v_bfi_b32 v151, s37, v151, v143
	v_pk_add_f32 v[150:151], v[150:151], v[230:231]
	v_pk_mul_f32 v[138:139], v[140:141], v[138:139]
	v_lshl_add_u64 v[62:63], s[6:7], 0, v[68:69]
	v_pk_mul_f32 v[150:151], v[152:153], v[150:151]
	v_lshl_add_u64 v[62:63], v[182:183], 1, v[62:63]
	v_cvt_pk_bf16_f32 v64, v138, v139
	v_cvt_pk_bf16_f32 v65, v150, v151
	v_mov_b32_e32 v236, v64
	v_mov_b32_e32 v237, v65

; DI float gelu_f(float x) { return 0.5f * x * (1.f + erff(x * 0.70710678118654752f)); }
; DI float silu_f(float x) { return x * __builtin_amdgcn_rcpf(1.f + __expf(-x)); }
; DI void st_bf4(u16* p, float a, float b, float c, float d) { *(uint2*)p = make_uint2(pk2(a, b), pk2(c, d)); }
;   template <int NT, int MT> DI void run(f32x4 (&acc)[NT][MT], int mb, int nb) const {
;     ...
;         if (n < 1024) {
;           st_bf4(abuf + (size_t)m * 1024 + n, v[0], v[1], v[2], v[3]);
;           float* dst = nullptr;
;           if (m < M_PROMPT) { int t = m & 8191; if (t >= 8177) dst = spp + ((size_t)((m >> 13) * 15 + (t - 8177))) * 1024 + n; }
;           else { int r = m - M_PROMPT; int s = r & 31; if (s >= 17) dst = sps + ((size_t)((r >> 5) * 15 + (s - 17))) * 1024 + n; }
;           if (dst) *(float4*)dst = make_float4(v[0], v[1], v[2], v[3]);
;         } else if (n < 3072) {
;           st_bf4(uvbuf + (size_t)m * 2048 + (n - 1024), gelu_f(v[0]), gelu_f(v[1]), gelu_f(v[2]), gelu_f(v[3]));
;         } else {
;           st_bf4(gatebuf + (size_t)m * 2048 + (n - 3072), silu_f(v[0]), silu_f(v[1]), silu_f(v[2]), silu_f(v[3]));
.LBB0_447:
	s_or_saveexec_b64 s[46:47], s[46:47]
	v_ashrrev_i32_e32 v69, 31, v182
	v_mov_b32_e32 v68, v182
	s_xor_b64 exec, exec, s[46:47]
	s_cbranch_execz .LBB0_449
	v_lshlrev_b64 v[70:71], 11, v[66:67]
	v_lshl_add_u64 v[70:71], s[96:97], 0, v[70:71]
	v_lshl_add_u64 v[70:71], v[68:69], 1, v[70:71]
	v_cvt_pk_bf16_f32 v62, v62, v63
	v_cvt_pk_bf16_f32 v63, v64, v65
	v_mov_b32_e32 v236, v62
	v_mov_b32_e32 v237, v63
.LBB0_449:
	s_or_b64 exec, exec, s[46:47]
	v_or_b32_e32 v62, 16, v66
	v_ashrrev_i32_e32 v63, 31, v62
	s_and_saveexec_b64 s[6:7], s[40:41]
	s_xor_b64 s[46:47], exec, s[6:7]
	s_cbranch_execz .LBB0_471
	v_lshlrev_b64 v[64:65], 12, v[62:63]
	s_and_saveexec_b64 s[6:7], s[38:39]
	s_xor_b64 s[48:49], exec, s[6:7]
	s_cbranch_execz .LBB0_452
	v_mul_f32_e32 v70, 0xbfb8aa3b, v58
	v_mul_f32_e32 v71, 0xbfb8aa3b, v59
	v_exp_f32_e32 v70, v70
	v_exp_f32_e32 v71, v71
	v_readlane_b32 s6, v252, 35
	v_readlane_b32 s7, v252, 36
	v_add_f32_e32 v70, 1.0, v70
	v_add_f32_e32 v71, 1.0, v71
	v_rcp_f32_e32 v70, v70
	v_rcp_f32_e32 v71, v71
	v_lshl_add_u64 v[64:65], s[6:7], 0, v[64:65]
	v_lshl_add_u64 v[64:65], v[182:183], 1, v[64:65]
	v_pk_mul_f32 v[58:59], v[58:59], v[70:71]
	v_mul_f32_e32 v70, 0xbfb8aa3b, v60
	v_mul_f32_e32 v71, 0xbfb8aa3b, v61
	v_exp_f32_e32 v70, v70
	v_exp_f32_e32 v71, v71
	v_cvt_pk_bf16_f32 v58, v58, v59
	v_add_f32_e32 v70, 1.0, v70
	v_add_f32_e32 v71, 1.0, v71
	v_rcp_f32_e32 v70, v70
	v_rcp_f32_e32 v71, v71
	s_nop 0
	v_pk_mul_f32 v[60:61], v[60:61], v[70:71]
	s_nop 0
	v_cvt_pk_bf16_f32 v59, v60, v61
	v_add_co_u32_e32 v60, vcc, 0xfffff000, v64
	s_nop 1
	v_addc_co_u32_e32 v61, vcc, -1, v65, vcc
	v_mov_b32_e32 v240, v58
	v_mov_b32_e32 v241, v59
.LBB0_452:
	s_andn2_saveexec_b64 s[48:49], s[48:49]
	s_cbranch_execz .LBB0_470
	v_pk_mul_f32 v[130:131], v[58:59], v[170:171]
	v_pk_mul_f32 v[142:143], v[60:61], v[170:171]
	v_and_b32_e32 v132, 0x7fffffff, v130
	v_and_b32_e32 v144, 0x7fffffff, v142
	v_and_b32_e32 v133, 0x7fffffff, v131
	v_and_b32_e32 v145, 0x7fffffff, v143
	v_pk_fma_f32 v[134:135], v[132:133], v[174:175], v[176:177]
	v_pk_fma_f32 v[146:147], v[144:145], v[174:175], v[176:177]
	v_pk_fma_f32 v[134:135], v[132:133], v[134:135], v[178:179]
	v_pk_fma_f32 v[146:147], v[144:145], v[146:147], v[178:179]
	v_pk_fma_f32 v[134:135], v[132:133], v[134:135], v[180:181]
	v_pk_fma_f32 v[146:147], v[144:145], v[146:147], v[180:181]
	v_pk_fma_f32 v[134:135], v[132:133], v[134:135], v[186:187]
	v_pk_fma_f32 v[146:147], v[144:145], v[146:147], v[186:187]
	v_pk_fma_f32 v[134:135], v[132:133], v[134:135], v[188:189]
	v_pk_fma_f32 v[146:147], v[144:145], v[146:147], v[188:189]
	v_pk_fma_f32 v[134:135], v[132:133], v[134:135], v[190:191]
	v_pk_fma_f32 v[146:147], v[144:145], v[146:147], v[190:191]
	v_pk_fma_f32 v[134:135], v[132:133], v[134:135], v[132:133]
	v_pk_fma_f32 v[146:147], v[144:145], v[146:147], v[144:145]
	v_pk_mul_f32 v[134:135], v[134:135], v[172:173]
	v_pk_mul_f32 v[146:147], v[146:147], v[172:173]
	v_pk_mul_f32 v[136:137], v[130:131], v[130:131]
	v_pk_mul_f32 v[148:149], v[142:143], v[142:143]
	v_exp_f32_e32 v134, v134
	v_exp_f32_e32 v146, v146
	v_exp_f32_e32 v135, v135
	v_exp_f32_e32 v147, v147
	v_pk_fma_f32 v[138:139], v[136:137], v[192:193], v[194:195]
	v_pk_fma_f32 v[150:151], v[148:149], v[192:193], v[194:195]
	v_pk_fma_f32 v[138:139], v[136:137], v[138:139], v[196:197]
	v_pk_fma_f32 v[150:151], v[148:149], v[150:151], v[196:197]
	v_pk_fma_f32 v[138:139], v[136:137], v[138:139], v[224:225]
	v_pk_fma_f32 v[150:151], v[148:149], v[150:151], v[224:225]
	v_pk_fma_f32 v[138:139], v[136:137], v[138:139], v[226:227]
	v_pk_fma_f32 v[150:151], v[148:149], v[150:151], v[226:227]
	v_pk_fma_f32 v[138:139], v[136:137], v[138:139], v[228:229]
	v_pk_fma_f32 v[150:151], v[148:149], v[150:151], v[228:229]
	v_pk_fma_f32 v[134:135], v[134:135], v[234:235], v[230:231]
	v_pk_fma_f32 v[146:147], v[146:147], v[234:235], v[230:231]
	v_pk_fma_f32 v[138:139], v[132:133], v[138:139], v[132:133]
	v_pk_fma_f32 v[150:151], v[144:145], v[150:151], v[144:145]
	v_pk_mul_f32 v[140:141], v[58:59], v[232:233]
	v_pk_mul_f32 v[152:153], v[60:61], v[232:233]
	v_cmp_ngt_f32_e32 vcc, 1.0, v132
	v_cmp_ngt_f32_e64 s[8:9], 1.0, v133
	v_readlane_b32 s6, v252, 33
	v_readlane_b32 s7, v252, 34
	v_cndmask_b32_e32 v138, v138, v134, vcc
	v_cndmask_b32_e64 v139, v139, v135, s[8:9]
	v_cmp_ngt_f32_e32 vcc, 1.0, v144
	v_cmp_ngt_f32_e64 s[8:9], 1.0, v145
	v_bfi_b32 v138, s37, v138, v130
	v_bfi_b32 v139, s37, v139, v131
	v_cndmask_b32_e32 v150, v150, v146, vcc
	v_cndmask_b32_e64 v151, v151, v147, s[8:9]
	v_pk_add_f32 v[138:139], v[138:139], v[230:231]
	v_bfi_b32 v150, s37, v150, v142
	v_bfi_b32 v151, s37, v151, v143
	v_pk_add_f32 v[150:151], v[150:151], v[230:231]
	v_pk_mul_f32 v[138:139], v[140:141], v[138:139]
	v_lshl_add_u64 v[58:59], s[6:7], 0, v[64:65]
	v_pk_mul_f32 v[150:151], v[152:153], v[150:151]
	v_lshl_add_u64 v[58:59], v[182:183], 1, v[58:59]
	v_cvt_pk_bf16_f32 v60, v138, v139
	v_cvt_pk_bf16_f32 v61, v150, v151
	v_mov_b32_e32 v240, v60
	v_mov_b32_e32 v241, v61

; DI void st_bf4(u16* p, float a, float b, float c, float d) { *(uint2*)p = make_uint2(pk2(a, b), pk2(c, d)); }
;   template <int NT, int MT> DI void run(f32x4 (&acc)[NT][MT], int mb, int nb) const {
;     ...
;         if (n < 1024) {
;           st_bf4(abuf + (size_t)m * 1024 + n, v[0], v[1], v[2], v[3]);
;           float* dst = nullptr;
;           if (m < M_PROMPT) { int t = m & 8191; if (t >= 8177) dst = spp + ((size_t)((m >> 13) * 15 + (t - 8177))) * 1024 + n; }
;           else { int r = m - M_PROMPT; int s = r & 31; if (s >= 17) dst = sps + ((size_t)((r >> 5) * 15 + (s - 17))) * 1024 + n; }
;           if (dst) *(float4*)dst = make_float4(v[0], v[1], v[2], v[3]);
.LBB0_471:
	s_andn2_saveexec_b64 s[46:47], s[46:47]
	s_cbranch_execz .LBB0_479
	v_lshlrev_b64 v[64:65], 11, v[62:63]
	v_lshl_add_u64 v[64:65], s[96:97], 0, v[64:65]
	v_lshl_add_u64 v[64:65], v[68:69], 1, v[64:65]
	v_cvt_pk_bf16_f32 v70, v58, v59
	v_cvt_pk_bf16_f32 v71, v60, v61
	s_movk_i32 s5, 0x3fef
	v_mov_b32_e32 v240, v70
	v_mov_b32_e32 v241, v71
	v_cmp_lt_i32_e32 vcc, s5, v66
	v_mov_b64_e32 v[64:65], 0
	s_and_saveexec_b64 s[48:49], vcc
	s_cbranch_execz .LBB0_476
	v_and_b32_e32 v70, 31, v62
	v_cmp_ne_u32_e32 vcc, 16, v70
	v_mov_b64_e32 v[64:65], 0
	s_and_saveexec_b64 s[50:51], vcc
	s_cbranch_execz .LBB0_475
	v_add_u32_e32 v64, 0xffffc010, v1
	v_lshrrev_b32_e32 v64, 5, v64
	v_mul_lo_u32 v64, v64, 15
	s_movk_i32 s5, 0xffef
	v_add3_u32 v64, v70, v64, s5
	v_mov_b32_e32 v65, v183
	v_readlane_b32 s6, v252, 57
	v_lshlrev_b64 v[64:65], 12, v[64:65]
	v_readlane_b32 s7, v252, 58
	s_nop 1
	v_lshl_add_u64 v[64:65], s[6:7], 0, v[64:65]
	v_lshl_add_u64 v[64:65], v[68:69], 2, v[64:65]

; DI float gelu_f(float x) { return 0.5f * x * (1.f + erff(x * 0.70710678118654752f)); }
; DI float silu_f(float x) { return x * __builtin_amdgcn_rcpf(1.f + __expf(-x)); }
; DI void st_bf4(u16* p, float a, float b, float c, float d) { *(uint2*)p = make_uint2(pk2(a, b), pk2(c, d)); }
;   template <int NT, int MT> DI void run(f32x4 (&acc)[NT][MT], int mb, int nb) const {
;     ...
;         } else if (n < 3072) {
;           st_bf4(uvbuf + (size_t)m * 2048 + (n - 1024), gelu_f(v[0]), gelu_f(v[1]), gelu_f(v[2]), gelu_f(v[3]));
;         } else {
;           st_bf4(gatebuf + (size_t)m * 2048 + (n - 3072), silu_f(v[0]), silu_f(v[1]), silu_f(v[2]), silu_f(v[3]));
.LBB0_479:
	s_or_b64 exec, exec, s[46:47]
	v_or_b32_e32 v58, 32, v66
	v_ashrrev_i32_e32 v59, 31, v58
	s_and_saveexec_b64 s[6:7], s[40:41]
	s_xor_b64 s[46:47], exec, s[6:7]
	s_cbranch_execz .LBB0_501
	v_lshlrev_b64 v[60:61], 12, v[58:59]
	s_and_saveexec_b64 s[6:7], s[38:39]
	s_xor_b64 s[48:49], exec, s[6:7]
	s_cbranch_execz .LBB0_482
	v_mul_f32_e32 v64, 0xbfb8aa3b, v54
	v_mul_f32_e32 v65, 0xbfb8aa3b, v55
	v_exp_f32_e32 v64, v64
	v_exp_f32_e32 v65, v65
	v_readlane_b32 s6, v252, 35
	v_readlane_b32 s7, v252, 36
	v_add_f32_e32 v64, 1.0, v64
	v_add_f32_e32 v65, 1.0, v65
	v_rcp_f32_e32 v64, v64
	v_rcp_f32_e32 v65, v65
	v_lshl_add_u64 v[60:61], s[6:7], 0, v[60:61]
	v_lshl_add_u64 v[60:61], v[182:183], 1, v[60:61]
	v_pk_mul_f32 v[54:55], v[54:55], v[64:65]
	v_mul_f32_e32 v64, 0xbfb8aa3b, v56
	v_mul_f32_e32 v65, 0xbfb8aa3b, v57
	v_exp_f32_e32 v64, v64
	v_exp_f32_e32 v65, v65
	v_cvt_pk_bf16_f32 v54, v54, v55
	v_add_f32_e32 v64, 1.0, v64
	v_add_f32_e32 v65, 1.0, v65
	v_rcp_f32_e32 v64, v64
	v_rcp_f32_e32 v65, v65
	s_nop 0
	v_pk_mul_f32 v[56:57], v[56:57], v[64:65]
	s_nop 0
	v_cvt_pk_bf16_f32 v55, v56, v57
	v_add_co_u32_e32 v56, vcc, 0xfffff000, v60
	s_nop 1
	v_addc_co_u32_e32 v57, vcc, -1, v61, vcc
	v_mov_b32_e32 v244, v54
	v_mov_b32_e32 v245, v55
.LBB0_482:
	s_andn2_saveexec_b64 s[48:49], s[48:49]
	s_cbranch_execz .LBB0_500
	v_pk_mul_f32 v[130:131], v[54:55], v[170:171]
	v_pk_mul_f32 v[142:143], v[56:57], v[170:171]
	v_and_b32_e32 v132, 0x7fffffff, v130
	v_and_b32_e32 v144, 0x7fffffff, v142
	v_and_b32_e32 v133, 0x7fffffff, v131
	v_and_b32_e32 v145, 0x7fffffff, v143
	v_pk_fma_f32 v[134:135], v[132:133], v[174:175], v[176:177]
	v_pk_fma_f32 v[146:147], v[144:145], v[174:175], v[176:177]
	v_pk_fma_f32 v[134:135], v[132:133], v[134:135], v[178:179]
	v_pk_fma_f32 v[146:147], v[144:145], v[146:147], v[178:179]
	v_pk_fma_f32 v[134:135], v[132:133], v[134:135], v[180:181]
	v_pk_fma_f32 v[146:147], v[144:145], v[146:147], v[180:181]
	v_pk_fma_f32 v[134:135], v[132:133], v[134:135], v[186:187]
	v_pk_fma_f32 v[146:147], v[144:145], v[146:147], v[186:187]
	v_pk_fma_f32 v[134:135], v[132:133], v[134:135], v[188:189]
	v_pk_fma_f32 v[146:147], v[144:145], v[146:147], v[188:189]
	v_pk_fma_f32 v[134:135], v[132:133], v[134:135], v[190:191]
	v_pk_fma_f32 v[146:147], v[144:145], v[146:147], v[190:191]
	v_pk_fma_f32 v[134:135], v[132:133], v[134:135], v[132:133]
	v_pk_fma_f32 v[146:147], v[144:145], v[146:147], v[144:145]
	v_pk_mul_f32 v[134:135], v[134:135], v[172:173]
	v_pk_mul_f32 v[146:147], v[146:147], v[172:173]
	v_pk_mul_f32 v[136:137], v[130:131], v[130:131]
	v_pk_mul_f32 v[148:149], v[142:143], v[142:143]
	v_exp_f32_e32 v134, v134
	v_exp_f32_e32 v146, v146
	v_exp_f32_e32 v135, v135
	v_exp_f32_e32 v147, v147
	v_pk_fma_f32 v[138:139], v[136:137], v[192:193], v[194:195]
	v_pk_fma_f32 v[150:151], v[148:149], v[192:193], v[194:195]
	v_pk_fma_f32 v[138:139], v[136:137], v[138:139], v[196:197]
	v_pk_fma_f32 v[150:151], v[148:149], v[150:151], v[196:197]
	v_pk_fma_f32 v[138:139], v[136:137], v[138:139], v[224:225]
	v_pk_fma_f32 v[150:151], v[148:149], v[150:151], v[224:225]
	v_pk_fma_f32 v[138:139], v[136:137], v[138:139], v[226:227]
	v_pk_fma_f32 v[150:151], v[148:149], v[150:151], v[226:227]
	v_pk_fma_f32 v[138:139], v[136:137], v[138:139], v[228:229]
	v_pk_fma_f32 v[150:151], v[148:149], v[150:151], v[228:229]
	v_pk_fma_f32 v[134:135], v[134:135], v[234:235], v[230:231]
	v_pk_fma_f32 v[146:147], v[146:147], v[234:235], v[230:231]
	v_pk_fma_f32 v[138:139], v[132:133], v[138:139], v[132:133]
	v_pk_fma_f32 v[150:151], v[144:145], v[150:151], v[144:145]
	v_pk_mul_f32 v[140:141], v[54:55], v[232:233]
	v_pk_mul_f32 v[152:153], v[56:57], v[232:233]
	v_cmp_ngt_f32_e32 vcc, 1.0, v132
	v_cmp_ngt_f32_e64 s[8:9], 1.0, v133
	v_readlane_b32 s6, v252, 33
	v_readlane_b32 s7, v252, 34
	v_cndmask_b32_e32 v138, v138, v134, vcc
	v_cndmask_b32_e64 v139, v139, v135, s[8:9]
	v_cmp_ngt_f32_e32 vcc, 1.0, v144
	v_cmp_ngt_f32_e64 s[8:9], 1.0, v145
	v_bfi_b32 v138, s37, v138, v130
	v_bfi_b32 v139, s37, v139, v131
	v_cndmask_b32_e32 v150, v150, v146, vcc
	v_cndmask_b32_e64 v151, v151, v147, s[8:9]
	v_pk_add_f32 v[138:139], v[138:139], v[230:231]
	v_bfi_b32 v150, s37, v150, v142
	v_bfi_b32 v151, s37, v151, v143
	v_pk_add_f32 v[150:151], v[150:151], v[230:231]
	v_pk_mul_f32 v[138:139], v[140:141], v[138:139]
	v_lshl_add_u64 v[54:55], s[6:7], 0, v[60:61]
	v_pk_mul_f32 v[150:151], v[152:153], v[150:151]
	v_lshl_add_u64 v[54:55], v[182:183], 1, v[54:55]
	v_cvt_pk_bf16_f32 v56, v138, v139
	v_cvt_pk_bf16_f32 v57, v150, v151
	v_mov_b32_e32 v244, v56
	v_mov_b32_e32 v245, v57

; DI float gelu_f(float x) { return 0.5f * x * (1.f + erff(x * 0.70710678118654752f)); }
; DI float silu_f(float x) { return x * __builtin_amdgcn_rcpf(1.f + __expf(-x)); }
; DI void st_bf4(u16* p, float a, float b, float c, float d) { *(uint2*)p = make_uint2(pk2(a, b), pk2(c, d)); }
;   template <int NT, int MT> DI void run(f32x4 (&acc)[NT][MT], int mb, int nb) const {
;     ...
;           st_bf4(abuf + (size_t)m * 1024 + n, v[0], v[1], v[2], v[3]);
;           float* dst = nullptr;
;           if (m < M_PROMPT) { int t = m & 8191; if (t >= 8177) dst = spp + ((size_t)((m >> 13) * 15 + (t - 8177))) * 1024 + n; }
;           else { int r = m - M_PROMPT; int s = r & 31; if (s >= 17) dst = sps + ((size_t)((r >> 5) * 15 + (s - 17))) * 1024 + n; }
;           if (dst) *(float4*)dst = make_float4(v[0], v[1], v[2], v[3]);
;         } else if (n < 3072) {
;           st_bf4(uvbuf + (size_t)m * 2048 + (n - 1024), gelu_f(v[0]), gelu_f(v[1]), gelu_f(v[2]), gelu_f(v[3]));
;         } else {
;           st_bf4(gatebuf + (size_t)m * 2048 + (n - 3072), silu_f(v[0]), silu_f(v[1]), silu_f(v[2]), silu_f(v[3]));
.LBB0_501:
	s_andn2_saveexec_b64 s[46:47], s[46:47]
	s_cbranch_execz .LBB0_503
	v_lshlrev_b64 v[60:61], 11, v[58:59]
	v_lshl_add_u64 v[60:61], s[96:97], 0, v[60:61]
	v_lshl_add_u64 v[60:61], v[68:69], 1, v[60:61]
	v_cvt_pk_bf16_f32 v54, v54, v55
	v_cvt_pk_bf16_f32 v55, v56, v57
	v_mov_b32_e32 v244, v54
	v_mov_b32_e32 v245, v55
.LBB0_503:
	s_or_b64 exec, exec, s[46:47]
	v_or_b32_e32 v54, 48, v66
	v_ashrrev_i32_e32 v55, 31, v54
	s_and_saveexec_b64 s[6:7], s[40:41]
	s_xor_b64 s[40:41], exec, s[6:7]
	s_cbranch_execz .LBB0_525
	v_lshlrev_b64 v[56:57], 12, v[54:55]
	s_and_saveexec_b64 s[6:7], s[38:39]
	s_xor_b64 s[46:47], exec, s[6:7]
	s_cbranch_execz .LBB0_506
	v_mul_f32_e32 v60, 0xbfb8aa3b, v50
	v_mul_f32_e32 v61, 0xbfb8aa3b, v51
	v_exp_f32_e32 v60, v60
	v_exp_f32_e32 v61, v61
	v_readlane_b32 s6, v252, 35
	v_readlane_b32 s7, v252, 36
	v_add_f32_e32 v60, 1.0, v60
	v_add_f32_e32 v61, 1.0, v61
	v_rcp_f32_e32 v60, v60
	v_rcp_f32_e32 v61, v61
	v_lshl_add_u64 v[56:57], s[6:7], 0, v[56:57]
	v_lshl_add_u64 v[56:57], v[182:183], 1, v[56:57]
	v_pk_mul_f32 v[50:51], v[50:51], v[60:61]
	v_mul_f32_e32 v60, 0xbfb8aa3b, v52
	v_mul_f32_e32 v61, 0xbfb8aa3b, v53
	v_exp_f32_e32 v60, v60
	v_exp_f32_e32 v61, v61
	v_cvt_pk_bf16_f32 v50, v50, v51
	v_add_f32_e32 v60, 1.0, v60
	v_add_f32_e32 v61, 1.0, v61
	v_rcp_f32_e32 v60, v60
	v_rcp_f32_e32 v61, v61
	s_nop 0
	v_pk_mul_f32 v[52:53], v[52:53], v[60:61]
	s_nop 0
	v_cvt_pk_bf16_f32 v51, v52, v53
	v_add_co_u32_e32 v52, vcc, 0xfffff000, v56
	s_nop 1
	v_addc_co_u32_e32 v53, vcc, -1, v57, vcc
	v_mov_b32_e32 v248, v50
	v_mov_b32_e32 v249, v51
.LBB0_506:
	s_andn2_saveexec_b64 s[46:47], s[46:47]
	s_cbranch_execz .LBB0_524
	v_pk_mul_f32 v[130:131], v[50:51], v[170:171]
	v_pk_mul_f32 v[142:143], v[52:53], v[170:171]
	v_and_b32_e32 v132, 0x7fffffff, v130
	v_and_b32_e32 v144, 0x7fffffff, v142
	v_and_b32_e32 v133, 0x7fffffff, v131
	v_and_b32_e32 v145, 0x7fffffff, v143
	v_pk_fma_f32 v[134:135], v[132:133], v[174:175], v[176:177]
	v_pk_fma_f32 v[146:147], v[144:145], v[174:175], v[176:177]
	v_pk_fma_f32 v[134:135], v[132:133], v[134:135], v[178:179]
	v_pk_fma_f32 v[146:147], v[144:145], v[146:147], v[178:179]
	v_pk_fma_f32 v[134:135], v[132:133], v[134:135], v[180:181]
	v_pk_fma_f32 v[146:147], v[144:145], v[146:147], v[180:181]
	v_pk_fma_f32 v[134:135], v[132:133], v[134:135], v[186:187]
	v_pk_fma_f32 v[146:147], v[144:145], v[146:147], v[186:187]
	v_pk_fma_f32 v[134:135], v[132:133], v[134:135], v[188:189]
	v_pk_fma_f32 v[146:147], v[144:145], v[146:147], v[188:189]
	v_pk_fma_f32 v[134:135], v[132:133], v[134:135], v[190:191]
	v_pk_fma_f32 v[146:147], v[144:145], v[146:147], v[190:191]
	v_pk_fma_f32 v[134:135], v[132:133], v[134:135], v[132:133]
	v_pk_fma_f32 v[146:147], v[144:145], v[146:147], v[144:145]
	v_pk_mul_f32 v[134:135], v[134:135], v[172:173]
	v_pk_mul_f32 v[146:147], v[146:147], v[172:173]
	v_pk_mul_f32 v[136:137], v[130:131], v[130:131]
	v_pk_mul_f32 v[148:149], v[142:143], v[142:143]
	v_exp_f32_e32 v134, v134
	v_exp_f32_e32 v146, v146
	v_exp_f32_e32 v135, v135
	v_exp_f32_e32 v147, v147
	v_pk_fma_f32 v[138:139], v[136:137], v[192:193], v[194:195]
	v_pk_fma_f32 v[150:151], v[148:149], v[192:193], v[194:195]
	v_pk_fma_f32 v[138:139], v[136:137], v[138:139], v[196:197]
	v_pk_fma_f32 v[150:151], v[148:149], v[150:151], v[196:197]
	v_pk_fma_f32 v[138:139], v[136:137], v[138:139], v[224:225]
	v_pk_fma_f32 v[150:151], v[148:149], v[150:151], v[224:225]
	v_pk_fma_f32 v[138:139], v[136:137], v[138:139], v[226:227]
	v_pk_fma_f32 v[150:151], v[148:149], v[150:151], v[226:227]
	v_pk_fma_f32 v[138:139], v[136:137], v[138:139], v[228:229]
	v_pk_fma_f32 v[150:151], v[148:149], v[150:151], v[228:229]
	v_pk_fma_f32 v[134:135], v[134:135], v[234:235], v[230:231]
	v_pk_fma_f32 v[146:147], v[146:147], v[234:235], v[230:231]
	v_pk_fma_f32 v[138:139], v[132:133], v[138:139], v[132:133]
	v_pk_fma_f32 v[150:151], v[144:145], v[150:151], v[144:145]
	v_pk_mul_f32 v[140:141], v[50:51], v[232:233]
	v_pk_mul_f32 v[152:153], v[52:53], v[232:233]
	v_cmp_ngt_f32_e32 vcc, 1.0, v132
	v_cmp_ngt_f32_e64 s[8:9], 1.0, v133
	v_readlane_b32 s6, v252, 33
	v_readlane_b32 s7, v252, 34
	v_cndmask_b32_e32 v138, v138, v134, vcc
	v_cndmask_b32_e64 v139, v139, v135, s[8:9]
	v_cmp_ngt_f32_e32 vcc, 1.0, v144
	v_cmp_ngt_f32_e64 s[8:9], 1.0, v145
	v_bfi_b32 v138, s37, v138, v130
	v_bfi_b32 v139, s37, v139, v131
	v_cndmask_b32_e32 v150, v150, v146, vcc
	v_cndmask_b32_e64 v151, v151, v147, s[8:9]
	v_pk_add_f32 v[138:139], v[138:139], v[230:231]
	v_bfi_b32 v150, s37, v150, v142
	v_bfi_b32 v151, s37, v151, v143
	v_pk_add_f32 v[150:151], v[150:151], v[230:231]
	v_pk_mul_f32 v[138:139], v[140:141], v[138:139]
	v_lshl_add_u64 v[50:51], s[6:7], 0, v[56:57]
	v_pk_mul_f32 v[150:151], v[152:153], v[150:151]
	v_lshl_add_u64 v[50:51], v[182:183], 1, v[50:51]
	v_cvt_pk_bf16_f32 v52, v138, v139
	v_cvt_pk_bf16_f32 v53, v150, v151
	v_mov_b32_e32 v248, v52
	v_mov_b32_e32 v249, v53

; DI void st_bf4(u16* p, float a, float b, float c, float d) { *(uint2*)p = make_uint2(pk2(a, b), pk2(c, d)); }
;   template <int NT, int MT> DI void run(f32x4 (&acc)[NT][MT], int mb, int nb) const {
;     ...
;           st_bf4(abuf + (size_t)m * 1024 + n, v[0], v[1], v[2], v[3]);
;           float* dst = nullptr;
;           if (m < M_PROMPT) { int t = m & 8191; if (t >= 8177) dst = spp + ((size_t)((m >> 13) * 15 + (t - 8177))) * 1024 + n; }
;           else { int r = m - M_PROMPT; int s = r & 31; if (s >= 17) dst = sps + ((size_t)((r >> 5) * 15 + (s - 17))) * 1024 + n; }
;           if (dst) *(float4*)dst = make_float4(v[0], v[1], v[2], v[3]);
.LBB0_525:
	s_andn2_saveexec_b64 s[40:41], s[40:41]
	s_cbranch_execz .LBB0_533
	v_lshlrev_b64 v[56:57], 11, v[54:55]
	v_lshl_add_u64 v[56:57], s[96:97], 0, v[56:57]
	s_movk_i32 s5, 0x3fcf
	v_lshl_add_u64 v[56:57], v[68:69], 1, v[56:57]
	v_cvt_pk_bf16_f32 v60, v50, v51
	v_cvt_pk_bf16_f32 v61, v52, v53
	v_cmp_lt_i32_e32 vcc, s5, v66
	v_mov_b32_e32 v248, v60
	v_mov_b32_e32 v249, v61
	s_and_saveexec_b64 s[6:7], vcc
	s_xor_b64 s[46:47], exec, s[6:7]
	s_cbranch_execz .LBB0_855
	v_and_b32_e32 v60, 31, v54
	v_cmp_ne_u32_e32 vcc, 16, v60
	v_mov_b64_e32 v[56:57], 0
	s_and_saveexec_b64 s[48:49], vcc
	s_cbranch_execz .LBB0_529
	v_add_u32_e32 v56, 0xffffc030, v1
	v_lshrrev_b32_e32 v56, 5, v56
	v_mul_lo_u32 v56, v56, 15
	s_movk_i32 s5, 0xffef
	v_add3_u32 v56, v60, v56, s5
	v_mov_b32_e32 v57, v183
	v_readlane_b32 s6, v252, 57
	v_lshlrev_b64 v[56:57], 12, v[56:57]
	v_readlane_b32 s7, v252, 58
	s_nop 1
	v_lshl_add_u64 v[56:57], s[6:7], 0, v[56:57]
	v_lshl_add_u64 v[56:57], v[68:69], 2, v[56:57]

; DI unsigned pk2(float a, float b) { f32x2_t f = {a, b}; return __builtin_bit_cast(unsigned, __builtin_convertvector(f, bf16x2_t)); }
; DI float gelu_f(float x) { return 0.5f * x * (1.f + erff(x * 0.70710678118654752f)); }
; DI float silu_f(float x) { return x * __builtin_amdgcn_rcpf(1.f + __expf(-x)); }
; DI void st_bf4(u16* p, float a, float b, float c, float d) { *(uint2*)p = make_uint2(pk2(a, b), pk2(c, d)); }
;   template <int NT, int MT> DI void run(f32x4 (&acc)[NT][MT], int mb, int nb) const {
;     ...
;         } else if (n < 3072) {
;           st_bf4(uvbuf + (size_t)m * 2048 + (n - 1024), gelu_f(v[0]), gelu_f(v[1]), gelu_f(v[2]), gelu_f(v[3]));
;         } else {
;           st_bf4(gatebuf + (size_t)m * 2048 + (n - 3072), silu_f(v[0]), silu_f(v[1]), silu_f(v[2]), silu_f(v[3]));
.LBB0_533:
	s_or_b64 exec, exec, s[40:41]
	s_movk_i32 s5, 0x3ef
	v_cmp_lt_i32_e64 s[40:41], s5, v182
	s_and_saveexec_b64 s[6:7], s[40:41]
	s_xor_b64 s[46:47], exec, s[6:7]
	s_cbranch_execz .LBB0_555
	v_lshlrev_b64 v[50:51], 12, v[66:67]
	s_and_saveexec_b64 s[6:7], s[38:39]
	s_xor_b64 s[48:49], exec, s[6:7]
	s_cbranch_execz .LBB0_536
	v_mul_f32_e32 v52, 0xbfb8aa3b, v46
	v_mul_f32_e32 v53, 0xbfb8aa3b, v47
	v_exp_f32_e32 v52, v52
	v_exp_f32_e32 v53, v53
	v_readlane_b32 s6, v252, 35
	v_readlane_b32 s7, v252, 36
	v_add_f32_e32 v52, 1.0, v52
	v_add_f32_e32 v53, 1.0, v53
	v_rcp_f32_e32 v52, v52
	v_rcp_f32_e32 v53, v53
	v_lshl_add_u64 v[50:51], s[6:7], 0, v[50:51]
	v_lshl_add_u64 v[50:51], v[182:183], 1, v[50:51]
	v_pk_mul_f32 v[46:47], v[46:47], v[52:53]
	v_mul_f32_e32 v52, 0xbfb8aa3b, v48
	v_mul_f32_e32 v53, 0xbfb8aa3b, v49
	v_exp_f32_e32 v52, v52
	v_exp_f32_e32 v53, v53
	v_cvt_pk_bf16_f32 v46, v46, v47
	v_add_f32_e32 v52, 1.0, v52
	v_add_f32_e32 v53, 1.0, v53
	v_rcp_f32_e32 v52, v52
	v_rcp_f32_e32 v53, v53
	s_nop 0
	v_pk_mul_f32 v[48:49], v[48:49], v[52:53]
	s_nop 0
	v_cvt_pk_bf16_f32 v47, v48, v49
	v_add_co_u32_e32 v48, vcc, 0xfffff000, v50
	s_nop 1
	v_addc_co_u32_e32 v49, vcc, -1, v51, vcc
	v_mov_b32_e32 v238, v46
	v_mov_b32_e32 v239, v47
	v_lshl_add_u64 v[156:157], v[48:49], 0, v[154:155]
	s_nop 0
	v_permlane16_swap_b32_e32 v236, v238
	v_permlane16_swap_b32_e32 v237, v239
	global_store_dwordx4 v[156:157], v[236:239], off offset:-2048
.LBB0_536:
	s_andn2_saveexec_b64 s[48:49], s[48:49]
	s_cbranch_execz .LBB0_554
	v_pk_mul_f32 v[130:131], v[46:47], v[170:171]
	v_pk_mul_f32 v[142:143], v[48:49], v[170:171]
	v_and_b32_e32 v132, 0x7fffffff, v130
	v_and_b32_e32 v144, 0x7fffffff, v142
	v_and_b32_e32 v133, 0x7fffffff, v131
	v_and_b32_e32 v145, 0x7fffffff, v143
	v_pk_fma_f32 v[134:135], v[132:133], v[174:175], v[176:177]
	v_pk_fma_f32 v[146:147], v[144:145], v[174:175], v[176:177]
	v_pk_fma_f32 v[134:135], v[132:133], v[134:135], v[178:179]
	v_pk_fma_f32 v[146:147], v[144:145], v[146:147], v[178:179]
	v_pk_fma_f32 v[134:135], v[132:133], v[134:135], v[180:181]
	v_pk_fma_f32 v[146:147], v[144:145], v[146:147], v[180:181]
	v_pk_fma_f32 v[134:135], v[132:133], v[134:135], v[186:187]
	v_pk_fma_f32 v[146:147], v[144:145], v[146:147], v[186:187]
	v_pk_fma_f32 v[134:135], v[132:133], v[134:135], v[188:189]
	v_pk_fma_f32 v[146:147], v[144:145], v[146:147], v[188:189]
	v_pk_fma_f32 v[134:135], v[132:133], v[134:135], v[190:191]
	v_pk_fma_f32 v[146:147], v[144:145], v[146:147], v[190:191]
	v_pk_fma_f32 v[134:135], v[132:133], v[134:135], v[132:133]
	v_pk_fma_f32 v[146:147], v[144:145], v[146:147], v[144:145]
	v_pk_mul_f32 v[134:135], v[134:135], v[172:173]
	v_pk_mul_f32 v[146:147], v[146:147], v[172:173]
	v_pk_mul_f32 v[136:137], v[130:131], v[130:131]
	v_pk_mul_f32 v[148:149], v[142:143], v[142:143]
	v_exp_f32_e32 v134, v134
	v_exp_f32_e32 v146, v146
	v_exp_f32_e32 v135, v135
	v_exp_f32_e32 v147, v147
	v_pk_fma_f32 v[138:139], v[136:137], v[192:193], v[194:195]
	v_pk_fma_f32 v[150:151], v[148:149], v[192:193], v[194:195]
	v_pk_fma_f32 v[138:139], v[136:137], v[138:139], v[196:197]
	v_pk_fma_f32 v[150:151], v[148:149], v[150:151], v[196:197]
	v_pk_fma_f32 v[138:139], v[136:137], v[138:139], v[224:225]
	v_pk_fma_f32 v[150:151], v[148:149], v[150:151], v[224:225]
	v_pk_fma_f32 v[138:139], v[136:137], v[138:139], v[226:227]
	v_pk_fma_f32 v[150:151], v[148:149], v[150:151], v[226:227]
	v_pk_fma_f32 v[138:139], v[136:137], v[138:139], v[228:229]
	v_pk_fma_f32 v[150:151], v[148:149], v[150:151], v[228:229]
	v_pk_fma_f32 v[134:135], v[134:135], v[234:235], v[230:231]
	v_pk_fma_f32 v[146:147], v[146:147], v[234:235], v[230:231]
	v_pk_fma_f32 v[138:139], v[132:133], v[138:139], v[132:133]
	v_pk_fma_f32 v[150:151], v[144:145], v[150:151], v[144:145]
	v_pk_mul_f32 v[140:141], v[46:47], v[232:233]
	v_pk_mul_f32 v[152:153], v[48:49], v[232:233]
	v_cmp_ngt_f32_e32 vcc, 1.0, v132
	v_cmp_ngt_f32_e64 s[8:9], 1.0, v133
	v_readlane_b32 s6, v252, 33
	v_readlane_b32 s7, v252, 34
	v_cndmask_b32_e32 v138, v138, v134, vcc
	v_cndmask_b32_e64 v139, v139, v135, s[8:9]
	v_cmp_ngt_f32_e32 vcc, 1.0, v144
	v_cmp_ngt_f32_e64 s[8:9], 1.0, v145
	v_bfi_b32 v138, s37, v138, v130
	v_bfi_b32 v139, s37, v139, v131
	v_cndmask_b32_e32 v150, v150, v146, vcc
	v_cndmask_b32_e64 v151, v151, v147, s[8:9]
	v_pk_add_f32 v[138:139], v[138:139], v[230:231]
	v_bfi_b32 v150, s37, v150, v142
	v_bfi_b32 v151, s37, v151, v143
	v_pk_add_f32 v[150:151], v[150:151], v[230:231]
	v_pk_mul_f32 v[138:139], v[140:141], v[138:139]
	v_lshl_add_u64 v[46:47], s[6:7], 0, v[50:51]
	v_pk_mul_f32 v[150:151], v[152:153], v[150:151]
	v_lshl_add_u64 v[46:47], v[182:183], 1, v[46:47]
	v_cvt_pk_bf16_f32 v48, v138, v139
	v_cvt_pk_bf16_f32 v49, v150, v151
	v_mov_b32_e32 v238, v48
	v_mov_b32_e32 v239, v49
	v_lshl_add_u64 v[156:157], v[46:47], 0, v[154:155]
	s_nop 0
	v_permlane16_swap_b32_e32 v236, v238
	v_permlane16_swap_b32_e32 v237, v239
	global_store_dwordx4 v[156:157], v[236:239], off offset:-2048

; DI float gelu_f(float x) { return 0.5f * x * (1.f + erff(x * 0.70710678118654752f)); }
; DI float silu_f(float x) { return x * __builtin_amdgcn_rcpf(1.f + __expf(-x)); }
; DI void st_bf4(u16* p, float a, float b, float c, float d) { *(uint2*)p = make_uint2(pk2(a, b), pk2(c, d)); }
;   template <int NT, int MT> DI void run(f32x4 (&acc)[NT][MT], int mb, int nb) const {
;     ...
;         if (n < 1024) {
;           st_bf4(abuf + (size_t)m * 1024 + n, v[0], v[1], v[2], v[3]);
;           float* dst = nullptr;
;           if (m < M_PROMPT) { int t = m & 8191; if (t >= 8177) dst = spp + ((size_t)((m >> 13) * 15 + (t - 8177))) * 1024 + n; }
;           else { int r = m - M_PROMPT; int s = r & 31; if (s >= 17) dst = sps + ((size_t)((r >> 5) * 15 + (s - 17))) * 1024 + n; }
;           if (dst) *(float4*)dst = make_float4(v[0], v[1], v[2], v[3]);
;         } else if (n < 3072) {
;           st_bf4(uvbuf + (size_t)m * 2048 + (n - 1024), gelu_f(v[0]), gelu_f(v[1]), gelu_f(v[2]), gelu_f(v[3]));
;         } else {
;           st_bf4(gatebuf + (size_t)m * 2048 + (n - 3072), silu_f(v[0]), silu_f(v[1]), silu_f(v[2]), silu_f(v[3]));
.LBB0_555:
	s_andn2_saveexec_b64 s[46:47], s[46:47]
	s_cbranch_execz .LBB0_557
	v_lshlrev_b64 v[50:51], 11, v[66:67]
	v_lshl_add_u64 v[50:51], s[96:97], 0, v[50:51]
	v_lshl_add_u64 v[50:51], v[68:69], 1, v[50:51]
	v_cvt_pk_bf16_f32 v46, v46, v47
	v_cvt_pk_bf16_f32 v47, v48, v49
	v_mov_b32_e32 v238, v46
	v_mov_b32_e32 v239, v47
	v_lshl_add_u64 v[156:157], v[50:51], 0, v[154:155]
	s_nop 0
	v_permlane16_swap_b32_e32 v236, v238
	v_permlane16_swap_b32_e32 v237, v239
	global_store_dwordx4 v[156:157], v[236:239], off offset:0
.LBB0_557:
	s_or_b64 exec, exec, s[46:47]
	s_and_saveexec_b64 s[6:7], s[40:41]
	s_xor_b64 s[46:47], exec, s[6:7]
	s_cbranch_execz .LBB0_579
	v_lshlrev_b64 v[46:47], 12, v[62:63]
	s_and_saveexec_b64 s[6:7], s[38:39]
	s_xor_b64 s[48:49], exec, s[6:7]
	s_cbranch_execz .LBB0_560
	v_mul_f32_e32 v48, 0xbfb8aa3b, v42
	v_mul_f32_e32 v49, 0xbfb8aa3b, v43
	v_exp_f32_e32 v48, v48
	v_exp_f32_e32 v49, v49
	v_readlane_b32 s6, v252, 35
	v_readlane_b32 s7, v252, 36
	v_add_f32_e32 v48, 1.0, v48
	v_add_f32_e32 v49, 1.0, v49
	v_rcp_f32_e32 v48, v48
	v_rcp_f32_e32 v49, v49
	v_lshl_add_u64 v[46:47], s[6:7], 0, v[46:47]
	v_lshl_add_u64 v[46:47], v[182:183], 1, v[46:47]
	v_pk_mul_f32 v[42:43], v[42:43], v[48:49]
	v_mul_f32_e32 v48, 0xbfb8aa3b, v44
	v_mul_f32_e32 v49, 0xbfb8aa3b, v45
	v_exp_f32_e32 v48, v48
	v_exp_f32_e32 v49, v49
	v_cvt_pk_bf16_f32 v42, v42, v43
	v_add_f32_e32 v48, 1.0, v48
	v_add_f32_e32 v49, 1.0, v49
	v_rcp_f32_e32 v48, v48
	v_rcp_f32_e32 v49, v49
	s_nop 0
	v_pk_mul_f32 v[44:45], v[44:45], v[48:49]
	s_nop 0
	v_cvt_pk_bf16_f32 v43, v44, v45
	v_add_co_u32_e32 v44, vcc, 0xfffff000, v46
	s_nop 1
	v_addc_co_u32_e32 v45, vcc, -1, v47, vcc
	v_mov_b32_e32 v242, v42
	v_mov_b32_e32 v243, v43
	v_lshl_add_u64 v[156:157], v[44:45], 0, v[154:155]
	s_nop 0
	v_permlane16_swap_b32_e32 v240, v242
	v_permlane16_swap_b32_e32 v241, v243
	global_store_dwordx4 v[156:157], v[240:243], off offset:-2048
.LBB0_560:
	s_andn2_saveexec_b64 s[48:49], s[48:49]
	s_cbranch_execz .LBB0_578
	v_pk_mul_f32 v[130:131], v[42:43], v[170:171]
	v_pk_mul_f32 v[142:143], v[44:45], v[170:171]
	v_and_b32_e32 v132, 0x7fffffff, v130
	v_and_b32_e32 v144, 0x7fffffff, v142
	v_and_b32_e32 v133, 0x7fffffff, v131
	v_and_b32_e32 v145, 0x7fffffff, v143
	v_pk_fma_f32 v[134:135], v[132:133], v[174:175], v[176:177]
	v_pk_fma_f32 v[146:147], v[144:145], v[174:175], v[176:177]
	v_pk_fma_f32 v[134:135], v[132:133], v[134:135], v[178:179]
	v_pk_fma_f32 v[146:147], v[144:145], v[146:147], v[178:179]
	v_pk_fma_f32 v[134:135], v[132:133], v[134:135], v[180:181]
	v_pk_fma_f32 v[146:147], v[144:145], v[146:147], v[180:181]
	v_pk_fma_f32 v[134:135], v[132:133], v[134:135], v[186:187]
	v_pk_fma_f32 v[146:147], v[144:145], v[146:147], v[186:187]
	v_pk_fma_f32 v[134:135], v[132:133], v[134:135], v[188:189]
	v_pk_fma_f32 v[146:147], v[144:145], v[146:147], v[188:189]
	v_pk_fma_f32 v[134:135], v[132:133], v[134:135], v[190:191]
	v_pk_fma_f32 v[146:147], v[144:145], v[146:147], v[190:191]
	v_pk_fma_f32 v[134:135], v[132:133], v[134:135], v[132:133]
	v_pk_fma_f32 v[146:147], v[144:145], v[146:147], v[144:145]
	v_pk_mul_f32 v[134:135], v[134:135], v[172:173]
	v_pk_mul_f32 v[146:147], v[146:147], v[172:173]
	v_pk_mul_f32 v[136:137], v[130:131], v[130:131]
	v_pk_mul_f32 v[148:149], v[142:143], v[142:143]
	v_exp_f32_e32 v134, v134
	v_exp_f32_e32 v146, v146
	v_exp_f32_e32 v135, v135
	v_exp_f32_e32 v147, v147
	v_pk_fma_f32 v[138:139], v[136:137], v[192:193], v[194:195]
	v_pk_fma_f32 v[150:151], v[148:149], v[192:193], v[194:195]
	v_pk_fma_f32 v[138:139], v[136:137], v[138:139], v[196:197]
	v_pk_fma_f32 v[150:151], v[148:149], v[150:151], v[196:197]
	v_pk_fma_f32 v[138:139], v[136:137], v[138:139], v[224:225]
	v_pk_fma_f32 v[150:151], v[148:149], v[150:151], v[224:225]
	v_pk_fma_f32 v[138:139], v[136:137], v[138:139], v[226:227]
	v_pk_fma_f32 v[150:151], v[148:149], v[150:151], v[226:227]
	v_pk_fma_f32 v[138:139], v[136:137], v[138:139], v[228:229]
	v_pk_fma_f32 v[150:151], v[148:149], v[150:151], v[228:229]
	v_pk_fma_f32 v[134:135], v[134:135], v[234:235], v[230:231]
	v_pk_fma_f32 v[146:147], v[146:147], v[234:235], v[230:231]
	v_pk_fma_f32 v[138:139], v[132:133], v[138:139], v[132:133]
	v_pk_fma_f32 v[150:151], v[144:145], v[150:151], v[144:145]
	v_pk_mul_f32 v[140:141], v[42:43], v[232:233]
	v_pk_mul_f32 v[152:153], v[44:45], v[232:233]
	v_cmp_ngt_f32_e32 vcc, 1.0, v132
	v_cmp_ngt_f32_e64 s[8:9], 1.0, v133
	v_readlane_b32 s6, v252, 33
	v_readlane_b32 s7, v252, 34
	v_cndmask_b32_e32 v138, v138, v134, vcc
	v_cndmask_b32_e64 v139, v139, v135, s[8:9]
	v_cmp_ngt_f32_e32 vcc, 1.0, v144
	v_cmp_ngt_f32_e64 s[8:9], 1.0, v145
	v_bfi_b32 v138, s37, v138, v130
	v_bfi_b32 v139, s37, v139, v131
	v_cndmask_b32_e32 v150, v150, v146, vcc
	v_cndmask_b32_e64 v151, v151, v147, s[8:9]
	v_pk_add_f32 v[138:139], v[138:139], v[230:231]
	v_bfi_b32 v150, s37, v150, v142
	v_bfi_b32 v151, s37, v151, v143
	v_pk_add_f32 v[150:151], v[150:151], v[230:231]
	v_pk_mul_f32 v[138:139], v[140:141], v[138:139]
	v_lshl_add_u64 v[42:43], s[6:7], 0, v[46:47]
	v_pk_mul_f32 v[150:151], v[152:153], v[150:151]
	v_lshl_add_u64 v[42:43], v[182:183], 1, v[42:43]
	v_cvt_pk_bf16_f32 v44, v138, v139
	v_cvt_pk_bf16_f32 v45, v150, v151
	v_mov_b32_e32 v242, v44
	v_mov_b32_e32 v243, v45
	v_lshl_add_u64 v[156:157], v[42:43], 0, v[154:155]
	s_nop 0
	v_permlane16_swap_b32_e32 v240, v242
	v_permlane16_swap_b32_e32 v241, v243
	global_store_dwordx4 v[156:157], v[240:243], off offset:-2048

; DI void st_bf4(u16* p, float a, float b, float c, float d) { *(uint2*)p = make_uint2(pk2(a, b), pk2(c, d)); }
;   template <int NT, int MT> DI void run(f32x4 (&acc)[NT][MT], int mb, int nb) const {
;     ...
;         if (n < 1024) {
;           st_bf4(abuf + (size_t)m * 1024 + n, v[0], v[1], v[2], v[3]);
;           float* dst = nullptr;
;           if (m < M_PROMPT) { int t = m & 8191; if (t >= 8177) dst = spp + ((size_t)((m >> 13) * 15 + (t - 8177))) * 1024 + n; }
;           else { int r = m - M_PROMPT; int s = r & 31; if (s >= 17) dst = sps + ((size_t)((r >> 5) * 15 + (s - 17))) * 1024 + n; }
;           if (dst) *(float4*)dst = make_float4(v[0], v[1], v[2], v[3]);
.LBB0_579:
	s_andn2_saveexec_b64 s[46:47], s[46:47]
	s_cbranch_execz .LBB0_587
	v_lshlrev_b64 v[46:47], 11, v[62:63]
	v_lshl_add_u64 v[46:47], s[96:97], 0, v[46:47]
	v_lshl_add_u64 v[46:47], v[68:69], 1, v[46:47]
	v_cvt_pk_bf16_f32 v48, v42, v43
	v_cvt_pk_bf16_f32 v49, v44, v45
	s_movk_i32 s5, 0x3fef
	v_mov_b32_e32 v242, v48
	v_mov_b32_e32 v243, v49
	v_lshl_add_u64 v[156:157], v[46:47], 0, v[154:155]
	s_nop 0
	v_permlane16_swap_b32_e32 v240, v242
	v_permlane16_swap_b32_e32 v241, v243
	global_store_dwordx4 v[156:157], v[240:243], off offset:0
	v_cmp_lt_i32_e32 vcc, s5, v66
	v_mov_b64_e32 v[46:47], 0
	s_and_saveexec_b64 s[48:49], vcc
	s_cbranch_execz .LBB0_584
	v_and_b32_e32 v48, 31, v62
	v_cmp_ne_u32_e32 vcc, 16, v48
	v_mov_b64_e32 v[46:47], 0
	s_and_saveexec_b64 s[50:51], vcc
	s_cbranch_execz .LBB0_583
	v_add_u32_e32 v46, 0xffffc010, v1
	v_lshrrev_b32_e32 v46, 5, v46
	v_mul_lo_u32 v46, v46, 15
	s_movk_i32 s5, 0xffef
	v_add3_u32 v46, v48, v46, s5
	v_mov_b32_e32 v47, v183
	v_readlane_b32 s6, v252, 57
	v_lshlrev_b64 v[46:47], 12, v[46:47]
	v_readlane_b32 s7, v252, 58
	s_nop 1
	v_lshl_add_u64 v[46:47], s[6:7], 0, v[46:47]
	v_lshl_add_u64 v[46:47], v[68:69], 2, v[46:47]
	v_lshl_add_u64 v[46:47], v[46:47], 0, 64

; DI unsigned pk2(float a, float b) { f32x2_t f = {a, b}; return __builtin_bit_cast(unsigned, __builtin_convertvector(f, bf16x2_t)); }
; DI float gelu_f(float x) { return 0.5f * x * (1.f + erff(x * 0.70710678118654752f)); }
; DI float silu_f(float x) { return x * __builtin_amdgcn_rcpf(1.f + __expf(-x)); }
; DI void st_bf4(u16* p, float a, float b, float c, float d) { *(uint2*)p = make_uint2(pk2(a, b), pk2(c, d)); }
;   template <int NT, int MT> DI void run(f32x4 (&acc)[NT][MT], int mb, int nb) const {
;     ...
;         } else if (n < 3072) {
;           st_bf4(uvbuf + (size_t)m * 2048 + (n - 1024), gelu_f(v[0]), gelu_f(v[1]), gelu_f(v[2]), gelu_f(v[3]));
;         } else {
;           st_bf4(gatebuf + (size_t)m * 2048 + (n - 3072), silu_f(v[0]), silu_f(v[1]), silu_f(v[2]), silu_f(v[3]));
.LBB0_587:
	s_or_b64 exec, exec, s[46:47]
	s_and_saveexec_b64 s[6:7], s[40:41]
	s_xor_b64 s[46:47], exec, s[6:7]
	s_cbranch_execz .LBB0_609
	v_lshlrev_b64 v[42:43], 12, v[58:59]
	s_and_saveexec_b64 s[6:7], s[38:39]
	s_xor_b64 s[48:49], exec, s[6:7]
	s_cbranch_execz .LBB0_590
	v_mul_f32_e32 v44, 0xbfb8aa3b, v38
	v_mul_f32_e32 v45, 0xbfb8aa3b, v39
	v_exp_f32_e32 v44, v44
	v_exp_f32_e32 v45, v45
	v_readlane_b32 s6, v252, 35
	v_readlane_b32 s7, v252, 36
	v_add_f32_e32 v44, 1.0, v44
	v_add_f32_e32 v45, 1.0, v45
	v_rcp_f32_e32 v44, v44
	v_rcp_f32_e32 v45, v45
	v_lshl_add_u64 v[42:43], s[6:7], 0, v[42:43]
	v_lshl_add_u64 v[42:43], v[182:183], 1, v[42:43]
	v_pk_mul_f32 v[38:39], v[38:39], v[44:45]
	v_mul_f32_e32 v44, 0xbfb8aa3b, v40
	v_mul_f32_e32 v45, 0xbfb8aa3b, v41
	v_exp_f32_e32 v44, v44
	v_exp_f32_e32 v45, v45
	v_cvt_pk_bf16_f32 v38, v38, v39
	v_add_f32_e32 v44, 1.0, v44
	v_add_f32_e32 v45, 1.0, v45
	v_rcp_f32_e32 v44, v44
	v_rcp_f32_e32 v45, v45
	s_nop 0
	v_pk_mul_f32 v[40:41], v[40:41], v[44:45]
	s_nop 0
	v_cvt_pk_bf16_f32 v39, v40, v41
	v_add_co_u32_e32 v40, vcc, 0xfffff000, v42
	s_nop 1
	v_addc_co_u32_e32 v41, vcc, -1, v43, vcc
	v_mov_b32_e32 v246, v38
	v_mov_b32_e32 v247, v39
	v_lshl_add_u64 v[156:157], v[40:41], 0, v[154:155]
	s_nop 0
	v_permlane16_swap_b32_e32 v244, v246
	v_permlane16_swap_b32_e32 v245, v247
	global_store_dwordx4 v[156:157], v[244:247], off offset:-2048
.LBB0_590:
	s_andn2_saveexec_b64 s[48:49], s[48:49]
	s_cbranch_execz .LBB0_608
	v_pk_mul_f32 v[130:131], v[38:39], v[170:171]
	v_pk_mul_f32 v[142:143], v[40:41], v[170:171]
	v_and_b32_e32 v132, 0x7fffffff, v130
	v_and_b32_e32 v144, 0x7fffffff, v142
	v_and_b32_e32 v133, 0x7fffffff, v131
	v_and_b32_e32 v145, 0x7fffffff, v143
	v_pk_fma_f32 v[134:135], v[132:133], v[174:175], v[176:177]
	v_pk_fma_f32 v[146:147], v[144:145], v[174:175], v[176:177]
	v_pk_fma_f32 v[134:135], v[132:133], v[134:135], v[178:179]
	v_pk_fma_f32 v[146:147], v[144:145], v[146:147], v[178:179]
	v_pk_fma_f32 v[134:135], v[132:133], v[134:135], v[180:181]
	v_pk_fma_f32 v[146:147], v[144:145], v[146:147], v[180:181]
	v_pk_fma_f32 v[134:135], v[132:133], v[134:135], v[186:187]
	v_pk_fma_f32 v[146:147], v[144:145], v[146:147], v[186:187]
	v_pk_fma_f32 v[134:135], v[132:133], v[134:135], v[188:189]
	v_pk_fma_f32 v[146:147], v[144:145], v[146:147], v[188:189]
	v_pk_fma_f32 v[134:135], v[132:133], v[134:135], v[190:191]
	v_pk_fma_f32 v[146:147], v[144:145], v[146:147], v[190:191]
	v_pk_fma_f32 v[134:135], v[132:133], v[134:135], v[132:133]
	v_pk_fma_f32 v[146:147], v[144:145], v[146:147], v[144:145]
	v_pk_mul_f32 v[134:135], v[134:135], v[172:173]
	v_pk_mul_f32 v[146:147], v[146:147], v[172:173]
	v_pk_mul_f32 v[136:137], v[130:131], v[130:131]
	v_pk_mul_f32 v[148:149], v[142:143], v[142:143]
	v_exp_f32_e32 v134, v134
	v_exp_f32_e32 v146, v146
	v_exp_f32_e32 v135, v135
	v_exp_f32_e32 v147, v147
	v_pk_fma_f32 v[138:139], v[136:137], v[192:193], v[194:195]
	v_pk_fma_f32 v[150:151], v[148:149], v[192:193], v[194:195]
	v_pk_fma_f32 v[138:139], v[136:137], v[138:139], v[196:197]
	v_pk_fma_f32 v[150:151], v[148:149], v[150:151], v[196:197]
	v_pk_fma_f32 v[138:139], v[136:137], v[138:139], v[224:225]
	v_pk_fma_f32 v[150:151], v[148:149], v[150:151], v[224:225]
	v_pk_fma_f32 v[138:139], v[136:137], v[138:139], v[226:227]
	v_pk_fma_f32 v[150:151], v[148:149], v[150:151], v[226:227]
	v_pk_fma_f32 v[138:139], v[136:137], v[138:139], v[228:229]
	v_pk_fma_f32 v[150:151], v[148:149], v[150:151], v[228:229]
	v_pk_fma_f32 v[134:135], v[134:135], v[234:235], v[230:231]
	v_pk_fma_f32 v[146:147], v[146:147], v[234:235], v[230:231]
	v_pk_fma_f32 v[138:139], v[132:133], v[138:139], v[132:133]
	v_pk_fma_f32 v[150:151], v[144:145], v[150:151], v[144:145]
	v_pk_mul_f32 v[140:141], v[38:39], v[232:233]
	v_pk_mul_f32 v[152:153], v[40:41], v[232:233]
	v_cmp_ngt_f32_e32 vcc, 1.0, v132
	v_cmp_ngt_f32_e64 s[8:9], 1.0, v133
	v_readlane_b32 s6, v252, 33
	v_readlane_b32 s7, v252, 34
	v_cndmask_b32_e32 v138, v138, v134, vcc
	v_cndmask_b32_e64 v139, v139, v135, s[8:9]
	v_cmp_ngt_f32_e32 vcc, 1.0, v144
	v_cmp_ngt_f32_e64 s[8:9], 1.0, v145
	v_bfi_b32 v138, s37, v138, v130
	v_bfi_b32 v139, s37, v139, v131
	v_cndmask_b32_e32 v150, v150, v146, vcc
	v_cndmask_b32_e64 v151, v151, v147, s[8:9]
	v_pk_add_f32 v[138:139], v[138:139], v[230:231]
	v_bfi_b32 v150, s37, v150, v142
	v_bfi_b32 v151, s37, v151, v143
	v_pk_add_f32 v[150:151], v[150:151], v[230:231]
	v_pk_mul_f32 v[138:139], v[140:141], v[138:139]
	v_lshl_add_u64 v[38:39], s[6:7], 0, v[42:43]
	v_pk_mul_f32 v[150:151], v[152:153], v[150:151]
	v_lshl_add_u64 v[38:39], v[182:183], 1, v[38:39]
	v_cvt_pk_bf16_f32 v40, v138, v139
	v_cvt_pk_bf16_f32 v41, v150, v151
	v_mov_b32_e32 v246, v40
	v_mov_b32_e32 v247, v41
	v_lshl_add_u64 v[156:157], v[38:39], 0, v[154:155]
	s_nop 0
	v_permlane16_swap_b32_e32 v244, v246
	v_permlane16_swap_b32_e32 v245, v247
	global_store_dwordx4 v[156:157], v[244:247], off offset:-2048

; DI float gelu_f(float x) { return 0.5f * x * (1.f + erff(x * 0.70710678118654752f)); }
; DI float silu_f(float x) { return x * __builtin_amdgcn_rcpf(1.f + __expf(-x)); }
; DI void st_bf4(u16* p, float a, float b, float c, float d) { *(uint2*)p = make_uint2(pk2(a, b), pk2(c, d)); }
;   template <int NT, int MT> DI void run(f32x4 (&acc)[NT][MT], int mb, int nb) const {
;     ...
;         if (n < 1024) {
;           st_bf4(abuf + (size_t)m * 1024 + n, v[0], v[1], v[2], v[3]);
;           float* dst = nullptr;
;           if (m < M_PROMPT) { int t = m & 8191; if (t >= 8177) dst = spp + ((size_t)((m >> 13) * 15 + (t - 8177))) * 1024 + n; }
;           else { int r = m - M_PROMPT; int s = r & 31; if (s >= 17) dst = sps + ((size_t)((r >> 5) * 15 + (s - 17))) * 1024 + n; }
;           if (dst) *(float4*)dst = make_float4(v[0], v[1], v[2], v[3]);
;         } else if (n < 3072) {
;           st_bf4(uvbuf + (size_t)m * 2048 + (n - 1024), gelu_f(v[0]), gelu_f(v[1]), gelu_f(v[2]), gelu_f(v[3]));
;         } else {
;           st_bf4(gatebuf + (size_t)m * 2048 + (n - 3072), silu_f(v[0]), silu_f(v[1]), silu_f(v[2]), silu_f(v[3]));
.LBB0_609:
	s_andn2_saveexec_b64 s[46:47], s[46:47]
	s_cbranch_execz .LBB0_611
	v_lshlrev_b64 v[42:43], 11, v[58:59]
	v_lshl_add_u64 v[42:43], s[96:97], 0, v[42:43]
	v_lshl_add_u64 v[42:43], v[68:69], 1, v[42:43]
	v_cvt_pk_bf16_f32 v38, v38, v39
	v_cvt_pk_bf16_f32 v39, v40, v41
	v_mov_b32_e32 v246, v38
	v_mov_b32_e32 v247, v39
	v_lshl_add_u64 v[156:157], v[42:43], 0, v[154:155]
	s_nop 0
	v_permlane16_swap_b32_e32 v244, v246
	v_permlane16_swap_b32_e32 v245, v247
	global_store_dwordx4 v[156:157], v[244:247], off offset:0
.LBB0_611:
	s_or_b64 exec, exec, s[46:47]
	s_and_saveexec_b64 s[6:7], s[40:41]
	s_xor_b64 s[40:41], exec, s[6:7]
	s_cbranch_execz .LBB0_633
	v_lshlrev_b64 v[38:39], 12, v[54:55]
	s_and_saveexec_b64 s[6:7], s[38:39]
	s_xor_b64 s[46:47], exec, s[6:7]
	s_cbranch_execz .LBB0_614
	v_mul_f32_e32 v40, 0xbfb8aa3b, v34
	v_mul_f32_e32 v41, 0xbfb8aa3b, v35
	v_exp_f32_e32 v40, v40
	v_exp_f32_e32 v41, v41
	v_readlane_b32 s6, v252, 35
	v_readlane_b32 s7, v252, 36
	v_add_f32_e32 v40, 1.0, v40
	v_add_f32_e32 v41, 1.0, v41
	v_rcp_f32_e32 v40, v40
	v_rcp_f32_e32 v41, v41
	v_lshl_add_u64 v[38:39], s[6:7], 0, v[38:39]
	v_lshl_add_u64 v[38:39], v[182:183], 1, v[38:39]
	v_pk_mul_f32 v[34:35], v[34:35], v[40:41]
	v_mul_f32_e32 v40, 0xbfb8aa3b, v36
	v_mul_f32_e32 v41, 0xbfb8aa3b, v37
	v_exp_f32_e32 v40, v40
	v_exp_f32_e32 v41, v41
	v_cvt_pk_bf16_f32 v34, v34, v35
	v_add_f32_e32 v40, 1.0, v40
	v_add_f32_e32 v41, 1.0, v41
	v_rcp_f32_e32 v40, v40
	v_rcp_f32_e32 v41, v41
	s_nop 0
	v_pk_mul_f32 v[36:37], v[36:37], v[40:41]
	s_nop 0
	v_cvt_pk_bf16_f32 v35, v36, v37
	v_add_co_u32_e32 v36, vcc, 0xfffff000, v38
	s_nop 1
	v_addc_co_u32_e32 v37, vcc, -1, v39, vcc
	v_mov_b32_e32 v250, v34
	v_mov_b32_e32 v251, v35
	v_lshl_add_u64 v[156:157], v[36:37], 0, v[154:155]
	s_nop 0
	v_permlane16_swap_b32_e32 v248, v250
	v_permlane16_swap_b32_e32 v249, v251
	global_store_dwordx4 v[156:157], v[248:251], off offset:-2048
.LBB0_614:
	s_andn2_saveexec_b64 s[46:47], s[46:47]
	s_cbranch_execz .LBB0_632
	v_pk_mul_f32 v[130:131], v[34:35], v[170:171]
	v_pk_mul_f32 v[142:143], v[36:37], v[170:171]
	v_and_b32_e32 v132, 0x7fffffff, v130
	v_and_b32_e32 v144, 0x7fffffff, v142
	v_and_b32_e32 v133, 0x7fffffff, v131
	v_and_b32_e32 v145, 0x7fffffff, v143
	v_pk_fma_f32 v[134:135], v[132:133], v[174:175], v[176:177]
	v_pk_fma_f32 v[146:147], v[144:145], v[174:175], v[176:177]
	v_pk_fma_f32 v[134:135], v[132:133], v[134:135], v[178:179]
	v_pk_fma_f32 v[146:147], v[144:145], v[146:147], v[178:179]
	v_pk_fma_f32 v[134:135], v[132:133], v[134:135], v[180:181]
	v_pk_fma_f32 v[146:147], v[144:145], v[146:147], v[180:181]
	v_pk_fma_f32 v[134:135], v[132:133], v[134:135], v[186:187]
	v_pk_fma_f32 v[146:147], v[144:145], v[146:147], v[186:187]
	v_pk_fma_f32 v[134:135], v[132:133], v[134:135], v[188:189]
	v_pk_fma_f32 v[146:147], v[144:145], v[146:147], v[188:189]
	v_pk_fma_f32 v[134:135], v[132:133], v[134:135], v[190:191]
	v_pk_fma_f32 v[146:147], v[144:145], v[146:147], v[190:191]
	v_pk_fma_f32 v[134:135], v[132:133], v[134:135], v[132:133]
	v_pk_fma_f32 v[146:147], v[144:145], v[146:147], v[144:145]
	v_pk_mul_f32 v[134:135], v[134:135], v[172:173]
	v_pk_mul_f32 v[146:147], v[146:147], v[172:173]
	v_pk_mul_f32 v[136:137], v[130:131], v[130:131]
	v_pk_mul_f32 v[148:149], v[142:143], v[142:143]
	v_exp_f32_e32 v134, v134
	v_exp_f32_e32 v146, v146
	v_exp_f32_e32 v135, v135
	v_exp_f32_e32 v147, v147
	v_pk_fma_f32 v[138:139], v[136:137], v[192:193], v[194:195]
	v_pk_fma_f32 v[150:151], v[148:149], v[192:193], v[194:195]
	v_pk_fma_f32 v[138:139], v[136:137], v[138:139], v[196:197]
	v_pk_fma_f32 v[150:151], v[148:149], v[150:151], v[196:197]
	v_pk_fma_f32 v[138:139], v[136:137], v[138:139], v[224:225]
	v_pk_fma_f32 v[150:151], v[148:149], v[150:151], v[224:225]
	v_pk_fma_f32 v[138:139], v[136:137], v[138:139], v[226:227]
	v_pk_fma_f32 v[150:151], v[148:149], v[150:151], v[226:227]
	v_pk_fma_f32 v[138:139], v[136:137], v[138:139], v[228:229]
	v_pk_fma_f32 v[150:151], v[148:149], v[150:151], v[228:229]
	v_pk_fma_f32 v[134:135], v[134:135], v[234:235], v[230:231]
	v_pk_fma_f32 v[146:147], v[146:147], v[234:235], v[230:231]
	v_pk_fma_f32 v[138:139], v[132:133], v[138:139], v[132:133]
	v_pk_fma_f32 v[150:151], v[144:145], v[150:151], v[144:145]
	v_pk_mul_f32 v[140:141], v[34:35], v[232:233]
	v_pk_mul_f32 v[152:153], v[36:37], v[232:233]
	v_cmp_ngt_f32_e32 vcc, 1.0, v132
	v_cmp_ngt_f32_e64 s[8:9], 1.0, v133
	v_readlane_b32 s6, v252, 33
	v_readlane_b32 s7, v252, 34
	v_cndmask_b32_e32 v138, v138, v134, vcc
	v_cndmask_b32_e64 v139, v139, v135, s[8:9]
	v_cmp_ngt_f32_e32 vcc, 1.0, v144
	v_cmp_ngt_f32_e64 s[8:9], 1.0, v145
	v_bfi_b32 v138, s37, v138, v130
	v_bfi_b32 v139, s37, v139, v131
	v_cndmask_b32_e32 v150, v150, v146, vcc
	v_cndmask_b32_e64 v151, v151, v147, s[8:9]
	v_pk_add_f32 v[138:139], v[138:139], v[230:231]
	v_bfi_b32 v150, s37, v150, v142
	v_bfi_b32 v151, s37, v151, v143
	v_pk_add_f32 v[150:151], v[150:151], v[230:231]
	v_pk_mul_f32 v[138:139], v[140:141], v[138:139]
	v_lshl_add_u64 v[34:35], s[6:7], 0, v[38:39]
	v_pk_mul_f32 v[150:151], v[152:153], v[150:151]
	v_lshl_add_u64 v[34:35], v[182:183], 1, v[34:35]
	v_cvt_pk_bf16_f32 v36, v138, v139
	v_cvt_pk_bf16_f32 v37, v150, v151
	v_mov_b32_e32 v250, v36
	v_mov_b32_e32 v251, v37
	v_lshl_add_u64 v[156:157], v[34:35], 0, v[154:155]
	s_nop 0
	v_permlane16_swap_b32_e32 v248, v250
	v_permlane16_swap_b32_e32 v249, v251
	global_store_dwordx4 v[156:157], v[248:251], off offset:-2048

; DI void st_bf4(u16* p, float a, float b, float c, float d) { *(uint2*)p = make_uint2(pk2(a, b), pk2(c, d)); }
;   template <int NT, int MT> DI void run(f32x4 (&acc)[NT][MT], int mb, int nb) const {
;     ...
;         if (n < 1024) {
;           st_bf4(abuf + (size_t)m * 1024 + n, v[0], v[1], v[2], v[3]);
;           float* dst = nullptr;
;           if (m < M_PROMPT) { int t = m & 8191; if (t >= 8177) dst = spp + ((size_t)((m >> 13) * 15 + (t - 8177))) * 1024 + n; }
;           else { int r = m - M_PROMPT; int s = r & 31; if (s >= 17) dst = sps + ((size_t)((r >> 5) * 15 + (s - 17))) * 1024 + n; }
;           if (dst) *(float4*)dst = make_float4(v[0], v[1], v[2], v[3]);
.LBB0_633:
	s_andn2_saveexec_b64 s[40:41], s[40:41]
	s_cbranch_execz .LBB0_641
	v_lshlrev_b64 v[38:39], 11, v[54:55]
	v_lshl_add_u64 v[38:39], s[96:97], 0, v[38:39]
	s_movk_i32 s5, 0x3fcf
	v_lshl_add_u64 v[38:39], v[68:69], 1, v[38:39]
	v_cvt_pk_bf16_f32 v40, v34, v35
	v_cvt_pk_bf16_f32 v41, v36, v37
	v_cmp_lt_i32_e32 vcc, s5, v66
	v_mov_b32_e32 v250, v40
	v_mov_b32_e32 v251, v41
	v_lshl_add_u64 v[156:157], v[38:39], 0, v[154:155]
	s_nop 0
	v_permlane16_swap_b32_e32 v248, v250
	v_permlane16_swap_b32_e32 v249, v251
	global_store_dwordx4 v[156:157], v[248:251], off offset:0
	s_and_saveexec_b64 s[6:7], vcc
	s_xor_b64 s[46:47], exec, s[6:7]
	s_cbranch_execz .LBB0_859
	v_and_b32_e32 v40, 31, v54
	v_cmp_ne_u32_e32 vcc, 16, v40
	v_mov_b64_e32 v[38:39], 0
	s_and_saveexec_b64 s[48:49], vcc
	s_cbranch_execz .LBB0_637
	v_add_u32_e32 v38, 0xffffc030, v1
	v_lshrrev_b32_e32 v38, 5, v38
	v_mul_lo_u32 v38, v38, 15
	s_movk_i32 s5, 0xffef
	v_add3_u32 v38, v40, v38, s5
	v_mov_b32_e32 v39, v183
	v_readlane_b32 s6, v252, 57
	v_lshlrev_b64 v[38:39], 12, v[38:39]
	v_readlane_b32 s7, v252, 58
	s_nop 1
	v_lshl_add_u64 v[38:39], s[6:7], 0, v[38:39]
	v_lshl_add_u64 v[38:39], v[68:69], 2, v[38:39]
	v_lshl_add_u64 v[38:39], v[38:39], 0, 64

; DI float gelu_f(float x) { return 0.5f * x * (1.f + erff(x * 0.70710678118654752f)); }
; DI float silu_f(float x) { return x * __builtin_amdgcn_rcpf(1.f + __expf(-x)); }
; DI void st_bf4(u16* p, float a, float b, float c, float d) { *(uint2*)p = make_uint2(pk2(a, b), pk2(c, d)); }
;   template <int NT, int MT> DI void run(f32x4 (&acc)[NT][MT], int mb, int nb) const {
;     ...
;         } else if (n < 3072) {
;           st_bf4(uvbuf + (size_t)m * 2048 + (n - 1024), gelu_f(v[0]), gelu_f(v[1]), gelu_f(v[2]), gelu_f(v[3]));
;         } else {
;           st_bf4(gatebuf + (size_t)m * 2048 + (n - 3072), silu_f(v[0]), silu_f(v[1]), silu_f(v[2]), silu_f(v[3]));
.LBB0_641:
	s_or_b64 exec, exec, s[40:41]
	s_movk_i32 s5, 0x3df
	v_cmp_lt_i32_e64 s[40:41], s5, v68
	s_and_saveexec_b64 s[6:7], s[40:41]
	s_xor_b64 s[46:47], exec, s[6:7]
	s_cbranch_execz .LBB0_663
	v_lshlrev_b64 v[34:35], 12, v[66:67]
	s_and_saveexec_b64 s[6:7], s[38:39]
	s_xor_b64 s[48:49], exec, s[6:7]
	s_cbranch_execz .LBB0_644
	v_mul_f32_e32 v36, 0xbfb8aa3b, v30
	v_mul_f32_e32 v37, 0xbfb8aa3b, v31
	v_exp_f32_e32 v36, v36
	v_exp_f32_e32 v37, v37
	v_readlane_b32 s6, v252, 35
	v_readlane_b32 s7, v252, 36
	v_add_f32_e32 v36, 1.0, v36
	v_add_f32_e32 v37, 1.0, v37
	v_rcp_f32_e32 v36, v36
	v_rcp_f32_e32 v37, v37
	v_lshl_add_u64 v[34:35], s[6:7], 0, v[34:35]
	v_lshl_add_u64 v[34:35], v[182:183], 1, v[34:35]
	v_pk_mul_f32 v[30:31], v[30:31], v[36:37]
	v_mul_f32_e32 v36, 0xbfb8aa3b, v32
	v_mul_f32_e32 v37, 0xbfb8aa3b, v33
	v_exp_f32_e32 v36, v36
	v_exp_f32_e32 v37, v37
	v_cvt_pk_bf16_f32 v30, v30, v31
	v_add_f32_e32 v36, 1.0, v36
	v_add_f32_e32 v37, 1.0, v37
	v_rcp_f32_e32 v36, v36
	v_rcp_f32_e32 v37, v37
	s_nop 0
	v_pk_mul_f32 v[32:33], v[32:33], v[36:37]
	s_nop 0
	v_cvt_pk_bf16_f32 v31, v32, v33
	v_add_co_u32_e32 v32, vcc, 0xfffff000, v34
	s_nop 1
	v_addc_co_u32_e32 v33, vcc, -1, v35, vcc
	v_mov_b32_e32 v236, v30
	v_mov_b32_e32 v237, v31
.LBB0_644:
	s_andn2_saveexec_b64 s[48:49], s[48:49]
	s_cbranch_execz .LBB0_662
	v_pk_mul_f32 v[130:131], v[30:31], v[170:171]
	v_pk_mul_f32 v[142:143], v[32:33], v[170:171]
	v_and_b32_e32 v132, 0x7fffffff, v130
	v_and_b32_e32 v144, 0x7fffffff, v142
	v_and_b32_e32 v133, 0x7fffffff, v131
	v_and_b32_e32 v145, 0x7fffffff, v143
	v_pk_fma_f32 v[134:135], v[132:133], v[174:175], v[176:177]
	v_pk_fma_f32 v[146:147], v[144:145], v[174:175], v[176:177]
	v_pk_fma_f32 v[134:135], v[132:133], v[134:135], v[178:179]
	v_pk_fma_f32 v[146:147], v[144:145], v[146:147], v[178:179]
	v_pk_fma_f32 v[134:135], v[132:133], v[134:135], v[180:181]
	v_pk_fma_f32 v[146:147], v[144:145], v[146:147], v[180:181]
	v_pk_fma_f32 v[134:135], v[132:133], v[134:135], v[186:187]
	v_pk_fma_f32 v[146:147], v[144:145], v[146:147], v[186:187]
	v_pk_fma_f32 v[134:135], v[132:133], v[134:135], v[188:189]
	v_pk_fma_f32 v[146:147], v[144:145], v[146:147], v[188:189]
	v_pk_fma_f32 v[134:135], v[132:133], v[134:135], v[190:191]
	v_pk_fma_f32 v[146:147], v[144:145], v[146:147], v[190:191]
	v_pk_fma_f32 v[134:135], v[132:133], v[134:135], v[132:133]
	v_pk_fma_f32 v[146:147], v[144:145], v[146:147], v[144:145]
	v_pk_mul_f32 v[134:135], v[134:135], v[172:173]
	v_pk_mul_f32 v[146:147], v[146:147], v[172:173]
	v_pk_mul_f32 v[136:137], v[130:131], v[130:131]
	v_pk_mul_f32 v[148:149], v[142:143], v[142:143]
	v_exp_f32_e32 v134, v134
	v_exp_f32_e32 v146, v146
	v_exp_f32_e32 v135, v135
	v_exp_f32_e32 v147, v147
	v_pk_fma_f32 v[138:139], v[136:137], v[192:193], v[194:195]
	v_pk_fma_f32 v[150:151], v[148:149], v[192:193], v[194:195]
	v_pk_fma_f32 v[138:139], v[136:137], v[138:139], v[196:197]
	v_pk_fma_f32 v[150:151], v[148:149], v[150:151], v[196:197]
	v_pk_fma_f32 v[138:139], v[136:137], v[138:139], v[224:225]
	v_pk_fma_f32 v[150:151], v[148:149], v[150:151], v[224:225]
	v_pk_fma_f32 v[138:139], v[136:137], v[138:139], v[226:227]
	v_pk_fma_f32 v[150:151], v[148:149], v[150:151], v[226:227]
	v_pk_fma_f32 v[138:139], v[136:137], v[138:139], v[228:229]
	v_pk_fma_f32 v[150:151], v[148:149], v[150:151], v[228:229]
	v_pk_fma_f32 v[134:135], v[134:135], v[234:235], v[230:231]
	v_pk_fma_f32 v[146:147], v[146:147], v[234:235], v[230:231]
	v_pk_fma_f32 v[138:139], v[132:133], v[138:139], v[132:133]
	v_pk_fma_f32 v[150:151], v[144:145], v[150:151], v[144:145]
	v_pk_mul_f32 v[140:141], v[30:31], v[232:233]
	v_pk_mul_f32 v[152:153], v[32:33], v[232:233]
	v_cmp_ngt_f32_e32 vcc, 1.0, v132
	v_cmp_ngt_f32_e64 s[8:9], 1.0, v133
	v_readlane_b32 s6, v252, 33
	v_readlane_b32 s7, v252, 34
	v_cndmask_b32_e32 v138, v138, v134, vcc
	v_cndmask_b32_e64 v139, v139, v135, s[8:9]
	v_cmp_ngt_f32_e32 vcc, 1.0, v144
	v_cmp_ngt_f32_e64 s[8:9], 1.0, v145
	v_bfi_b32 v138, s37, v138, v130
	v_bfi_b32 v139, s37, v139, v131
	v_cndmask_b32_e32 v150, v150, v146, vcc
	v_cndmask_b32_e64 v151, v151, v147, s[8:9]
	v_pk_add_f32 v[138:139], v[138:139], v[230:231]
	v_bfi_b32 v150, s37, v150, v142
	v_bfi_b32 v151, s37, v151, v143
	v_pk_add_f32 v[150:151], v[150:151], v[230:231]
	v_pk_mul_f32 v[138:139], v[140:141], v[138:139]
	v_lshl_add_u64 v[30:31], s[6:7], 0, v[34:35]
	v_pk_mul_f32 v[150:151], v[152:153], v[150:151]
	v_lshl_add_u64 v[30:31], v[182:183], 1, v[30:31]
	v_cvt_pk_bf16_f32 v32, v138, v139
	v_cvt_pk_bf16_f32 v33, v150, v151
	v_mov_b32_e32 v236, v32
	v_mov_b32_e32 v237, v33

; DI float gelu_f(float x) { return 0.5f * x * (1.f + erff(x * 0.70710678118654752f)); }
; DI float silu_f(float x) { return x * __builtin_amdgcn_rcpf(1.f + __expf(-x)); }
; DI void st_bf4(u16* p, float a, float b, float c, float d) { *(uint2*)p = make_uint2(pk2(a, b), pk2(c, d)); }
;   template <int NT, int MT> DI void run(f32x4 (&acc)[NT][MT], int mb, int nb) const {
;     ...
;         if (n < 1024) {
;           st_bf4(abuf + (size_t)m * 1024 + n, v[0], v[1], v[2], v[3]);
;           float* dst = nullptr;
;           if (m < M_PROMPT) { int t = m & 8191; if (t >= 8177) dst = spp + ((size_t)((m >> 13) * 15 + (t - 8177))) * 1024 + n; }
;           else { int r = m - M_PROMPT; int s = r & 31; if (s >= 17) dst = sps + ((size_t)((r >> 5) * 15 + (s - 17))) * 1024 + n; }
;           if (dst) *(float4*)dst = make_float4(v[0], v[1], v[2], v[3]);
;         } else if (n < 3072) {
;           st_bf4(uvbuf + (size_t)m * 2048 + (n - 1024), gelu_f(v[0]), gelu_f(v[1]), gelu_f(v[2]), gelu_f(v[3]));
;         } else {
;           st_bf4(gatebuf + (size_t)m * 2048 + (n - 3072), silu_f(v[0]), silu_f(v[1]), silu_f(v[2]), silu_f(v[3]));
.LBB0_663:
	s_andn2_saveexec_b64 s[46:47], s[46:47]
	s_cbranch_execz .LBB0_665
	v_lshlrev_b64 v[34:35], 11, v[66:67]
	v_lshl_add_u64 v[34:35], s[96:97], 0, v[34:35]
	v_lshl_add_u64 v[34:35], v[68:69], 1, v[34:35]
	v_cvt_pk_bf16_f32 v30, v30, v31
	v_cvt_pk_bf16_f32 v31, v32, v33
	v_mov_b32_e32 v236, v30
	v_mov_b32_e32 v237, v31
.LBB0_665:
	s_or_b64 exec, exec, s[46:47]
	s_and_saveexec_b64 s[6:7], s[40:41]
	s_xor_b64 s[46:47], exec, s[6:7]
	s_cbranch_execz .LBB0_687
	v_lshlrev_b64 v[30:31], 12, v[62:63]
	s_and_saveexec_b64 s[6:7], s[38:39]
	s_xor_b64 s[48:49], exec, s[6:7]
	s_cbranch_execz .LBB0_668
	v_mul_f32_e32 v32, 0xbfb8aa3b, v26
	v_mul_f32_e32 v33, 0xbfb8aa3b, v27
	v_exp_f32_e32 v32, v32
	v_exp_f32_e32 v33, v33
	v_readlane_b32 s6, v252, 35
	v_readlane_b32 s7, v252, 36
	v_add_f32_e32 v32, 1.0, v32
	v_add_f32_e32 v33, 1.0, v33
	v_rcp_f32_e32 v32, v32
	v_rcp_f32_e32 v33, v33
	v_lshl_add_u64 v[30:31], s[6:7], 0, v[30:31]
	v_lshl_add_u64 v[30:31], v[182:183], 1, v[30:31]
	v_pk_mul_f32 v[26:27], v[26:27], v[32:33]
	v_mul_f32_e32 v32, 0xbfb8aa3b, v28
	v_mul_f32_e32 v33, 0xbfb8aa3b, v29
	v_exp_f32_e32 v32, v32
	v_exp_f32_e32 v33, v33
	v_cvt_pk_bf16_f32 v26, v26, v27
	v_add_f32_e32 v32, 1.0, v32
	v_add_f32_e32 v33, 1.0, v33
	v_rcp_f32_e32 v32, v32
	v_rcp_f32_e32 v33, v33
	s_nop 0
	v_pk_mul_f32 v[28:29], v[28:29], v[32:33]
	s_nop 0
	v_cvt_pk_bf16_f32 v27, v28, v29
	v_add_co_u32_e32 v28, vcc, 0xfffff000, v30
	s_nop 1
	v_addc_co_u32_e32 v29, vcc, -1, v31, vcc
	v_mov_b32_e32 v240, v26
	v_mov_b32_e32 v241, v27
.LBB0_668:
	s_andn2_saveexec_b64 s[48:49], s[48:49]
	s_cbranch_execz .LBB0_686
	v_pk_mul_f32 v[130:131], v[26:27], v[170:171]
	v_pk_mul_f32 v[142:143], v[28:29], v[170:171]
	v_and_b32_e32 v132, 0x7fffffff, v130
	v_and_b32_e32 v144, 0x7fffffff, v142
	v_and_b32_e32 v133, 0x7fffffff, v131
	v_and_b32_e32 v145, 0x7fffffff, v143
	v_pk_fma_f32 v[134:135], v[132:133], v[174:175], v[176:177]
	v_pk_fma_f32 v[146:147], v[144:145], v[174:175], v[176:177]
	v_pk_fma_f32 v[134:135], v[132:133], v[134:135], v[178:179]
	v_pk_fma_f32 v[146:147], v[144:145], v[146:147], v[178:179]
	v_pk_fma_f32 v[134:135], v[132:133], v[134:135], v[180:181]
	v_pk_fma_f32 v[146:147], v[144:145], v[146:147], v[180:181]
	v_pk_fma_f32 v[134:135], v[132:133], v[134:135], v[186:187]
	v_pk_fma_f32 v[146:147], v[144:145], v[146:147], v[186:187]
	v_pk_fma_f32 v[134:135], v[132:133], v[134:135], v[188:189]
	v_pk_fma_f32 v[146:147], v[144:145], v[146:147], v[188:189]
	v_pk_fma_f32 v[134:135], v[132:133], v[134:135], v[190:191]
	v_pk_fma_f32 v[146:147], v[144:145], v[146:147], v[190:191]
	v_pk_fma_f32 v[134:135], v[132:133], v[134:135], v[132:133]
	v_pk_fma_f32 v[146:147], v[144:145], v[146:147], v[144:145]
	v_pk_mul_f32 v[134:135], v[134:135], v[172:173]
	v_pk_mul_f32 v[146:147], v[146:147], v[172:173]
	v_pk_mul_f32 v[136:137], v[130:131], v[130:131]
	v_pk_mul_f32 v[148:149], v[142:143], v[142:143]
	v_exp_f32_e32 v134, v134
	v_exp_f32_e32 v146, v146
	v_exp_f32_e32 v135, v135
	v_exp_f32_e32 v147, v147
	v_pk_fma_f32 v[138:139], v[136:137], v[192:193], v[194:195]
	v_pk_fma_f32 v[150:151], v[148:149], v[192:193], v[194:195]
	v_pk_fma_f32 v[138:139], v[136:137], v[138:139], v[196:197]
	v_pk_fma_f32 v[150:151], v[148:149], v[150:151], v[196:197]
	v_pk_fma_f32 v[138:139], v[136:137], v[138:139], v[224:225]
	v_pk_fma_f32 v[150:151], v[148:149], v[150:151], v[224:225]
	v_pk_fma_f32 v[138:139], v[136:137], v[138:139], v[226:227]
	v_pk_fma_f32 v[150:151], v[148:149], v[150:151], v[226:227]
	v_pk_fma_f32 v[138:139], v[136:137], v[138:139], v[228:229]
	v_pk_fma_f32 v[150:151], v[148:149], v[150:151], v[228:229]
	v_pk_fma_f32 v[134:135], v[134:135], v[234:235], v[230:231]
	v_pk_fma_f32 v[146:147], v[146:147], v[234:235], v[230:231]
	v_pk_fma_f32 v[138:139], v[132:133], v[138:139], v[132:133]
	v_pk_fma_f32 v[150:151], v[144:145], v[150:151], v[144:145]
	v_pk_mul_f32 v[140:141], v[26:27], v[232:233]
	v_pk_mul_f32 v[152:153], v[28:29], v[232:233]
	v_cmp_ngt_f32_e32 vcc, 1.0, v132
	v_cmp_ngt_f32_e64 s[8:9], 1.0, v133
	v_readlane_b32 s6, v252, 33
	v_readlane_b32 s7, v252, 34
	v_cndmask_b32_e32 v138, v138, v134, vcc
	v_cndmask_b32_e64 v139, v139, v135, s[8:9]
	v_cmp_ngt_f32_e32 vcc, 1.0, v144
	v_cmp_ngt_f32_e64 s[8:9], 1.0, v145
	v_bfi_b32 v138, s37, v138, v130
	v_bfi_b32 v139, s37, v139, v131
	v_cndmask_b32_e32 v150, v150, v146, vcc
	v_cndmask_b32_e64 v151, v151, v147, s[8:9]
	v_pk_add_f32 v[138:139], v[138:139], v[230:231]
	v_bfi_b32 v150, s37, v150, v142
	v_bfi_b32 v151, s37, v151, v143
	v_pk_add_f32 v[150:151], v[150:151], v[230:231]
	v_pk_mul_f32 v[138:139], v[140:141], v[138:139]
	v_lshl_add_u64 v[26:27], s[6:7], 0, v[30:31]
	v_pk_mul_f32 v[150:151], v[152:153], v[150:151]
	v_lshl_add_u64 v[26:27], v[182:183], 1, v[26:27]
	v_cvt_pk_bf16_f32 v28, v138, v139
	v_cvt_pk_bf16_f32 v29, v150, v151
	v_mov_b32_e32 v240, v28
	v_mov_b32_e32 v241, v29

; DI void st_bf4(u16* p, float a, float b, float c, float d) { *(uint2*)p = make_uint2(pk2(a, b), pk2(c, d)); }
;   template <int NT, int MT> DI void run(f32x4 (&acc)[NT][MT], int mb, int nb) const {
;     ...
;         if (n < 1024) {
;           st_bf4(abuf + (size_t)m * 1024 + n, v[0], v[1], v[2], v[3]);
;           float* dst = nullptr;
;           if (m < M_PROMPT) { int t = m & 8191; if (t >= 8177) dst = spp + ((size_t)((m >> 13) * 15 + (t - 8177))) * 1024 + n; }
;           else { int r = m - M_PROMPT; int s = r & 31; if (s >= 17) dst = sps + ((size_t)((r >> 5) * 15 + (s - 17))) * 1024 + n; }
;           if (dst) *(float4*)dst = make_float4(v[0], v[1], v[2], v[3]);
.LBB0_687:
	s_andn2_saveexec_b64 s[46:47], s[46:47]
	s_cbranch_execz .LBB0_695
	v_lshlrev_b64 v[30:31], 11, v[62:63]
	v_lshl_add_u64 v[30:31], s[96:97], 0, v[30:31]
	v_lshl_add_u64 v[30:31], v[68:69], 1, v[30:31]
	v_cvt_pk_bf16_f32 v32, v26, v27
	v_cvt_pk_bf16_f32 v33, v28, v29
	s_movk_i32 s5, 0x3fef
	v_mov_b32_e32 v240, v32
	v_mov_b32_e32 v241, v33
	v_cmp_lt_i32_e32 vcc, s5, v66
	v_mov_b64_e32 v[30:31], 0
	s_and_saveexec_b64 s[48:49], vcc
	s_cbranch_execz .LBB0_692
	v_and_b32_e32 v32, 31, v62
	v_cmp_ne_u32_e32 vcc, 16, v32
	v_mov_b64_e32 v[30:31], 0
	s_and_saveexec_b64 s[50:51], vcc
	s_cbranch_execz .LBB0_691
	v_add_u32_e32 v30, 0xffffc010, v1
	v_lshrrev_b32_e32 v30, 5, v30
	v_mul_lo_u32 v30, v30, 15
	s_movk_i32 s5, 0xffef
	v_add3_u32 v30, v32, v30, s5
	v_mov_b32_e32 v31, v183
	v_readlane_b32 s6, v252, 57
	v_lshlrev_b64 v[30:31], 12, v[30:31]
	v_readlane_b32 s7, v252, 58
	s_nop 1
	v_lshl_add_u64 v[30:31], s[6:7], 0, v[30:31]
	v_lshl_add_u64 v[30:31], v[68:69], 2, v[30:31]
	v_lshl_add_u64 v[30:31], v[30:31], 0, s[28:29]

; DI float gelu_f(float x) { return 0.5f * x * (1.f + erff(x * 0.70710678118654752f)); }
; DI float silu_f(float x) { return x * __builtin_amdgcn_rcpf(1.f + __expf(-x)); }
; DI void st_bf4(u16* p, float a, float b, float c, float d) { *(uint2*)p = make_uint2(pk2(a, b), pk2(c, d)); }
;   template <int NT, int MT> DI void run(f32x4 (&acc)[NT][MT], int mb, int nb) const {
;     ...
;         } else if (n < 3072) {
;           st_bf4(uvbuf + (size_t)m * 2048 + (n - 1024), gelu_f(v[0]), gelu_f(v[1]), gelu_f(v[2]), gelu_f(v[3]));
;         } else {
;           st_bf4(gatebuf + (size_t)m * 2048 + (n - 3072), silu_f(v[0]), silu_f(v[1]), silu_f(v[2]), silu_f(v[3]));
.LBB0_695:
	s_or_b64 exec, exec, s[46:47]
	s_and_saveexec_b64 s[6:7], s[40:41]
	s_xor_b64 s[46:47], exec, s[6:7]
	s_cbranch_execz .LBB0_717
	v_lshlrev_b64 v[26:27], 12, v[58:59]
	s_and_saveexec_b64 s[6:7], s[38:39]
	s_xor_b64 s[48:49], exec, s[6:7]
	s_cbranch_execz .LBB0_698
	v_mul_f32_e32 v28, 0xbfb8aa3b, v22
	v_mul_f32_e32 v29, 0xbfb8aa3b, v23
	v_exp_f32_e32 v28, v28
	v_exp_f32_e32 v29, v29
	v_readlane_b32 s6, v252, 35
	v_readlane_b32 s7, v252, 36
	v_add_f32_e32 v28, 1.0, v28
	v_add_f32_e32 v29, 1.0, v29
	v_rcp_f32_e32 v28, v28
	v_rcp_f32_e32 v29, v29
	v_lshl_add_u64 v[26:27], s[6:7], 0, v[26:27]
	v_lshl_add_u64 v[26:27], v[182:183], 1, v[26:27]
	v_pk_mul_f32 v[22:23], v[22:23], v[28:29]
	v_mul_f32_e32 v28, 0xbfb8aa3b, v24
	v_mul_f32_e32 v29, 0xbfb8aa3b, v25
	v_exp_f32_e32 v28, v28
	v_exp_f32_e32 v29, v29
	v_cvt_pk_bf16_f32 v22, v22, v23
	v_add_f32_e32 v28, 1.0, v28
	v_add_f32_e32 v29, 1.0, v29
	v_rcp_f32_e32 v28, v28
	v_rcp_f32_e32 v29, v29
	s_nop 0
	v_pk_mul_f32 v[24:25], v[24:25], v[28:29]
	s_nop 0
	v_cvt_pk_bf16_f32 v23, v24, v25
	v_add_co_u32_e32 v24, vcc, 0xfffff000, v26
	s_nop 1
	v_addc_co_u32_e32 v25, vcc, -1, v27, vcc
	v_mov_b32_e32 v244, v22
	v_mov_b32_e32 v245, v23
.LBB0_698:
	s_andn2_saveexec_b64 s[48:49], s[48:49]
	s_cbranch_execz .LBB0_716
	v_pk_mul_f32 v[130:131], v[22:23], v[170:171]
	v_pk_mul_f32 v[142:143], v[24:25], v[170:171]
	v_and_b32_e32 v132, 0x7fffffff, v130
	v_and_b32_e32 v144, 0x7fffffff, v142
	v_and_b32_e32 v133, 0x7fffffff, v131
	v_and_b32_e32 v145, 0x7fffffff, v143
	v_pk_fma_f32 v[134:135], v[132:133], v[174:175], v[176:177]
	v_pk_fma_f32 v[146:147], v[144:145], v[174:175], v[176:177]
	v_pk_fma_f32 v[134:135], v[132:133], v[134:135], v[178:179]
	v_pk_fma_f32 v[146:147], v[144:145], v[146:147], v[178:179]
	v_pk_fma_f32 v[134:135], v[132:133], v[134:135], v[180:181]
	v_pk_fma_f32 v[146:147], v[144:145], v[146:147], v[180:181]
	v_pk_fma_f32 v[134:135], v[132:133], v[134:135], v[186:187]
	v_pk_fma_f32 v[146:147], v[144:145], v[146:147], v[186:187]
	v_pk_fma_f32 v[134:135], v[132:133], v[134:135], v[188:189]
	v_pk_fma_f32 v[146:147], v[144:145], v[146:147], v[188:189]
	v_pk_fma_f32 v[134:135], v[132:133], v[134:135], v[190:191]
	v_pk_fma_f32 v[146:147], v[144:145], v[146:147], v[190:191]
	v_pk_fma_f32 v[134:135], v[132:133], v[134:135], v[132:133]
	v_pk_fma_f32 v[146:147], v[144:145], v[146:147], v[144:145]
	v_pk_mul_f32 v[134:135], v[134:135], v[172:173]
	v_pk_mul_f32 v[146:147], v[146:147], v[172:173]
	v_pk_mul_f32 v[136:137], v[130:131], v[130:131]
	v_pk_mul_f32 v[148:149], v[142:143], v[142:143]
	v_exp_f32_e32 v134, v134
	v_exp_f32_e32 v146, v146
	v_exp_f32_e32 v135, v135
	v_exp_f32_e32 v147, v147
	v_pk_fma_f32 v[138:139], v[136:137], v[192:193], v[194:195]
	v_pk_fma_f32 v[150:151], v[148:149], v[192:193], v[194:195]
	v_pk_fma_f32 v[138:139], v[136:137], v[138:139], v[196:197]
	v_pk_fma_f32 v[150:151], v[148:149], v[150:151], v[196:197]
	v_pk_fma_f32 v[138:139], v[136:137], v[138:139], v[224:225]
	v_pk_fma_f32 v[150:151], v[148:149], v[150:151], v[224:225]
	v_pk_fma_f32 v[138:139], v[136:137], v[138:139], v[226:227]
	v_pk_fma_f32 v[150:151], v[148:149], v[150:151], v[226:227]
	v_pk_fma_f32 v[138:139], v[136:137], v[138:139], v[228:229]
	v_pk_fma_f32 v[150:151], v[148:149], v[150:151], v[228:229]
	v_pk_fma_f32 v[134:135], v[134:135], v[234:235], v[230:231]
	v_pk_fma_f32 v[146:147], v[146:147], v[234:235], v[230:231]
	v_pk_fma_f32 v[138:139], v[132:133], v[138:139], v[132:133]
	v_pk_fma_f32 v[150:151], v[144:145], v[150:151], v[144:145]
	v_pk_mul_f32 v[140:141], v[22:23], v[232:233]
	v_pk_mul_f32 v[152:153], v[24:25], v[232:233]
	v_cmp_ngt_f32_e32 vcc, 1.0, v132
	v_cmp_ngt_f32_e64 s[8:9], 1.0, v133
	v_readlane_b32 s6, v252, 33
	v_readlane_b32 s7, v252, 34
	v_cndmask_b32_e32 v138, v138, v134, vcc
	v_cndmask_b32_e64 v139, v139, v135, s[8:9]
	v_cmp_ngt_f32_e32 vcc, 1.0, v144
	v_cmp_ngt_f32_e64 s[8:9], 1.0, v145
	v_bfi_b32 v138, s37, v138, v130
	v_bfi_b32 v139, s37, v139, v131
	v_cndmask_b32_e32 v150, v150, v146, vcc
	v_cndmask_b32_e64 v151, v151, v147, s[8:9]
	v_pk_add_f32 v[138:139], v[138:139], v[230:231]
	v_bfi_b32 v150, s37, v150, v142
	v_bfi_b32 v151, s37, v151, v143
	v_pk_add_f32 v[150:151], v[150:151], v[230:231]
	v_pk_mul_f32 v[138:139], v[140:141], v[138:139]
	v_lshl_add_u64 v[22:23], s[6:7], 0, v[26:27]
	v_pk_mul_f32 v[150:151], v[152:153], v[150:151]
	v_lshl_add_u64 v[22:23], v[182:183], 1, v[22:23]
	v_cvt_pk_bf16_f32 v24, v138, v139
	v_cvt_pk_bf16_f32 v25, v150, v151
	v_mov_b32_e32 v244, v24
	v_mov_b32_e32 v245, v25

; DI float gelu_f(float x) { return 0.5f * x * (1.f + erff(x * 0.70710678118654752f)); }
; DI float silu_f(float x) { return x * __builtin_amdgcn_rcpf(1.f + __expf(-x)); }
; DI void st_bf4(u16* p, float a, float b, float c, float d) { *(uint2*)p = make_uint2(pk2(a, b), pk2(c, d)); }
;   template <int NT, int MT> DI void run(f32x4 (&acc)[NT][MT], int mb, int nb) const {
;     ...
;         if (n < 1024) {
;           st_bf4(abuf + (size_t)m * 1024 + n, v[0], v[1], v[2], v[3]);
;           float* dst = nullptr;
;           if (m < M_PROMPT) { int t = m & 8191; if (t >= 8177) dst = spp + ((size_t)((m >> 13) * 15 + (t - 8177))) * 1024 + n; }
;           else { int r = m - M_PROMPT; int s = r & 31; if (s >= 17) dst = sps + ((size_t)((r >> 5) * 15 + (s - 17))) * 1024 + n; }
;           if (dst) *(float4*)dst = make_float4(v[0], v[1], v[2], v[3]);
;         } else if (n < 3072) {
;           st_bf4(uvbuf + (size_t)m * 2048 + (n - 1024), gelu_f(v[0]), gelu_f(v[1]), gelu_f(v[2]), gelu_f(v[3]));
;         } else {
;           st_bf4(gatebuf + (size_t)m * 2048 + (n - 3072), silu_f(v[0]), silu_f(v[1]), silu_f(v[2]), silu_f(v[3]));
.LBB0_717:
	s_andn2_saveexec_b64 s[46:47], s[46:47]
	s_cbranch_execz .LBB0_719
	v_lshlrev_b64 v[26:27], 11, v[58:59]
	v_lshl_add_u64 v[26:27], s[96:97], 0, v[26:27]
	v_lshl_add_u64 v[26:27], v[68:69], 1, v[26:27]
	v_cvt_pk_bf16_f32 v22, v22, v23
	v_cvt_pk_bf16_f32 v23, v24, v25
	v_mov_b32_e32 v244, v22
	v_mov_b32_e32 v245, v23
.LBB0_719:
	s_or_b64 exec, exec, s[46:47]
	s_and_saveexec_b64 s[6:7], s[40:41]
	s_xor_b64 s[40:41], exec, s[6:7]
	s_cbranch_execz .LBB0_741
	v_lshlrev_b64 v[22:23], 12, v[54:55]
	s_and_saveexec_b64 s[6:7], s[38:39]
	s_xor_b64 s[46:47], exec, s[6:7]
	s_cbranch_execz .LBB0_722
	v_mul_f32_e32 v24, 0xbfb8aa3b, v18
	v_mul_f32_e32 v25, 0xbfb8aa3b, v19
	v_exp_f32_e32 v24, v24
	v_exp_f32_e32 v25, v25
	v_readlane_b32 s6, v252, 35
	v_readlane_b32 s7, v252, 36
	v_add_f32_e32 v24, 1.0, v24
	v_add_f32_e32 v25, 1.0, v25
	v_rcp_f32_e32 v24, v24
	v_rcp_f32_e32 v25, v25
	v_lshl_add_u64 v[22:23], s[6:7], 0, v[22:23]
	v_lshl_add_u64 v[22:23], v[182:183], 1, v[22:23]
	v_pk_mul_f32 v[18:19], v[18:19], v[24:25]
	v_mul_f32_e32 v24, 0xbfb8aa3b, v20
	v_mul_f32_e32 v25, 0xbfb8aa3b, v21
	v_exp_f32_e32 v24, v24
	v_exp_f32_e32 v25, v25
	v_cvt_pk_bf16_f32 v18, v18, v19
	v_add_f32_e32 v24, 1.0, v24
	v_add_f32_e32 v25, 1.0, v25
	v_rcp_f32_e32 v24, v24
	v_rcp_f32_e32 v25, v25
	s_nop 0
	v_pk_mul_f32 v[20:21], v[20:21], v[24:25]
	s_nop 0
	v_cvt_pk_bf16_f32 v19, v20, v21
	v_add_co_u32_e32 v20, vcc, 0xfffff000, v22
	s_nop 1
	v_addc_co_u32_e32 v21, vcc, -1, v23, vcc
	v_mov_b32_e32 v248, v18
	v_mov_b32_e32 v249, v19
.LBB0_722:
	s_andn2_saveexec_b64 s[46:47], s[46:47]
	s_cbranch_execz .LBB0_740
	v_pk_mul_f32 v[130:131], v[18:19], v[170:171]
	v_pk_mul_f32 v[142:143], v[20:21], v[170:171]
	v_and_b32_e32 v132, 0x7fffffff, v130
	v_and_b32_e32 v144, 0x7fffffff, v142
	v_and_b32_e32 v133, 0x7fffffff, v131
	v_and_b32_e32 v145, 0x7fffffff, v143
	v_pk_fma_f32 v[134:135], v[132:133], v[174:175], v[176:177]
	v_pk_fma_f32 v[146:147], v[144:145], v[174:175], v[176:177]
	v_pk_fma_f32 v[134:135], v[132:133], v[134:135], v[178:179]
	v_pk_fma_f32 v[146:147], v[144:145], v[146:147], v[178:179]
	v_pk_fma_f32 v[134:135], v[132:133], v[134:135], v[180:181]
	v_pk_fma_f32 v[146:147], v[144:145], v[146:147], v[180:181]
	v_pk_fma_f32 v[134:135], v[132:133], v[134:135], v[186:187]
	v_pk_fma_f32 v[146:147], v[144:145], v[146:147], v[186:187]
	v_pk_fma_f32 v[134:135], v[132:133], v[134:135], v[188:189]
	v_pk_fma_f32 v[146:147], v[144:145], v[146:147], v[188:189]
	v_pk_fma_f32 v[134:135], v[132:133], v[134:135], v[190:191]
	v_pk_fma_f32 v[146:147], v[144:145], v[146:147], v[190:191]
	v_pk_fma_f32 v[134:135], v[132:133], v[134:135], v[132:133]
	v_pk_fma_f32 v[146:147], v[144:145], v[146:147], v[144:145]
	v_pk_mul_f32 v[134:135], v[134:135], v[172:173]
	v_pk_mul_f32 v[146:147], v[146:147], v[172:173]
	v_pk_mul_f32 v[136:137], v[130:131], v[130:131]
	v_pk_mul_f32 v[148:149], v[142:143], v[142:143]
	v_exp_f32_e32 v134, v134
	v_exp_f32_e32 v146, v146
	v_exp_f32_e32 v135, v135
	v_exp_f32_e32 v147, v147
	v_pk_fma_f32 v[138:139], v[136:137], v[192:193], v[194:195]
	v_pk_fma_f32 v[150:151], v[148:149], v[192:193], v[194:195]
	v_pk_fma_f32 v[138:139], v[136:137], v[138:139], v[196:197]
	v_pk_fma_f32 v[150:151], v[148:149], v[150:151], v[196:197]
	v_pk_fma_f32 v[138:139], v[136:137], v[138:139], v[224:225]
	v_pk_fma_f32 v[150:151], v[148:149], v[150:151], v[224:225]
	v_pk_fma_f32 v[138:139], v[136:137], v[138:139], v[226:227]
	v_pk_fma_f32 v[150:151], v[148:149], v[150:151], v[226:227]
	v_pk_fma_f32 v[138:139], v[136:137], v[138:139], v[228:229]
	v_pk_fma_f32 v[150:151], v[148:149], v[150:151], v[228:229]
	v_pk_fma_f32 v[134:135], v[134:135], v[234:235], v[230:231]
	v_pk_fma_f32 v[146:147], v[146:147], v[234:235], v[230:231]
	v_pk_fma_f32 v[138:139], v[132:133], v[138:139], v[132:133]
	v_pk_fma_f32 v[150:151], v[144:145], v[150:151], v[144:145]
	v_pk_mul_f32 v[140:141], v[18:19], v[232:233]
	v_pk_mul_f32 v[152:153], v[20:21], v[232:233]
	v_cmp_ngt_f32_e32 vcc, 1.0, v132
	v_cmp_ngt_f32_e64 s[8:9], 1.0, v133
	v_readlane_b32 s6, v252, 33
	v_readlane_b32 s7, v252, 34
	v_cndmask_b32_e32 v138, v138, v134, vcc
	v_cndmask_b32_e64 v139, v139, v135, s[8:9]
	v_cmp_ngt_f32_e32 vcc, 1.0, v144
	v_cmp_ngt_f32_e64 s[8:9], 1.0, v145
	v_bfi_b32 v138, s37, v138, v130
	v_bfi_b32 v139, s37, v139, v131
	v_cndmask_b32_e32 v150, v150, v146, vcc
	v_cndmask_b32_e64 v151, v151, v147, s[8:9]
	v_pk_add_f32 v[138:139], v[138:139], v[230:231]
	v_bfi_b32 v150, s37, v150, v142
	v_bfi_b32 v151, s37, v151, v143
	v_pk_add_f32 v[150:151], v[150:151], v[230:231]
	v_pk_mul_f32 v[138:139], v[140:141], v[138:139]
	v_lshl_add_u64 v[18:19], s[6:7], 0, v[22:23]
	v_pk_mul_f32 v[150:151], v[152:153], v[150:151]
	v_lshl_add_u64 v[18:19], v[182:183], 1, v[18:19]
	v_cvt_pk_bf16_f32 v20, v138, v139
	v_cvt_pk_bf16_f32 v21, v150, v151
	v_mov_b32_e32 v248, v20
	v_mov_b32_e32 v249, v21

; DI void st_bf4(u16* p, float a, float b, float c, float d) { *(uint2*)p = make_uint2(pk2(a, b), pk2(c, d)); }
;   template <int NT, int MT> DI void run(f32x4 (&acc)[NT][MT], int mb, int nb) const {
;     ...
;         if (n < 1024) {
;           st_bf4(abuf + (size_t)m * 1024 + n, v[0], v[1], v[2], v[3]);
;           float* dst = nullptr;
;           if (m < M_PROMPT) { int t = m & 8191; if (t >= 8177) dst = spp + ((size_t)((m >> 13) * 15 + (t - 8177))) * 1024 + n; }
;           else { int r = m - M_PROMPT; int s = r & 31; if (s >= 17) dst = sps + ((size_t)((r >> 5) * 15 + (s - 17))) * 1024 + n; }
;           if (dst) *(float4*)dst = make_float4(v[0], v[1], v[2], v[3]);
.LBB0_741:
	s_andn2_saveexec_b64 s[40:41], s[40:41]
	s_cbranch_execz .LBB0_749
	v_lshlrev_b64 v[22:23], 11, v[54:55]
	v_lshl_add_u64 v[22:23], s[96:97], 0, v[22:23]
	s_movk_i32 s5, 0x3fcf
	v_lshl_add_u64 v[22:23], v[68:69], 1, v[22:23]
	v_cvt_pk_bf16_f32 v24, v18, v19
	v_cvt_pk_bf16_f32 v25, v20, v21
	v_cmp_lt_i32_e32 vcc, s5, v66
	v_mov_b32_e32 v248, v24
	v_mov_b32_e32 v249, v25
	s_and_saveexec_b64 s[6:7], vcc
	s_xor_b64 s[46:47], exec, s[6:7]
	s_cbranch_execz .LBB0_863
	v_and_b32_e32 v24, 31, v54
	v_cmp_ne_u32_e32 vcc, 16, v24
	v_mov_b64_e32 v[22:23], 0
	s_and_saveexec_b64 s[48:49], vcc
	s_cbranch_execz .LBB0_745
	v_add_u32_e32 v22, 0xffffc030, v1
	v_lshrrev_b32_e32 v22, 5, v22
	v_mul_lo_u32 v22, v22, 15
	s_movk_i32 s5, 0xffef
	v_add3_u32 v22, v24, v22, s5
	v_mov_b32_e32 v23, v183
	v_readlane_b32 s6, v252, 57
	v_lshlrev_b64 v[22:23], 12, v[22:23]
	v_readlane_b32 s7, v252, 58
	s_nop 1
	v_lshl_add_u64 v[22:23], s[6:7], 0, v[22:23]
	v_lshl_add_u64 v[22:23], v[68:69], 2, v[22:23]
	v_lshl_add_u64 v[22:23], v[22:23], 0, s[28:29]

; DI unsigned pk2(float a, float b) { f32x2_t f = {a, b}; return __builtin_bit_cast(unsigned, __builtin_convertvector(f, bf16x2_t)); }
; DI float gelu_f(float x) { return 0.5f * x * (1.f + erff(x * 0.70710678118654752f)); }
; DI float silu_f(float x) { return x * __builtin_amdgcn_rcpf(1.f + __expf(-x)); }
; DI void st_bf4(u16* p, float a, float b, float c, float d) { *(uint2*)p = make_uint2(pk2(a, b), pk2(c, d)); }
;   template <int NT, int MT> DI void run(f32x4 (&acc)[NT][MT], int mb, int nb) const {
;     ...
;         } else if (n < 3072) {
;           st_bf4(uvbuf + (size_t)m * 2048 + (n - 1024), gelu_f(v[0]), gelu_f(v[1]), gelu_f(v[2]), gelu_f(v[3]));
;         } else {
;           st_bf4(gatebuf + (size_t)m * 2048 + (n - 3072), silu_f(v[0]), silu_f(v[1]), silu_f(v[2]), silu_f(v[3]));
.LBB0_749:
	s_or_b64 exec, exec, s[40:41]
	s_movk_i32 s5, 0x3cf
	v_cmp_lt_i32_e64 s[40:41], s5, v182
	s_and_saveexec_b64 s[6:7], s[40:41]
	s_xor_b64 s[46:47], exec, s[6:7]
	s_cbranch_execz .LBB0_771
	v_lshlrev_b64 v[18:19], 12, v[66:67]
	s_and_saveexec_b64 s[6:7], s[38:39]
	s_xor_b64 s[48:49], exec, s[6:7]
	s_cbranch_execz .LBB0_752
	v_mul_f32_e32 v20, 0xbfb8aa3b, v14
	v_mul_f32_e32 v21, 0xbfb8aa3b, v15
	v_exp_f32_e32 v20, v20
	v_exp_f32_e32 v21, v21
	v_readlane_b32 s6, v252, 35
	v_readlane_b32 s7, v252, 36
	v_add_f32_e32 v20, 1.0, v20
	v_add_f32_e32 v21, 1.0, v21
	v_rcp_f32_e32 v20, v20
	v_rcp_f32_e32 v21, v21
	v_lshl_add_u64 v[18:19], s[6:7], 0, v[18:19]
	v_lshl_add_u64 v[18:19], v[182:183], 1, v[18:19]
	v_pk_mul_f32 v[14:15], v[14:15], v[20:21]
	v_mul_f32_e32 v20, 0xbfb8aa3b, v16
	v_mul_f32_e32 v21, 0xbfb8aa3b, v17
	v_exp_f32_e32 v20, v20
	v_exp_f32_e32 v21, v21
	v_cvt_pk_bf16_f32 v14, v14, v15
	v_add_f32_e32 v20, 1.0, v20
	v_add_f32_e32 v21, 1.0, v21
	v_rcp_f32_e32 v20, v20
	v_rcp_f32_e32 v21, v21
	s_nop 0
	v_pk_mul_f32 v[16:17], v[16:17], v[20:21]
	s_nop 0
	v_cvt_pk_bf16_f32 v15, v16, v17
	v_add_co_u32_e32 v16, vcc, 0xfffff000, v18
	s_nop 1
	v_addc_co_u32_e32 v17, vcc, -1, v19, vcc
	v_mov_b32_e32 v238, v14
	v_mov_b32_e32 v239, v15
	v_lshl_add_u64 v[156:157], v[16:17], 0, v[154:155]
	s_nop 0
	v_permlane16_swap_b32_e32 v236, v238
	v_permlane16_swap_b32_e32 v237, v239
	global_store_dwordx4 v[156:157], v[236:239], off offset:-1984
.LBB0_752:
	s_andn2_saveexec_b64 s[48:49], s[48:49]
	s_cbranch_execz .LBB0_770
	v_pk_mul_f32 v[130:131], v[14:15], v[170:171]
	v_pk_mul_f32 v[142:143], v[16:17], v[170:171]
	v_and_b32_e32 v132, 0x7fffffff, v130
	v_and_b32_e32 v144, 0x7fffffff, v142
	v_and_b32_e32 v133, 0x7fffffff, v131
	v_and_b32_e32 v145, 0x7fffffff, v143
	v_pk_fma_f32 v[134:135], v[132:133], v[174:175], v[176:177]
	v_pk_fma_f32 v[146:147], v[144:145], v[174:175], v[176:177]
	v_pk_fma_f32 v[134:135], v[132:133], v[134:135], v[178:179]
	v_pk_fma_f32 v[146:147], v[144:145], v[146:147], v[178:179]
	v_pk_fma_f32 v[134:135], v[132:133], v[134:135], v[180:181]
	v_pk_fma_f32 v[146:147], v[144:145], v[146:147], v[180:181]
	v_pk_fma_f32 v[134:135], v[132:133], v[134:135], v[186:187]
	v_pk_fma_f32 v[146:147], v[144:145], v[146:147], v[186:187]
	v_pk_fma_f32 v[134:135], v[132:133], v[134:135], v[188:189]
	v_pk_fma_f32 v[146:147], v[144:145], v[146:147], v[188:189]
	v_pk_fma_f32 v[134:135], v[132:133], v[134:135], v[190:191]
	v_pk_fma_f32 v[146:147], v[144:145], v[146:147], v[190:191]
	v_pk_fma_f32 v[134:135], v[132:133], v[134:135], v[132:133]
	v_pk_fma_f32 v[146:147], v[144:145], v[146:147], v[144:145]
	v_pk_mul_f32 v[134:135], v[134:135], v[172:173]
	v_pk_mul_f32 v[146:147], v[146:147], v[172:173]
	v_pk_mul_f32 v[136:137], v[130:131], v[130:131]
	v_pk_mul_f32 v[148:149], v[142:143], v[142:143]
	v_exp_f32_e32 v134, v134
	v_exp_f32_e32 v146, v146
	v_exp_f32_e32 v135, v135
	v_exp_f32_e32 v147, v147
	v_pk_fma_f32 v[138:139], v[136:137], v[192:193], v[194:195]
	v_pk_fma_f32 v[150:151], v[148:149], v[192:193], v[194:195]
	v_pk_fma_f32 v[138:139], v[136:137], v[138:139], v[196:197]
	v_pk_fma_f32 v[150:151], v[148:149], v[150:151], v[196:197]
	v_pk_fma_f32 v[138:139], v[136:137], v[138:139], v[224:225]
	v_pk_fma_f32 v[150:151], v[148:149], v[150:151], v[224:225]
	v_pk_fma_f32 v[138:139], v[136:137], v[138:139], v[226:227]
	v_pk_fma_f32 v[150:151], v[148:149], v[150:151], v[226:227]
	v_pk_fma_f32 v[138:139], v[136:137], v[138:139], v[228:229]
	v_pk_fma_f32 v[150:151], v[148:149], v[150:151], v[228:229]
	v_pk_fma_f32 v[134:135], v[134:135], v[234:235], v[230:231]
	v_pk_fma_f32 v[146:147], v[146:147], v[234:235], v[230:231]
	v_pk_fma_f32 v[138:139], v[132:133], v[138:139], v[132:133]
	v_pk_fma_f32 v[150:151], v[144:145], v[150:151], v[144:145]
	v_pk_mul_f32 v[140:141], v[14:15], v[232:233]
	v_pk_mul_f32 v[152:153], v[16:17], v[232:233]
	v_cmp_ngt_f32_e32 vcc, 1.0, v132
	v_cmp_ngt_f32_e64 s[8:9], 1.0, v133
	v_readlane_b32 s6, v252, 33
	v_readlane_b32 s7, v252, 34
	v_cndmask_b32_e32 v138, v138, v134, vcc
	v_cndmask_b32_e64 v139, v139, v135, s[8:9]
	v_cmp_ngt_f32_e32 vcc, 1.0, v144
	v_cmp_ngt_f32_e64 s[8:9], 1.0, v145
	v_bfi_b32 v138, s37, v138, v130
	v_bfi_b32 v139, s37, v139, v131
	v_cndmask_b32_e32 v150, v150, v146, vcc
	v_cndmask_b32_e64 v151, v151, v147, s[8:9]
	v_pk_add_f32 v[138:139], v[138:139], v[230:231]
	v_bfi_b32 v150, s37, v150, v142
	v_bfi_b32 v151, s37, v151, v143
	v_pk_add_f32 v[150:151], v[150:151], v[230:231]
	v_pk_mul_f32 v[138:139], v[140:141], v[138:139]
	v_lshl_add_u64 v[14:15], s[6:7], 0, v[18:19]
	v_pk_mul_f32 v[150:151], v[152:153], v[150:151]
	v_lshl_add_u64 v[14:15], v[182:183], 1, v[14:15]
	v_cvt_pk_bf16_f32 v16, v138, v139
	v_cvt_pk_bf16_f32 v17, v150, v151
	v_mov_b32_e32 v238, v16
	v_mov_b32_e32 v239, v17
	v_lshl_add_u64 v[156:157], v[14:15], 0, v[154:155]
	s_nop 0
	v_permlane16_swap_b32_e32 v236, v238
	v_permlane16_swap_b32_e32 v237, v239
	global_store_dwordx4 v[156:157], v[236:239], off offset:-1984

; DI float gelu_f(float x) { return 0.5f * x * (1.f + erff(x * 0.70710678118654752f)); }
; DI float silu_f(float x) { return x * __builtin_amdgcn_rcpf(1.f + __expf(-x)); }
; DI void st_bf4(u16* p, float a, float b, float c, float d) { *(uint2*)p = make_uint2(pk2(a, b), pk2(c, d)); }
;   template <int NT, int MT> DI void run(f32x4 (&acc)[NT][MT], int mb, int nb) const {
;     ...
;         if (n < 1024) {
;           st_bf4(abuf + (size_t)m * 1024 + n, v[0], v[1], v[2], v[3]);
;           float* dst = nullptr;
;           if (m < M_PROMPT) { int t = m & 8191; if (t >= 8177) dst = spp + ((size_t)((m >> 13) * 15 + (t - 8177))) * 1024 + n; }
;           else { int r = m - M_PROMPT; int s = r & 31; if (s >= 17) dst = sps + ((size_t)((r >> 5) * 15 + (s - 17))) * 1024 + n; }
;           if (dst) *(float4*)dst = make_float4(v[0], v[1], v[2], v[3]);
;         } else if (n < 3072) {
;           st_bf4(uvbuf + (size_t)m * 2048 + (n - 1024), gelu_f(v[0]), gelu_f(v[1]), gelu_f(v[2]), gelu_f(v[3]));
;         } else {
;           st_bf4(gatebuf + (size_t)m * 2048 + (n - 3072), silu_f(v[0]), silu_f(v[1]), silu_f(v[2]), silu_f(v[3]));
.LBB0_771:
	s_andn2_saveexec_b64 s[46:47], s[46:47]
	s_cbranch_execz .LBB0_773
	v_lshlrev_b64 v[18:19], 11, v[66:67]
	v_lshl_add_u64 v[18:19], s[96:97], 0, v[18:19]
	v_lshl_add_u64 v[18:19], v[68:69], 1, v[18:19]
	v_cvt_pk_bf16_f32 v14, v14, v15
	v_cvt_pk_bf16_f32 v15, v16, v17
	v_mov_b32_e32 v238, v14
	v_mov_b32_e32 v239, v15
	v_lshl_add_u64 v[156:157], v[18:19], 0, v[154:155]
	s_nop 0
	v_permlane16_swap_b32_e32 v236, v238
	v_permlane16_swap_b32_e32 v237, v239
	global_store_dwordx4 v[156:157], v[236:239], off offset:64
.LBB0_773:
	s_or_b64 exec, exec, s[46:47]
	s_and_saveexec_b64 s[6:7], s[40:41]
	s_xor_b64 s[46:47], exec, s[6:7]
	s_cbranch_execz .LBB0_795
	v_lshlrev_b64 v[14:15], 12, v[62:63]
	s_and_saveexec_b64 s[6:7], s[38:39]
	s_xor_b64 s[48:49], exec, s[6:7]
	s_cbranch_execz .LBB0_776
	v_mul_f32_e32 v16, 0xbfb8aa3b, v10
	v_mul_f32_e32 v17, 0xbfb8aa3b, v11
	v_exp_f32_e32 v16, v16
	v_exp_f32_e32 v17, v17
	v_readlane_b32 s6, v252, 35
	v_readlane_b32 s7, v252, 36
	v_add_f32_e32 v16, 1.0, v16
	v_add_f32_e32 v17, 1.0, v17
	v_rcp_f32_e32 v16, v16
	v_rcp_f32_e32 v17, v17
	v_lshl_add_u64 v[14:15], s[6:7], 0, v[14:15]
	v_lshl_add_u64 v[14:15], v[182:183], 1, v[14:15]
	v_pk_mul_f32 v[10:11], v[10:11], v[16:17]
	v_mul_f32_e32 v16, 0xbfb8aa3b, v12
	v_mul_f32_e32 v17, 0xbfb8aa3b, v13
	v_exp_f32_e32 v16, v16
	v_exp_f32_e32 v17, v17
	v_cvt_pk_bf16_f32 v10, v10, v11
	v_add_f32_e32 v16, 1.0, v16
	v_add_f32_e32 v17, 1.0, v17
	v_rcp_f32_e32 v16, v16
	v_rcp_f32_e32 v17, v17
	s_nop 0
	v_pk_mul_f32 v[12:13], v[12:13], v[16:17]
	s_nop 0
	v_cvt_pk_bf16_f32 v11, v12, v13
	v_add_co_u32_e32 v12, vcc, 0xfffff000, v14
	s_nop 1
	v_addc_co_u32_e32 v13, vcc, -1, v15, vcc
	v_mov_b32_e32 v242, v10
	v_mov_b32_e32 v243, v11
	v_lshl_add_u64 v[156:157], v[12:13], 0, v[154:155]
	s_nop 0
	v_permlane16_swap_b32_e32 v240, v242
	v_permlane16_swap_b32_e32 v241, v243
	global_store_dwordx4 v[156:157], v[240:243], off offset:-1984
.LBB0_776:
	s_andn2_saveexec_b64 s[48:49], s[48:49]
	s_cbranch_execz .LBB0_794
	v_pk_mul_f32 v[130:131], v[10:11], v[170:171]
	v_pk_mul_f32 v[142:143], v[12:13], v[170:171]
	v_and_b32_e32 v132, 0x7fffffff, v130
	v_and_b32_e32 v144, 0x7fffffff, v142
	v_and_b32_e32 v133, 0x7fffffff, v131
	v_and_b32_e32 v145, 0x7fffffff, v143
	v_pk_fma_f32 v[134:135], v[132:133], v[174:175], v[176:177]
	v_pk_fma_f32 v[146:147], v[144:145], v[174:175], v[176:177]
	v_pk_fma_f32 v[134:135], v[132:133], v[134:135], v[178:179]
	v_pk_fma_f32 v[146:147], v[144:145], v[146:147], v[178:179]
	v_pk_fma_f32 v[134:135], v[132:133], v[134:135], v[180:181]
	v_pk_fma_f32 v[146:147], v[144:145], v[146:147], v[180:181]
	v_pk_fma_f32 v[134:135], v[132:133], v[134:135], v[186:187]
	v_pk_fma_f32 v[146:147], v[144:145], v[146:147], v[186:187]
	v_pk_fma_f32 v[134:135], v[132:133], v[134:135], v[188:189]
	v_pk_fma_f32 v[146:147], v[144:145], v[146:147], v[188:189]
	v_pk_fma_f32 v[134:135], v[132:133], v[134:135], v[190:191]
	v_pk_fma_f32 v[146:147], v[144:145], v[146:147], v[190:191]
	v_pk_fma_f32 v[134:135], v[132:133], v[134:135], v[132:133]
	v_pk_fma_f32 v[146:147], v[144:145], v[146:147], v[144:145]
	v_pk_mul_f32 v[134:135], v[134:135], v[172:173]
	v_pk_mul_f32 v[146:147], v[146:147], v[172:173]
	v_pk_mul_f32 v[136:137], v[130:131], v[130:131]
	v_pk_mul_f32 v[148:149], v[142:143], v[142:143]
	v_exp_f32_e32 v134, v134
	v_exp_f32_e32 v146, v146
	v_exp_f32_e32 v135, v135
	v_exp_f32_e32 v147, v147
	v_pk_fma_f32 v[138:139], v[136:137], v[192:193], v[194:195]
	v_pk_fma_f32 v[150:151], v[148:149], v[192:193], v[194:195]
	v_pk_fma_f32 v[138:139], v[136:137], v[138:139], v[196:197]
	v_pk_fma_f32 v[150:151], v[148:149], v[150:151], v[196:197]
	v_pk_fma_f32 v[138:139], v[136:137], v[138:139], v[224:225]
	v_pk_fma_f32 v[150:151], v[148:149], v[150:151], v[224:225]
	v_pk_fma_f32 v[138:139], v[136:137], v[138:139], v[226:227]
	v_pk_fma_f32 v[150:151], v[148:149], v[150:151], v[226:227]
	v_pk_fma_f32 v[138:139], v[136:137], v[138:139], v[228:229]
	v_pk_fma_f32 v[150:151], v[148:149], v[150:151], v[228:229]
	v_pk_fma_f32 v[134:135], v[134:135], v[234:235], v[230:231]
	v_pk_fma_f32 v[146:147], v[146:147], v[234:235], v[230:231]
	v_pk_fma_f32 v[138:139], v[132:133], v[138:139], v[132:133]
	v_pk_fma_f32 v[150:151], v[144:145], v[150:151], v[144:145]
	v_pk_mul_f32 v[140:141], v[10:11], v[232:233]
	v_pk_mul_f32 v[152:153], v[12:13], v[232:233]
	v_cmp_ngt_f32_e32 vcc, 1.0, v132
	v_cmp_ngt_f32_e64 s[8:9], 1.0, v133
	v_readlane_b32 s6, v252, 33
	v_readlane_b32 s7, v252, 34
	v_cndmask_b32_e32 v138, v138, v134, vcc
	v_cndmask_b32_e64 v139, v139, v135, s[8:9]
	v_cmp_ngt_f32_e32 vcc, 1.0, v144
	v_cmp_ngt_f32_e64 s[8:9], 1.0, v145
	v_bfi_b32 v138, s37, v138, v130
	v_bfi_b32 v139, s37, v139, v131
	v_cndmask_b32_e32 v150, v150, v146, vcc
	v_cndmask_b32_e64 v151, v151, v147, s[8:9]
	v_pk_add_f32 v[138:139], v[138:139], v[230:231]
	v_bfi_b32 v150, s37, v150, v142
	v_bfi_b32 v151, s37, v151, v143
	v_pk_add_f32 v[150:151], v[150:151], v[230:231]
	v_pk_mul_f32 v[138:139], v[140:141], v[138:139]
	v_lshl_add_u64 v[10:11], s[6:7], 0, v[14:15]
	v_pk_mul_f32 v[150:151], v[152:153], v[150:151]
	v_lshl_add_u64 v[10:11], v[182:183], 1, v[10:11]
	v_cvt_pk_bf16_f32 v12, v138, v139
	v_cvt_pk_bf16_f32 v13, v150, v151
	v_mov_b32_e32 v242, v12
	v_mov_b32_e32 v243, v13
	v_lshl_add_u64 v[156:157], v[10:11], 0, v[154:155]
	s_nop 0
	v_permlane16_swap_b32_e32 v240, v242
	v_permlane16_swap_b32_e32 v241, v243
	global_store_dwordx4 v[156:157], v[240:243], off offset:-1984

; DI void st_bf4(u16* p, float a, float b, float c, float d) { *(uint2*)p = make_uint2(pk2(a, b), pk2(c, d)); }
;   template <int NT, int MT> DI void run(f32x4 (&acc)[NT][MT], int mb, int nb) const {
;     ...
;         if (n < 1024) {
;           st_bf4(abuf + (size_t)m * 1024 + n, v[0], v[1], v[2], v[3]);
;           float* dst = nullptr;
;           if (m < M_PROMPT) { int t = m & 8191; if (t >= 8177) dst = spp + ((size_t)((m >> 13) * 15 + (t - 8177))) * 1024 + n; }
;           else { int r = m - M_PROMPT; int s = r & 31; if (s >= 17) dst = sps + ((size_t)((r >> 5) * 15 + (s - 17))) * 1024 + n; }
;           if (dst) *(float4*)dst = make_float4(v[0], v[1], v[2], v[3]);
.LBB0_795:
	s_andn2_saveexec_b64 s[46:47], s[46:47]
	s_cbranch_execz .LBB0_803
	v_lshlrev_b64 v[14:15], 11, v[62:63]
	v_lshl_add_u64 v[14:15], s[96:97], 0, v[14:15]
	v_lshl_add_u64 v[14:15], v[68:69], 1, v[14:15]
	v_cvt_pk_bf16_f32 v16, v10, v11
	v_cvt_pk_bf16_f32 v17, v12, v13
	s_movk_i32 s5, 0x3fef
	v_mov_b32_e32 v242, v16
	v_mov_b32_e32 v243, v17
	v_lshl_add_u64 v[156:157], v[14:15], 0, v[154:155]
	s_nop 0
	v_permlane16_swap_b32_e32 v240, v242
	v_permlane16_swap_b32_e32 v241, v243
	global_store_dwordx4 v[156:157], v[240:243], off offset:64
	v_cmp_lt_i32_e32 vcc, s5, v66
	v_mov_b64_e32 v[14:15], 0
	s_and_saveexec_b64 s[48:49], vcc
	s_cbranch_execz .LBB0_800
	v_and_b32_e32 v16, 31, v62
	v_cmp_ne_u32_e32 vcc, 16, v16
	v_mov_b64_e32 v[14:15], 0
	s_and_saveexec_b64 s[50:51], vcc
	s_cbranch_execz .LBB0_799
	v_add_u32_e32 v14, 0xffffc010, v1
	v_lshrrev_b32_e32 v14, 5, v14
	v_mul_lo_u32 v14, v14, 15
	s_movk_i32 s5, 0xffef
	v_add3_u32 v14, v16, v14, s5
	v_mov_b32_e32 v15, v183
	v_readlane_b32 s6, v252, 57
	v_lshlrev_b64 v[14:15], 12, v[14:15]
	v_readlane_b32 s7, v252, 58
	s_nop 1
	v_lshl_add_u64 v[14:15], s[6:7], 0, v[14:15]
	v_lshl_add_u64 v[14:15], v[68:69], 2, v[14:15]
	s_mov_b64 s[6:7], 0xc0
	v_lshl_add_u64 v[14:15], v[14:15], 0, s[6:7]

; DI unsigned pk2(float a, float b) { f32x2_t f = {a, b}; return __builtin_bit_cast(unsigned, __builtin_convertvector(f, bf16x2_t)); }
; DI float gelu_f(float x) { return 0.5f * x * (1.f + erff(x * 0.70710678118654752f)); }
; DI float silu_f(float x) { return x * __builtin_amdgcn_rcpf(1.f + __expf(-x)); }
; DI void st_bf4(u16* p, float a, float b, float c, float d) { *(uint2*)p = make_uint2(pk2(a, b), pk2(c, d)); }
;   template <int NT, int MT> DI void run(f32x4 (&acc)[NT][MT], int mb, int nb) const {
;     ...
;         } else if (n < 3072) {
;           st_bf4(uvbuf + (size_t)m * 2048 + (n - 1024), gelu_f(v[0]), gelu_f(v[1]), gelu_f(v[2]), gelu_f(v[3]));
;         } else {
;           st_bf4(gatebuf + (size_t)m * 2048 + (n - 3072), silu_f(v[0]), silu_f(v[1]), silu_f(v[2]), silu_f(v[3]));
.LBB0_803:
	s_or_b64 exec, exec, s[46:47]
	s_and_saveexec_b64 s[6:7], s[40:41]
	s_xor_b64 s[46:47], exec, s[6:7]
	s_cbranch_execz .LBB0_825
	v_lshlrev_b64 v[10:11], 12, v[58:59]
	s_and_saveexec_b64 s[6:7], s[38:39]
	s_xor_b64 s[48:49], exec, s[6:7]
	s_cbranch_execz .LBB0_806
	v_mul_f32_e32 v12, 0xbfb8aa3b, v6
	v_mul_f32_e32 v13, 0xbfb8aa3b, v7
	v_exp_f32_e32 v12, v12
	v_exp_f32_e32 v13, v13
	v_readlane_b32 s6, v252, 35
	v_readlane_b32 s7, v252, 36
	v_add_f32_e32 v12, 1.0, v12
	v_add_f32_e32 v13, 1.0, v13
	v_rcp_f32_e32 v12, v12
	v_rcp_f32_e32 v13, v13
	v_lshl_add_u64 v[10:11], s[6:7], 0, v[10:11]
	v_lshl_add_u64 v[10:11], v[182:183], 1, v[10:11]
	v_pk_mul_f32 v[6:7], v[6:7], v[12:13]
	v_mul_f32_e32 v12, 0xbfb8aa3b, v8
	v_mul_f32_e32 v13, 0xbfb8aa3b, v9
	v_exp_f32_e32 v12, v12
	v_exp_f32_e32 v13, v13
	v_cvt_pk_bf16_f32 v6, v6, v7
	v_add_f32_e32 v12, 1.0, v12
	v_add_f32_e32 v13, 1.0, v13
	v_rcp_f32_e32 v12, v12
	v_rcp_f32_e32 v13, v13
	s_nop 0
	v_pk_mul_f32 v[8:9], v[8:9], v[12:13]
	s_nop 0
	v_cvt_pk_bf16_f32 v7, v8, v9
	v_add_co_u32_e32 v8, vcc, 0xfffff000, v10
	s_nop 1
	v_addc_co_u32_e32 v9, vcc, -1, v11, vcc
	v_mov_b32_e32 v246, v6
	v_mov_b32_e32 v247, v7
	v_lshl_add_u64 v[156:157], v[8:9], 0, v[154:155]
	s_nop 0
	v_permlane16_swap_b32_e32 v244, v246
	v_permlane16_swap_b32_e32 v245, v247
	global_store_dwordx4 v[156:157], v[244:247], off offset:-1984
.LBB0_806:
	s_andn2_saveexec_b64 s[48:49], s[48:49]
	s_cbranch_execz .LBB0_824
	v_pk_mul_f32 v[130:131], v[6:7], v[170:171]
	v_pk_mul_f32 v[142:143], v[8:9], v[170:171]
	v_and_b32_e32 v132, 0x7fffffff, v130
	v_and_b32_e32 v144, 0x7fffffff, v142
	v_and_b32_e32 v133, 0x7fffffff, v131
	v_and_b32_e32 v145, 0x7fffffff, v143
	v_pk_fma_f32 v[134:135], v[132:133], v[174:175], v[176:177]
	v_pk_fma_f32 v[146:147], v[144:145], v[174:175], v[176:177]
	v_pk_fma_f32 v[134:135], v[132:133], v[134:135], v[178:179]
	v_pk_fma_f32 v[146:147], v[144:145], v[146:147], v[178:179]
	v_pk_fma_f32 v[134:135], v[132:133], v[134:135], v[180:181]
	v_pk_fma_f32 v[146:147], v[144:145], v[146:147], v[180:181]
	v_pk_fma_f32 v[134:135], v[132:133], v[134:135], v[186:187]
	v_pk_fma_f32 v[146:147], v[144:145], v[146:147], v[186:187]
	v_pk_fma_f32 v[134:135], v[132:133], v[134:135], v[188:189]
	v_pk_fma_f32 v[146:147], v[144:145], v[146:147], v[188:189]
	v_pk_fma_f32 v[134:135], v[132:133], v[134:135], v[190:191]
	v_pk_fma_f32 v[146:147], v[144:145], v[146:147], v[190:191]
	v_pk_fma_f32 v[134:135], v[132:133], v[134:135], v[132:133]
	v_pk_fma_f32 v[146:147], v[144:145], v[146:147], v[144:145]
	v_pk_mul_f32 v[134:135], v[134:135], v[172:173]
	v_pk_mul_f32 v[146:147], v[146:147], v[172:173]
	v_pk_mul_f32 v[136:137], v[130:131], v[130:131]
	v_pk_mul_f32 v[148:149], v[142:143], v[142:143]
	v_exp_f32_e32 v134, v134
	v_exp_f32_e32 v146, v146
	v_exp_f32_e32 v135, v135
	v_exp_f32_e32 v147, v147
	v_pk_fma_f32 v[138:139], v[136:137], v[192:193], v[194:195]
	v_pk_fma_f32 v[150:151], v[148:149], v[192:193], v[194:195]
	v_pk_fma_f32 v[138:139], v[136:137], v[138:139], v[196:197]
	v_pk_fma_f32 v[150:151], v[148:149], v[150:151], v[196:197]
	v_pk_fma_f32 v[138:139], v[136:137], v[138:139], v[224:225]
	v_pk_fma_f32 v[150:151], v[148:149], v[150:151], v[224:225]
	v_pk_fma_f32 v[138:139], v[136:137], v[138:139], v[226:227]
	v_pk_fma_f32 v[150:151], v[148:149], v[150:151], v[226:227]
	v_pk_fma_f32 v[138:139], v[136:137], v[138:139], v[228:229]
	v_pk_fma_f32 v[150:151], v[148:149], v[150:151], v[228:229]
	v_pk_fma_f32 v[134:135], v[134:135], v[234:235], v[230:231]
	v_pk_fma_f32 v[146:147], v[146:147], v[234:235], v[230:231]
	v_pk_fma_f32 v[138:139], v[132:133], v[138:139], v[132:133]
	v_pk_fma_f32 v[150:151], v[144:145], v[150:151], v[144:145]
	v_pk_mul_f32 v[140:141], v[6:7], v[232:233]
	v_pk_mul_f32 v[152:153], v[8:9], v[232:233]
	v_cmp_ngt_f32_e32 vcc, 1.0, v132
	v_cmp_ngt_f32_e64 s[8:9], 1.0, v133
	v_readlane_b32 s6, v252, 33
	v_readlane_b32 s7, v252, 34
	v_cndmask_b32_e32 v138, v138, v134, vcc
	v_cndmask_b32_e64 v139, v139, v135, s[8:9]
	v_cmp_ngt_f32_e32 vcc, 1.0, v144
	v_cmp_ngt_f32_e64 s[8:9], 1.0, v145
	v_bfi_b32 v138, s37, v138, v130
	v_bfi_b32 v139, s37, v139, v131
	v_cndmask_b32_e32 v150, v150, v146, vcc
	v_cndmask_b32_e64 v151, v151, v147, s[8:9]
	v_pk_add_f32 v[138:139], v[138:139], v[230:231]
	v_bfi_b32 v150, s37, v150, v142
	v_bfi_b32 v151, s37, v151, v143
	v_pk_add_f32 v[150:151], v[150:151], v[230:231]
	v_pk_mul_f32 v[138:139], v[140:141], v[138:139]
	v_lshl_add_u64 v[6:7], s[6:7], 0, v[10:11]
	v_pk_mul_f32 v[150:151], v[152:153], v[150:151]
	v_lshl_add_u64 v[6:7], v[182:183], 1, v[6:7]
	v_cvt_pk_bf16_f32 v8, v138, v139
	v_cvt_pk_bf16_f32 v9, v150, v151
	v_mov_b32_e32 v246, v8
	v_mov_b32_e32 v247, v9
	v_lshl_add_u64 v[156:157], v[6:7], 0, v[154:155]
	s_nop 0
	v_permlane16_swap_b32_e32 v244, v246
	v_permlane16_swap_b32_e32 v245, v247
	global_store_dwordx4 v[156:157], v[244:247], off offset:-1984

; DI void st_bf4(u16* p, float a, float b, float c, float d) { *(uint2*)p = make_uint2(pk2(a, b), pk2(c, d)); }
; DI float gelu_f(float x) { return 0.5f * x * (1.f + erff(x * 0.70710678118654752f)); }
; DI float silu_f(float x) { return x * __builtin_amdgcn_rcpf(1.f + __expf(-x)); }
;   template <int NT, int MT> DI void run(f32x4 (&acc)[NT][MT], int mb, int nb) const {
;     ...
;         f32x4 v = acc[nt][mt];
;         if (n < 1024) {
;           st_bf4(abuf + (size_t)m * 1024 + n, v[0], v[1], v[2], v[3]);
;           float* dst = nullptr;
;           if (m < M_PROMPT) { int t = m & 8191; if (t >= 8177) dst = spp + ((size_t)((m >> 13) * 15 + (t - 8177))) * 1024 + n; }
;           else { int r = m - M_PROMPT; int s = r & 31; if (s >= 17) dst = sps + ((size_t)((r >> 5) * 15 + (s - 17))) * 1024 + n; }
;           if (dst) *(float4*)dst = make_float4(v[0], v[1], v[2], v[3]);
;         } else if (n < 3072) {
;           st_bf4(uvbuf + (size_t)m * 2048 + (n - 1024), gelu_f(v[0]), gelu_f(v[1]), gelu_f(v[2]), gelu_f(v[3]));
;         } else {
;           st_bf4(gatebuf + (size_t)m * 2048 + (n - 3072), silu_f(v[0]), silu_f(v[1]), silu_f(v[2]), silu_f(v[3]));
;         }
.LBB0_825:
	s_andn2_saveexec_b64 s[46:47], s[46:47]
	s_cbranch_execz .LBB0_827
	v_lshlrev_b64 v[10:11], 11, v[58:59]
	v_lshl_add_u64 v[10:11], s[96:97], 0, v[10:11]
	v_lshl_add_u64 v[10:11], v[68:69], 1, v[10:11]
	v_cvt_pk_bf16_f32 v6, v6, v7
	v_cvt_pk_bf16_f32 v7, v8, v9
	v_mov_b32_e32 v246, v6
	v_mov_b32_e32 v247, v7
	v_lshl_add_u64 v[156:157], v[10:11], 0, v[154:155]
	s_nop 0
	v_permlane16_swap_b32_e32 v244, v246
	v_permlane16_swap_b32_e32 v245, v247
	global_store_dwordx4 v[156:157], v[244:247], off offset:64
.LBB0_827:
	s_or_b64 exec, exec, s[46:47]
	s_and_saveexec_b64 s[6:7], s[40:41]
	s_xor_b64 s[40:41], exec, s[6:7]
	s_cbranch_execz .LBB0_849
	v_lshlrev_b64 v[6:7], 12, v[54:55]
	s_and_saveexec_b64 s[6:7], s[38:39]
	s_xor_b64 s[38:39], exec, s[6:7]
	s_cbranch_execz .LBB0_830
	v_mul_f32_e32 v1, 0xbfb8aa3b, v2
	v_exp_f32_e32 v1, v1
	v_readlane_b32 s6, v252, 35
	v_readlane_b32 s7, v252, 36
	v_add_f32_e32 v1, 1.0, v1
	v_rcp_f32_e32 v8, v1
	v_mul_f32_e32 v1, 0xbfb8aa3b, v3
	v_exp_f32_e32 v1, v1
	v_lshl_add_u64 v[6:7], s[6:7], 0, v[6:7]
	v_lshl_add_u64 v[6:7], v[182:183], 1, v[6:7]
	v_add_f32_e32 v1, 1.0, v1
	v_rcp_f32_e32 v9, v1
	v_mul_f32_e32 v1, 0xbfb8aa3b, v4
	v_exp_f32_e32 v1, v1
	v_pk_mul_f32 v[2:3], v[2:3], v[8:9]
	s_nop 0
	v_cvt_pk_bf16_f32 v2, v2, v3
	v_add_f32_e32 v1, 1.0, v1
	v_rcp_f32_e32 v8, v1
	v_mul_f32_e32 v1, 0xbfb8aa3b, v5
	v_exp_f32_e32 v1, v1
	s_nop 0
	v_add_f32_e32 v1, 1.0, v1
	v_rcp_f32_e32 v9, v1
	s_nop 0
	v_pk_mul_f32 v[4:5], v[4:5], v[8:9]
	s_nop 0
	v_cvt_pk_bf16_f32 v3, v4, v5
	v_add_co_u32_e32 v4, vcc, 0xfffff000, v6
	s_nop 1
	v_addc_co_u32_e32 v5, vcc, -1, v7, vcc
	v_mov_b32_e32 v250, v2
	v_mov_b32_e32 v251, v3
	v_lshl_add_u64 v[156:157], v[4:5], 0, v[154:155]
	s_nop 0
	v_permlane16_swap_b32_e32 v248, v250
	v_permlane16_swap_b32_e32 v249, v251
	global_store_dwordx4 v[156:157], v[248:251], off offset:-1984
.LBB0_830:
	s_andn2_saveexec_b64 s[38:39], s[38:39]
	s_cbranch_execz .LBB0_848
	v_pk_mul_f32 v[130:131], v[2:3], v[170:171]
	v_pk_mul_f32 v[142:143], v[4:5], v[170:171]
	v_and_b32_e32 v132, 0x7fffffff, v130
	v_and_b32_e32 v144, 0x7fffffff, v142
	v_and_b32_e32 v133, 0x7fffffff, v131
	v_and_b32_e32 v145, 0x7fffffff, v143
	v_pk_fma_f32 v[134:135], v[132:133], v[174:175], v[176:177]
	v_pk_fma_f32 v[146:147], v[144:145], v[174:175], v[176:177]
	v_pk_fma_f32 v[134:135], v[132:133], v[134:135], v[178:179]
	v_pk_fma_f32 v[146:147], v[144:145], v[146:147], v[178:179]
	v_pk_fma_f32 v[134:135], v[132:133], v[134:135], v[180:181]
	v_pk_fma_f32 v[146:147], v[144:145], v[146:147], v[180:181]
	v_pk_fma_f32 v[134:135], v[132:133], v[134:135], v[186:187]
	v_pk_fma_f32 v[146:147], v[144:145], v[146:147], v[186:187]
	v_pk_fma_f32 v[134:135], v[132:133], v[134:135], v[188:189]
	v_pk_fma_f32 v[146:147], v[144:145], v[146:147], v[188:189]
	v_pk_fma_f32 v[134:135], v[132:133], v[134:135], v[190:191]
	v_pk_fma_f32 v[146:147], v[144:145], v[146:147], v[190:191]
	v_pk_fma_f32 v[134:135], v[132:133], v[134:135], v[132:133]
	v_pk_fma_f32 v[146:147], v[144:145], v[146:147], v[144:145]
	v_pk_mul_f32 v[134:135], v[134:135], v[172:173]
	v_pk_mul_f32 v[146:147], v[146:147], v[172:173]
	v_pk_mul_f32 v[136:137], v[130:131], v[130:131]
	v_pk_mul_f32 v[148:149], v[142:143], v[142:143]
	v_exp_f32_e32 v134, v134
	v_exp_f32_e32 v146, v146
	v_exp_f32_e32 v135, v135
	v_exp_f32_e32 v147, v147
	v_pk_fma_f32 v[138:139], v[136:137], v[192:193], v[194:195]
	v_pk_fma_f32 v[150:151], v[148:149], v[192:193], v[194:195]
	v_pk_fma_f32 v[138:139], v[136:137], v[138:139], v[196:197]
	v_pk_fma_f32 v[150:151], v[148:149], v[150:151], v[196:197]
	v_pk_fma_f32 v[138:139], v[136:137], v[138:139], v[224:225]
	v_pk_fma_f32 v[150:151], v[148:149], v[150:151], v[224:225]
	v_pk_fma_f32 v[138:139], v[136:137], v[138:139], v[226:227]
	v_pk_fma_f32 v[150:151], v[148:149], v[150:151], v[226:227]
	v_pk_fma_f32 v[138:139], v[136:137], v[138:139], v[228:229]
	v_pk_fma_f32 v[150:151], v[148:149], v[150:151], v[228:229]
	v_pk_fma_f32 v[134:135], v[134:135], v[234:235], v[230:231]
	v_pk_fma_f32 v[146:147], v[146:147], v[234:235], v[230:231]
	v_pk_fma_f32 v[138:139], v[132:133], v[138:139], v[132:133]
	v_pk_fma_f32 v[150:151], v[144:145], v[150:151], v[144:145]
	v_pk_mul_f32 v[140:141], v[2:3], v[232:233]
	v_pk_mul_f32 v[152:153], v[4:5], v[232:233]
	v_cmp_ngt_f32_e32 vcc, 1.0, v132
	v_cmp_ngt_f32_e64 s[8:9], 1.0, v133
	v_readlane_b32 s6, v252, 33
	v_readlane_b32 s7, v252, 34
	v_cndmask_b32_e32 v138, v138, v134, vcc
	v_cndmask_b32_e64 v139, v139, v135, s[8:9]
	v_cmp_ngt_f32_e32 vcc, 1.0, v144
	v_cmp_ngt_f32_e64 s[8:9], 1.0, v145
	v_bfi_b32 v138, s37, v138, v130
	v_bfi_b32 v139, s37, v139, v131
	v_cndmask_b32_e32 v150, v150, v146, vcc
	v_cndmask_b32_e64 v151, v151, v147, s[8:9]
	v_pk_add_f32 v[138:139], v[138:139], v[230:231]
	v_bfi_b32 v150, s37, v150, v142
	v_bfi_b32 v151, s37, v151, v143
	v_pk_add_f32 v[150:151], v[150:151], v[230:231]
	v_pk_mul_f32 v[138:139], v[140:141], v[138:139]
	v_lshl_add_u64 v[2:3], s[6:7], 0, v[6:7]
	v_pk_mul_f32 v[150:151], v[152:153], v[150:151]
	v_lshl_add_u64 v[2:3], v[182:183], 1, v[2:3]
	v_cvt_pk_bf16_f32 v4, v138, v139
	v_cvt_pk_bf16_f32 v5, v150, v151
	v_mov_b32_e32 v250, v4
	v_mov_b32_e32 v251, v5
	v_lshl_add_u64 v[156:157], v[2:3], 0, v[154:155]
	s_nop 0
	v_permlane16_swap_b32_e32 v248, v250
	v_permlane16_swap_b32_e32 v249, v251
	global_store_dwordx4 v[156:157], v[248:251], off offset:-1984

; DI void st_bf4(u16* p, float a, float b, float c, float d) { *(uint2*)p = make_uint2(pk2(a, b), pk2(c, d)); }
;   template <int NT, int MT> DI void run(f32x4 (&acc)[NT][MT], int mb, int nb) const {
;     ...
;         if (n < 1024) {
;           st_bf4(abuf + (size_t)m * 1024 + n, v[0], v[1], v[2], v[3]);
;           float* dst = nullptr;
;           if (m < M_PROMPT) { int t = m & 8191; if (t >= 8177) dst = spp + ((size_t)((m >> 13) * 15 + (t - 8177))) * 1024 + n; }
;           else { int r = m - M_PROMPT; int s = r & 31; if (s >= 17) dst = sps + ((size_t)((r >> 5) * 15 + (s - 17))) * 1024 + n; }
;           if (dst) *(float4*)dst = make_float4(v[0], v[1], v[2], v[3]);
.LBB0_849:
	s_andn2_saveexec_b64 s[38:39], s[40:41]
	s_cbranch_execz .LBB0_418
	v_lshlrev_b64 v[6:7], 11, v[54:55]
	v_lshl_add_u64 v[6:7], s[96:97], 0, v[6:7]
	s_movk_i32 s5, 0x3fcf
	v_lshl_add_u64 v[6:7], v[68:69], 1, v[6:7]
	v_cvt_pk_bf16_f32 v8, v2, v3
	v_cvt_pk_bf16_f32 v9, v4, v5
	v_cmp_lt_i32_e32 vcc, s5, v66
	v_mov_b32_e32 v250, v8
	v_mov_b32_e32 v251, v9
	v_lshl_add_u64 v[156:157], v[6:7], 0, v[154:155]
	s_nop 0
	v_permlane16_swap_b32_e32 v248, v250
	v_permlane16_swap_b32_e32 v249, v251
	global_store_dwordx4 v[156:157], v[248:251], off offset:64
	s_and_saveexec_b64 s[6:7], vcc
	s_xor_b64 s[40:41], exec, s[6:7]
	s_cbranch_execz .LBB0_867
	v_and_b32_e32 v8, 31, v54
	v_cmp_ne_u32_e32 vcc, 16, v8
	v_mov_b64_e32 v[6:7], 0
	s_and_saveexec_b64 s[46:47], vcc
	s_cbranch_execz .LBB0_853
	v_add_u32_e32 v1, 0xffffc030, v1
	v_lshrrev_b32_e32 v1, 5, v1
	v_mul_lo_u32 v1, v1, 15
	s_movk_i32 s5, 0xffef
	v_add3_u32 v182, v8, v1, s5
	v_readlane_b32 s6, v252, 57
	v_lshlrev_b64 v[6:7], 12, v[182:183]
	v_readlane_b32 s7, v252, 58
	s_nop 1
	v_lshl_add_u64 v[6:7], s[6:7], 0, v[6:7]
	v_lshl_add_u64 v[6:7], v[68:69], 2, v[6:7]
	s_mov_b64 s[6:7], 0xc0
	v_lshl_add_u64 v[6:7], v[6:7], 0, s[6:7]

; template <int MT, class Epi>
; DI void gemm_tile(const u16* __restrict__ X, long ldx, const u16* __restrict__ W, long ldw, int K, char* smem,
;                   int m0, int n0, const Epi& epi, bool pre = false, const u16* Xn = nullptr, const u16* Wn = nullptr) {
;     ...
;   do {
;     asm volatile("s_waitcnt vmcnt(0)" ::: "memory");
;     __syncthreads();
;     if (kt + 1 < nk) GT_DMA((unsigned)((kt + 1) & 1) * 32768u)
;     else if (Xn != nullptr) { xe = Xn + oxe; xo = Xn + oxo; we = Wn + owe; wo = Wn + owo; GT_DMA(0u) }
;     const char* cur = smem + (kt & 1) * 32768;
; #pragma unroll
;     for (int ks = 0; ks < 2; ++ks) {
;       bf16x8 xf[MT], wf[4];
;       const int ch = ((ks * 4 + g) ^ rsw) << 4;
; #pragma unroll
;       for (int i = 0; i < MT; ++i) xf[i] = *(const bf16x8*)(cur + (wm * 16 * MT + i * 16 + lr) * 128 + ch);
; #pragma unroll
;       for (int i = 0; i < 4; ++i) wf[i] = *(const bf16x8*)(cur + 16384 + (wn * 64 + i * 16 + lr) * 128 + ch);
; #pragma unroll
;       for (int nt = 0; nt < 4; ++nt)
; #pragma unroll
;         for (int mt = 0; mt < MT; ++mt)
;           acc[nt][mt] = __builtin_amdgcn_mfma_f32_16x16x32_bf16(wf[nt], xf[mt], acc[nt][mt], 0, 0, 0);
;     }
;   } while (++kt < nk);
.LBB0_1312:
	s_add_i32 s7, s8, 0x8000
	v_lshl_add_u64 v[124:125], v[74:75], 0, s[40:41]
	s_and_b32 s9, s7, 0x8000
	v_lshl_add_u64 v[122:123], v[72:73], 0, s[40:41]
	v_lshl_add_u64 v[126:127], v[124:125], 0, s[74:75]
	s_waitcnt vmcnt(0)
	s_waitcnt lgkmcnt(0)
	s_barrier
	s_and_b32 s8, s8, 0x8000
	v_or_b32_e32 v162, s8, v84
	v_add3_u32 v163, v162, v80, v81
	v_add3_u32 v164, v162, v83, v81
	v_or_b32_e32 v165, s8, v82
	v_add3_u32 v166, v165, v80, v81
	v_add3_u32 v167, v165, v83, v81
	ds_read_b128 v[86:89], v163
	ds_read_b128 v[90:93], v163 offset:2048
	ds_read_b128 v[94:97], v163 offset:4096
	ds_read_b128 v[98:101], v163 offset:6144
	ds_read_b128 v[102:105], v164 offset:16384
	ds_read_b128 v[106:109], v164 offset:18432
	ds_read_b128 v[110:113], v164 offset:20480
	ds_read_b128 v[114:117], v164 offset:22528
	ds_read_b128 v[130:133], v166
	ds_read_b128 v[134:137], v166 offset:2048
	ds_read_b128 v[138:141], v166 offset:4096
	ds_read_b128 v[142:145], v166 offset:6144
	ds_read_b128 v[146:149], v167 offset:16384
	ds_read_b128 v[150:153], v167 offset:18432
	ds_read_b128 v[154:157], v167 offset:20480
	ds_read_b128 v[158:161], v167 offset:22528
	s_add_i32 s10, s9, s5
	s_mov_b32 m0, s10
	s_nop 0
	global_load_lds_dwordx4 v[126:127], off
	v_lshl_add_u64 v[126:127], v[122:123], 0, s[94:95]
	s_add_i32 s11, s10, 0x400
	s_mov_b32 m0, s11
	s_nop 0
	global_load_lds_dwordx4 v[126:127], off
	v_lshl_add_u64 v[124:125], v[124:125], 0, s[76:77]
	s_add_i32 s11, s10, 0x800
	s_mov_b32 m0, s11
	s_nop 0
	global_load_lds_dwordx4 v[124:125], off
	v_lshl_add_u64 v[120:121], v[70:71], 0, s[40:41]
	v_lshl_add_u64 v[122:123], v[122:123], 0, s[54:55]
	s_addk_i32 s10, 0xc00
	s_mov_b32 m0, s10
	s_nop 0
	global_load_lds_dwordx4 v[122:123], off
	v_lshl_add_u64 v[118:119], v[68:69], 0, s[40:41]
	v_lshl_add_u64 v[128:129], v[120:121], 0, s[28:29]
	s_add_i32 s9, s9, s6
	s_mov_b32 m0, s9
	s_nop 0
	global_load_lds_dwordx4 v[128:129], off
	v_lshl_add_u64 v[122:123], v[118:119], 0, s[94:95]
	s_add_i32 s10, s9, 0x400
	s_mov_b32 m0, s10
	s_nop 0
	global_load_lds_dwordx4 v[122:123], off
	v_lshl_add_u64 v[120:121], v[120:121], 0, s[78:79]
	s_add_i32 s10, s9, 0x800
	s_mov_b32 m0, s10
	s_nop 0
	global_load_lds_dwordx4 v[120:121], off
	v_lshl_add_u64 v[118:119], v[118:119], 0, s[54:55]
	s_addk_i32 s9, 0xc00
	s_mov_b32 m0, s9
	s_nop 0
	global_load_lds_dwordx4 v[118:119], off
	s_mov_b32 s8, s7
	s_add_u32 s40, s40, 0x80
	s_addc_u32 s41, s41, 0
	s_cmpk_lg_i32 s40, 0x780
	s_waitcnt lgkmcnt(11)
	v_mfma_f32_16x16x32_bf16 v[48:51], v[102:105], v[98:101], v[48:51]
	s_waitcnt lgkmcnt(10)
	v_mfma_f32_16x16x32_bf16 v[32:35], v[106:109], v[98:101], v[32:35]
	s_waitcnt lgkmcnt(9)
	v_mfma_f32_16x16x32_bf16 v[16:19], v[110:113], v[98:101], v[16:19]
	s_waitcnt lgkmcnt(8)
	v_mfma_f32_16x16x32_bf16 v[0:3], v[114:117], v[98:101], v[0:3]
	v_mfma_f32_16x16x32_bf16 v[60:63], v[102:105], v[86:89], v[60:63]
	v_mfma_f32_16x16x32_bf16 v[56:59], v[102:105], v[90:93], v[56:59]
	v_mfma_f32_16x16x32_bf16 v[52:55], v[102:105], v[94:97], v[52:55]
	v_mfma_f32_16x16x32_bf16 v[44:47], v[106:109], v[86:89], v[44:47]
	v_mfma_f32_16x16x32_bf16 v[40:43], v[106:109], v[90:93], v[40:43]
	v_mfma_f32_16x16x32_bf16 v[36:39], v[106:109], v[94:97], v[36:39]
	v_mfma_f32_16x16x32_bf16 v[28:31], v[110:113], v[86:89], v[28:31]
	v_mfma_f32_16x16x32_bf16 v[24:27], v[110:113], v[90:93], v[24:27]
	v_mfma_f32_16x16x32_bf16 v[20:23], v[110:113], v[94:97], v[20:23]
	v_mfma_f32_16x16x32_bf16 v[12:15], v[114:117], v[86:89], v[12:15]
	v_mfma_f32_16x16x32_bf16 v[8:11], v[114:117], v[90:93], v[8:11]
	v_mfma_f32_16x16x32_bf16 v[4:7], v[114:117], v[94:97], v[4:7]
	s_waitcnt lgkmcnt(3)
	v_mfma_f32_16x16x32_bf16 v[60:63], v[146:149], v[130:133], v[60:63]
	v_mfma_f32_16x16x32_bf16 v[56:59], v[146:149], v[134:137], v[56:59]
	v_mfma_f32_16x16x32_bf16 v[52:55], v[146:149], v[138:141], v[52:55]
	v_mfma_f32_16x16x32_bf16 v[48:51], v[146:149], v[142:145], v[48:51]
	s_waitcnt lgkmcnt(2)
	v_mfma_f32_16x16x32_bf16 v[44:47], v[150:153], v[130:133], v[44:47]
	v_mfma_f32_16x16x32_bf16 v[40:43], v[150:153], v[134:137], v[40:43]
	v_mfma_f32_16x16x32_bf16 v[36:39], v[150:153], v[138:141], v[36:39]
	v_mfma_f32_16x16x32_bf16 v[32:35], v[150:153], v[142:145], v[32:35]
	s_waitcnt lgkmcnt(1)
	v_mfma_f32_16x16x32_bf16 v[28:31], v[154:157], v[130:133], v[28:31]
	v_mfma_f32_16x16x32_bf16 v[24:27], v[154:157], v[134:137], v[24:27]
	v_mfma_f32_16x16x32_bf16 v[20:23], v[154:157], v[138:141], v[20:23]
	v_mfma_f32_16x16x32_bf16 v[16:19], v[154:157], v[142:145], v[16:19]
	s_waitcnt lgkmcnt(0)
	v_mfma_f32_16x16x32_bf16 v[12:15], v[158:161], v[130:133], v[12:15]
	v_mfma_f32_16x16x32_bf16 v[8:11], v[158:161], v[134:137], v[8:11]
	v_mfma_f32_16x16x32_bf16 v[4:7], v[158:161], v[138:141], v[4:7]
	v_mfma_f32_16x16x32_bf16 v[0:3], v[158:161], v[142:145], v[0:3]
	s_cbranch_scc1 .LBB0_1312
; DI int get_bid() { int b = blockIdx.x; asm volatile("" : "+s"(b)); return b; }
; template <int MT, class Epi>
; DI void gemm_tile(const u16* __restrict__ X, long ldx, const u16* __restrict__ W, long ldw, int K, char* smem,
;                   int m0, int n0, const Epi& epi, bool pre = false, const u16* Xn = nullptr, const u16* Wn = nullptr) {
;     ...
;     if (kt + 1 < nk) GT_DMA((unsigned)((kt + 1) & 1) * 32768u)
;     else if (Xn != nullptr) { xe = Xn + oxe; xo = Xn + oxo; we = Wn + owe; wo = Wn + owo; GT_DMA(0u) }
;     const char* cur = smem + (kt & 1) * 32768;
; #pragma unroll
;     for (int ks = 0; ks < 2; ++ks) {
;       bf16x8 xf[MT], wf[4];
;       const int ch = ((ks * 4 + g) ^ rsw) << 4;
; #pragma unroll
;       for (int i = 0; i < MT; ++i) xf[i] = *(const bf16x8*)(cur + (wm * 16 * MT + i * 16 + lr) * 128 + ch);
; #pragma unroll
;       for (int i = 0; i < 4; ++i) wf[i] = *(const bf16x8*)(cur + 16384 + (wn * 64 + i * 16 + lr) * 128 + ch);
; #pragma unroll
;       for (int nt = 0; nt < 4; ++nt)
; #pragma unroll
;         for (int mt = 0; mt < MT; ++mt)
;           acc[nt][mt] = __builtin_amdgcn_mfma_f32_16x16x32_bf16(wf[nt], xf[mt], acc[nt][mt], 0, 0, 0);
;     }
;   } while (++kt < nk);
;     ...
;   epi.run(acc, m0 + wm * 16 * MT + lr, n0 + wn * 64 + 4 * g);
; DI void phase_even(const Params& p, int e, int sub, char* smem) {
;     ...
;     for (int t = get_bid(); t < 132 * 40; t += gridDim.x) {
;       const int tm = t / 40, tn = t % 40;
;       const int t2 = t + gridDim.x, tm2 = t2 / 40, tn2 = t2 % 40;
;       const bool nx = t2 < 132 * 40;
;       gemm_tile<4>(hbuf + (size_t)tm * 128 * 1024, 1024, W + WE_IN + (size_t)tn * 128 * 1024, 1024, 1024, smem, tm * 128, tn * 128, epi, pre,
;                    nx ? hbuf + (size_t)tm2 * 128 * 1024 : nullptr, W + WE_IN + (size_t)tn2 * 128 * 1024);
	v_bfe_u32 v154, v185, 4, 1
	v_mul_u32_u24_e32 v154, 24, v154
	v_mov_b32_e32 v155, 0
	v_mov_b32_e32 v170, 0x3f3504f3
	v_mov_b32_e32 v171, 0x3f3504f3
	v_mov_b32_e32 v172, 0xbfb8aa3b
	v_mov_b32_e32 v173, 0xbfb8aa3b
	v_mov_b32_e32 v174, 0x378e98ab
	v_mov_b32_e32 v175, 0x378e98ab
	v_mov_b32_e32 v176, 0xb9c68948
	v_mov_b32_e32 v177, 0xb9c68948
	v_mov_b32_e32 v178, 0x3b7cd369
	v_mov_b32_e32 v179, 0x3b7cd369
	v_mov_b32_e32 v180, 0xbcc618b2
	v_mov_b32_e32 v181, 0xbcc618b2
	v_mov_b32_e32 v186, 0x3dda74e4
	v_mov_b32_e32 v187, 0x3dda74e4
	v_mov_b32_e32 v188, 0x3f228afd
	v_mov_b32_e32 v189, 0x3f228afd
	v_mov_b32_e32 v190, 0x3e03c728
	v_mov_b32_e32 v191, 0x3e03c728
	v_mov_b32_e32 v192, 0xba1345e1
	v_mov_b32_e32 v193, 0xba1345e1
	v_mov_b32_e32 v194, 0x3ba10414
	v_mov_b32_e32 v195, 0x3ba10414
	v_mov_b32_e32 v196, 0xbcdac9b8
	v_mov_b32_e32 v197, 0xbcdac9b8
	v_mov_b32_e32 v224, 0x3de703be
	v_mov_b32_e32 v225, 0x3de703be
	v_mov_b32_e32 v226, 0xbec09330
	v_mov_b32_e32 v227, 0xbec09330
	v_mov_b32_e32 v228, 0x3e0375d0
	v_mov_b32_e32 v229, 0x3e0375d0
	v_mov_b32_e32 v230, 1.0
	v_mov_b32_e32 v231, 1.0
	v_mov_b32_e32 v232, 0.5
	v_mov_b32_e32 v233, 0.5
	v_mov_b32_e32 v234, -1.0
	v_mov_b32_e32 v235, -1.0
	v_readlane_b32 s8, v255, 5
	v_readlane_b32 s14, v255, 11
	s_add_i32 s4, s4, s14
	s_mul_hi_i32 s7, s4, 0x66666667
	s_lshr_b32 s8, s7, 31
	s_ashr_i32 s7, s7, 4
	s_add_i32 s46, s7, s8
	s_cmpk_gt_i32 s4, 0x149f
	v_readlane_b32 s9, v255, 6
	s_cselect_b64 s[44:45], -1, 0
	s_ashr_i32 s47, s46, 31
	s_lshl_b64 s[8:9], s[46:47], 18
	s_add_u32 s7, s0, s8
	s_addc_u32 s8, s1, s9
	s_cmpk_lt_i32 s4, 0x14a0
	s_waitcnt vmcnt(0)
	s_cselect_b32 s41, s8, 0
	s_cselect_b32 s40, s7, 0
	v_readlane_b32 s12, v255, 9
	v_readlane_b32 s13, v255, 10
	s_cmp_eq_u64 s[40:41], 0
	v_readlane_b32 s10, v255, 7
	v_readlane_b32 s11, v255, 8
	v_readlane_b32 s15, v255, 12
	s_barrier
	s_cbranch_scc1 .LBB0_1315
	s_mul_i32 s7, s46, 40
	s_sub_i32 s8, s4, s7
	s_ashr_i32 s9, s8, 31
	s_lshl_b64 s[8:9], s[8:9], 18
	s_add_u32 s8, s12, s8
	s_addc_u32 s9, s13, s9
	v_lshl_add_u64 v[68:69], s[40:41], 0, v[66:67]
	v_lshl_add_u64 v[70:71], s[8:9], 0, v[64:65]
	v_lshl_add_u64 v[64:65], s[40:41], 0, v[64:65]
	s_mov_b32 m0, s5
	s_nop 0
	global_load_lds_dwordx4 v[68:69], off
	s_mov_b64 s[10:11], 0x4000
	v_lshl_add_u64 v[66:67], s[8:9], 0, v[66:67]
	v_lshl_add_u64 v[72:73], v[64:65], 0, s[10:11]
	s_add_i32 s7, s5, 0x400
	s_mov_b32 m0, s7
	s_nop 0
	global_load_lds_dwordx4 v[72:73], off
	s_mov_b64 s[12:13], 0x8000
	v_lshl_add_u64 v[68:69], v[68:69], 0, s[12:13]
	s_add_i32 s7, s5, 0x800
	s_mov_b32 m0, s7
	s_nop 0
	global_load_lds_dwordx4 v[68:69], off
	s_mov_b64 s[14:15], 0xc000
	v_lshl_add_u64 v[64:65], v[64:65], 0, s[14:15]
	s_add_i32 s7, s5, 0xc00
	s_mov_b32 m0, s7
	s_nop 0
	global_load_lds_dwordx4 v[64:65], off
	s_mov_b32 m0, s6
	s_nop 0
	global_load_lds_dwordx4 v[66:67], off
	v_lshl_add_u64 v[64:65], v[70:71], 0, s[10:11]
	s_add_i32 s6, s5, 0x4400
	s_mov_b32 m0, s6
	s_nop 0
	global_load_lds_dwordx4 v[64:65], off
	v_lshl_add_u64 v[64:65], v[66:67], 0, s[12:13]
	s_add_i32 s6, s5, 0x4800
	s_mov_b32 m0, s6
	s_nop 0
	global_load_lds_dwordx4 v[64:65], off
	v_lshl_add_u64 v[64:65], v[70:71], 0, s[14:15]
	s_addk_i32 s5, 0x4c00
	s_mov_b32 m0, s5
	s_nop 0
	global_load_lds_dwordx4 v[64:65], off
.LBB0_1315:
	v_add3_u32 v92, v84, v83, v81
	ds_read_b128 v[64:67], v92 offset:49152
	v_add3_u32 v88, v84, v80, v81
	ds_read_b128 v[68:71], v88 offset:32768
	ds_read_b128 v[72:75], v88 offset:34816
	ds_read_b128 v[84:87], v88 offset:36864
	ds_read_b128 v[88:91], v88 offset:38912
	s_lshl_b32 s6, s38, 7
	s_lshl_b32 s5, s42, 7
	s_waitcnt lgkmcnt(3)
	v_mfma_f32_16x16x32_bf16 v[60:63], v[64:67], v[68:71], v[60:63]
	s_waitcnt lgkmcnt(2)
	v_mfma_f32_16x16x32_bf16 v[56:59], v[64:67], v[72:75], v[56:59]
	s_waitcnt lgkmcnt(1)
	v_mfma_f32_16x16x32_bf16 v[52:55], v[64:67], v[84:87], v[52:55]
	s_waitcnt lgkmcnt(0)
	v_mfma_f32_16x16x32_bf16 v[48:51], v[64:67], v[88:91], v[48:51]
	ds_read_b128 v[64:67], v92 offset:51200
	s_waitcnt lgkmcnt(0)
	v_mfma_f32_16x16x32_bf16 v[44:47], v[64:67], v[68:71], v[44:47]
	v_mfma_f32_16x16x32_bf16 v[40:43], v[64:67], v[72:75], v[40:43]
	v_mfma_f32_16x16x32_bf16 v[36:39], v[64:67], v[84:87], v[36:39]
	v_mfma_f32_16x16x32_bf16 v[32:35], v[64:67], v[88:91], v[32:35]
	ds_read_b128 v[64:67], v92 offset:53248
	s_waitcnt lgkmcnt(0)
	v_mfma_f32_16x16x32_bf16 v[28:31], v[64:67], v[68:71], v[28:31]
	v_mfma_f32_16x16x32_bf16 v[24:27], v[64:67], v[72:75], v[24:27]
	v_mfma_f32_16x16x32_bf16 v[20:23], v[64:67], v[84:87], v[20:23]
	v_mfma_f32_16x16x32_bf16 v[16:19], v[64:67], v[88:91], v[16:19]
	ds_read_b128 v[64:67], v92 offset:55296
	v_add3_u32 v92, v82, v83, v81
	s_waitcnt lgkmcnt(0)
	v_mfma_f32_16x16x32_bf16 v[12:15], v[64:67], v[68:71], v[12:15]
	ds_read_b128 v[68:71], v92 offset:49152
	v_mfma_f32_16x16x32_bf16 v[4:7], v[64:67], v[84:87], v[4:7]
	v_add3_u32 v84, v82, v80, v81
	ds_read_b128 v[80:83], v84 offset:36864
	v_mfma_f32_16x16x32_bf16 v[8:11], v[64:67], v[72:75], v[8:11]
	ds_read_b128 v[72:75], v84 offset:34816
	v_mfma_f32_16x16x32_bf16 v[0:3], v[64:67], v[88:91], v[0:3]
	ds_read_b128 v[64:67], v84 offset:32768
	ds_read_b128 v[84:87], v84 offset:38912
	ds_read_b128 v[88:91], v92 offset:55296
	s_waitcnt lgkmcnt(2)
	v_mfma_f32_16x16x32_bf16 v[60:63], v[68:71], v[64:67], v[60:63]
	v_mfma_f32_16x16x32_bf16 v[56:59], v[68:71], v[72:75], v[56:59]
	v_mfma_f32_16x16x32_bf16 v[52:55], v[68:71], v[80:83], v[52:55]
	s_waitcnt lgkmcnt(1)
	v_mfma_f32_16x16x32_bf16 v[48:51], v[68:71], v[84:87], v[48:51]
	ds_read_b128 v[68:71], v92 offset:51200
	s_waitcnt lgkmcnt(0)
	v_mfma_f32_16x16x32_bf16 v[44:47], v[68:71], v[64:67], v[44:47]
	v_mfma_f32_16x16x32_bf16 v[40:43], v[68:71], v[72:75], v[40:43]
	v_mfma_f32_16x16x32_bf16 v[36:39], v[68:71], v[80:83], v[36:39]
	v_mfma_f32_16x16x32_bf16 v[32:35], v[68:71], v[84:87], v[32:35]
	ds_read_b128 v[68:71], v92 offset:53248
	s_waitcnt lgkmcnt(0)
	v_mfma_f32_16x16x32_bf16 v[28:31], v[68:71], v[64:67], v[28:31]
	v_mfma_f32_16x16x32_bf16 v[24:27], v[68:71], v[72:75], v[24:27]
	v_mfma_f32_16x16x32_bf16 v[20:23], v[68:71], v[80:83], v[20:23]
	v_mfma_f32_16x16x32_bf16 v[16:19], v[68:71], v[84:87], v[16:19]
	v_lshl_or_b32 v68, v77, 6, s5
	s_movk_i32 s5, 0x3ff
	v_mfma_f32_16x16x32_bf16 v[12:15], v[88:91], v[64:67], v[12:15]
	v_lshl_add_u32 v65, v79, 6, s6
	v_lshl_or_b32 v182, v76, 2, v65
	v_or_b32_e32 v64, v68, v78
	v_mfma_f32_16x16x32_bf16 v[8:11], v[88:91], v[72:75], v[8:11]
	v_cmp_lt_i32_e64 s[40:41], s5, v182
	s_movk_i32 s5, 0xbff
	v_cmp_lt_u32_e64 s[38:39], s5, v65
	v_mfma_f32_16x16x32_bf16 v[4:7], v[88:91], v[80:83], v[4:7]
	v_ashrrev_i32_e32 v65, 31, v64
	v_mfma_f32_16x16x32_bf16 v[0:3], v[88:91], v[84:87], v[0:3]
	s_and_saveexec_b64 s[6:7], s[40:41]
	s_xor_b64 s[46:47], exec, s[6:7]
	s_cbranch_execz .LBB0_1337
; DI void st_bf4(u16* p, float a, float b, float c, float d) { *(uint2*)p = make_uint2(pk2(a, b), pk2(c, d)); }
; DI float gelu_f(float x) { return 0.5f * x * (1.f + erff(x * 0.70710678118654752f)); }
; DI float silu_f(float x) { return x * __builtin_amdgcn_rcpf(1.f + __expf(-x)); }
;   template <int NT, int MT> DI void run(f32x4 (&acc)[NT][MT], int mb, int nb) const {
;     ...
;         } else if (n < 3072) {
;           st_bf4(uvbuf + (size_t)m * 2048 + (n - 1024), gelu_f(v[0]), gelu_f(v[1]), gelu_f(v[2]), gelu_f(v[3]));
;         } else {
;           st_bf4(gatebuf + (size_t)m * 2048 + (n - 3072), silu_f(v[0]), silu_f(v[1]), silu_f(v[2]), silu_f(v[3]));
	v_lshlrev_b64 v[66:67], 12, v[64:65]
	s_and_saveexec_b64 s[6:7], s[38:39]
	s_xor_b64 s[48:49], exec, s[6:7]
	s_cbranch_execz .LBB0_1318
	v_mul_f32_e32 v69, 0xbfb8aa3b, v60
	v_exp_f32_e32 v69, v69
	v_readlane_b32 s6, v252, 35
	v_readlane_b32 s7, v252, 36
	v_add_f32_e32 v69, 1.0, v69
	v_rcp_f32_e32 v70, v69
	v_mul_f32_e32 v69, 0xbfb8aa3b, v61
	v_exp_f32_e32 v69, v69
	v_lshl_add_u64 v[66:67], s[6:7], 0, v[66:67]
	v_lshl_add_u64 v[66:67], v[182:183], 1, v[66:67]
	v_add_f32_e32 v69, 1.0, v69
	v_rcp_f32_e32 v71, v69
	v_mul_f32_e32 v69, 0xbfb8aa3b, v62
	v_exp_f32_e32 v69, v69
	v_pk_mul_f32 v[60:61], v[60:61], v[70:71]
	s_nop 0
	v_cvt_pk_bf16_f32 v60, v60, v61
	v_add_f32_e32 v69, 1.0, v69
	v_rcp_f32_e32 v70, v69
	v_mul_f32_e32 v69, 0xbfb8aa3b, v63
	v_exp_f32_e32 v69, v69
	s_nop 0
	v_add_f32_e32 v69, 1.0, v69
	v_rcp_f32_e32 v71, v69
	s_nop 0
	v_pk_mul_f32 v[62:63], v[62:63], v[70:71]
	s_nop 0
	v_cvt_pk_bf16_f32 v61, v62, v63
	v_add_co_u32_e32 v62, vcc, 0xfffff000, v66
	s_nop 1
	v_addc_co_u32_e32 v63, vcc, -1, v67, vcc
	v_mov_b32_e32 v236, v60
	v_mov_b32_e32 v237, v61
.LBB0_1318:
	s_andn2_saveexec_b64 s[48:49], s[48:49]
	s_cbranch_execz .LBB0_1336
	v_pk_mul_f32 v[130:131], v[60:61], v[170:171]
	v_pk_mul_f32 v[142:143], v[62:63], v[170:171]
	v_and_b32_e32 v132, 0x7fffffff, v130
	v_and_b32_e32 v144, 0x7fffffff, v142
	v_and_b32_e32 v133, 0x7fffffff, v131
	v_and_b32_e32 v145, 0x7fffffff, v143
	v_pk_fma_f32 v[134:135], v[132:133], v[174:175], v[176:177]
	v_pk_fma_f32 v[146:147], v[144:145], v[174:175], v[176:177]
	v_pk_fma_f32 v[134:135], v[132:133], v[134:135], v[178:179]
	v_pk_fma_f32 v[146:147], v[144:145], v[146:147], v[178:179]
	v_pk_fma_f32 v[134:135], v[132:133], v[134:135], v[180:181]
	v_pk_fma_f32 v[146:147], v[144:145], v[146:147], v[180:181]
	v_pk_fma_f32 v[134:135], v[132:133], v[134:135], v[186:187]
	v_pk_fma_f32 v[146:147], v[144:145], v[146:147], v[186:187]
	v_pk_fma_f32 v[134:135], v[132:133], v[134:135], v[188:189]
	v_pk_fma_f32 v[146:147], v[144:145], v[146:147], v[188:189]
	v_pk_fma_f32 v[134:135], v[132:133], v[134:135], v[190:191]
	v_pk_fma_f32 v[146:147], v[144:145], v[146:147], v[190:191]
	v_pk_fma_f32 v[134:135], v[132:133], v[134:135], v[132:133]
	v_pk_fma_f32 v[146:147], v[144:145], v[146:147], v[144:145]
	v_pk_mul_f32 v[134:135], v[134:135], v[172:173]
	v_pk_mul_f32 v[146:147], v[146:147], v[172:173]
	v_pk_mul_f32 v[136:137], v[130:131], v[130:131]
	v_pk_mul_f32 v[148:149], v[142:143], v[142:143]
	v_exp_f32_e32 v134, v134
	v_exp_f32_e32 v146, v146
	v_exp_f32_e32 v135, v135
	v_exp_f32_e32 v147, v147
	v_pk_fma_f32 v[138:139], v[136:137], v[192:193], v[194:195]
	v_pk_fma_f32 v[150:151], v[148:149], v[192:193], v[194:195]
	v_pk_fma_f32 v[138:139], v[136:137], v[138:139], v[196:197]
	v_pk_fma_f32 v[150:151], v[148:149], v[150:151], v[196:197]
	v_pk_fma_f32 v[138:139], v[136:137], v[138:139], v[224:225]
	v_pk_fma_f32 v[150:151], v[148:149], v[150:151], v[224:225]
	v_pk_fma_f32 v[138:139], v[136:137], v[138:139], v[226:227]
	v_pk_fma_f32 v[150:151], v[148:149], v[150:151], v[226:227]
	v_pk_fma_f32 v[138:139], v[136:137], v[138:139], v[228:229]
	v_pk_fma_f32 v[150:151], v[148:149], v[150:151], v[228:229]
	v_pk_fma_f32 v[134:135], v[134:135], v[234:235], v[230:231]
	v_pk_fma_f32 v[146:147], v[146:147], v[234:235], v[230:231]
	v_pk_fma_f32 v[138:139], v[132:133], v[138:139], v[132:133]
	v_pk_fma_f32 v[150:151], v[144:145], v[150:151], v[144:145]
	v_pk_mul_f32 v[140:141], v[60:61], v[232:233]
	v_pk_mul_f32 v[152:153], v[62:63], v[232:233]
	v_cmp_ngt_f32_e32 vcc, 1.0, v132
	v_cmp_ngt_f32_e64 s[8:9], 1.0, v133
	v_readlane_b32 s6, v252, 33
	v_readlane_b32 s7, v252, 34
	v_cndmask_b32_e32 v138, v138, v134, vcc
	v_cndmask_b32_e64 v139, v139, v135, s[8:9]
	v_cmp_ngt_f32_e32 vcc, 1.0, v144
	v_cmp_ngt_f32_e64 s[8:9], 1.0, v145
	v_bfi_b32 v138, s37, v138, v130
	v_bfi_b32 v139, s37, v139, v131
	v_cndmask_b32_e32 v150, v150, v146, vcc
	v_cndmask_b32_e64 v151, v151, v147, s[8:9]
	v_pk_add_f32 v[138:139], v[138:139], v[230:231]
	v_bfi_b32 v150, s37, v150, v142
	v_bfi_b32 v151, s37, v151, v143
	v_pk_add_f32 v[150:151], v[150:151], v[230:231]
	v_pk_mul_f32 v[138:139], v[140:141], v[138:139]
	v_lshl_add_u64 v[60:61], s[6:7], 0, v[66:67]
	v_pk_mul_f32 v[150:151], v[152:153], v[150:151]
	v_lshl_add_u64 v[60:61], v[182:183], 1, v[60:61]
	v_cvt_pk_bf16_f32 v62, v138, v139
	v_cvt_pk_bf16_f32 v63, v150, v151
	v_mov_b32_e32 v236, v62
	v_mov_b32_e32 v237, v63

; DI void st_bf4(u16* p, float a, float b, float c, float d) { *(uint2*)p = make_uint2(pk2(a, b), pk2(c, d)); }
; DI float gelu_f(float x) { return 0.5f * x * (1.f + erff(x * 0.70710678118654752f)); }
; DI float silu_f(float x) { return x * __builtin_amdgcn_rcpf(1.f + __expf(-x)); }
;   template <int NT, int MT> DI void run(f32x4 (&acc)[NT][MT], int mb, int nb) const {
;     ...
;         if (n < 1024) {
;           st_bf4(abuf + (size_t)m * 1024 + n, v[0], v[1], v[2], v[3]);
;           float* dst = nullptr;
;           if (m < M_PROMPT) { int t = m & 8191; if (t >= 8177) dst = spp + ((size_t)((m >> 13) * 15 + (t - 8177))) * 1024 + n; }
;           else { int r = m - M_PROMPT; int s = r & 31; if (s >= 17) dst = sps + ((size_t)((r >> 5) * 15 + (s - 17))) * 1024 + n; }
;           if (dst) *(float4*)dst = make_float4(v[0], v[1], v[2], v[3]);
;         } else if (n < 3072) {
;           st_bf4(uvbuf + (size_t)m * 2048 + (n - 1024), gelu_f(v[0]), gelu_f(v[1]), gelu_f(v[2]), gelu_f(v[3]));
;         } else {
;           st_bf4(gatebuf + (size_t)m * 2048 + (n - 3072), silu_f(v[0]), silu_f(v[1]), silu_f(v[2]), silu_f(v[3]));
.LBB0_1337:
	s_or_saveexec_b64 s[46:47], s[46:47]
	v_ashrrev_i32_e32 v67, 31, v182
	v_mov_b32_e32 v66, v182
	s_xor_b64 exec, exec, s[46:47]
	s_cbranch_execz .LBB0_1339
	v_lshlrev_b64 v[70:71], 11, v[64:65]
	v_lshl_add_u64 v[70:71], s[96:97], 0, v[70:71]
	v_lshl_add_u64 v[70:71], v[66:67], 1, v[70:71]
	v_cvt_pk_bf16_f32 v60, v60, v61
	v_cvt_pk_bf16_f32 v61, v62, v63
	v_mov_b32_e32 v236, v60
	v_mov_b32_e32 v237, v61
.LBB0_1339:
	s_or_b64 exec, exec, s[46:47]
	v_or_b32_e32 v60, 16, v64
	v_ashrrev_i32_e32 v61, 31, v60
	s_and_saveexec_b64 s[6:7], s[40:41]
	s_xor_b64 s[46:47], exec, s[6:7]
	s_cbranch_execz .LBB0_1361
	v_lshlrev_b64 v[62:63], 12, v[60:61]
	s_and_saveexec_b64 s[6:7], s[38:39]
	s_xor_b64 s[48:49], exec, s[6:7]
	s_cbranch_execz .LBB0_1342
	v_mul_f32_e32 v69, 0xbfb8aa3b, v56
	v_exp_f32_e32 v69, v69
	v_readlane_b32 s6, v252, 35
	v_readlane_b32 s7, v252, 36
	v_add_f32_e32 v69, 1.0, v69
	v_rcp_f32_e32 v70, v69
	v_mul_f32_e32 v69, 0xbfb8aa3b, v57
	v_exp_f32_e32 v69, v69
	v_lshl_add_u64 v[62:63], s[6:7], 0, v[62:63]
	v_lshl_add_u64 v[62:63], v[182:183], 1, v[62:63]
	v_add_f32_e32 v69, 1.0, v69
	v_rcp_f32_e32 v71, v69
	v_mul_f32_e32 v69, 0xbfb8aa3b, v58
	v_exp_f32_e32 v69, v69
	v_pk_mul_f32 v[56:57], v[56:57], v[70:71]
	s_nop 0
	v_cvt_pk_bf16_f32 v56, v56, v57
	v_add_f32_e32 v69, 1.0, v69
	v_rcp_f32_e32 v70, v69
	v_mul_f32_e32 v69, 0xbfb8aa3b, v59
	v_exp_f32_e32 v69, v69
	s_nop 0
	v_add_f32_e32 v69, 1.0, v69
	v_rcp_f32_e32 v71, v69
	s_nop 0
	v_pk_mul_f32 v[58:59], v[58:59], v[70:71]
	s_nop 0
	v_cvt_pk_bf16_f32 v57, v58, v59
	v_add_co_u32_e32 v58, vcc, 0xfffff000, v62
	s_nop 1
	v_addc_co_u32_e32 v59, vcc, -1, v63, vcc
	v_mov_b32_e32 v240, v56
	v_mov_b32_e32 v241, v57
.LBB0_1342:
	s_andn2_saveexec_b64 s[48:49], s[48:49]
	s_cbranch_execz .LBB0_1360
	v_pk_mul_f32 v[130:131], v[56:57], v[170:171]
	v_pk_mul_f32 v[142:143], v[58:59], v[170:171]
	v_and_b32_e32 v132, 0x7fffffff, v130
	v_and_b32_e32 v144, 0x7fffffff, v142
	v_and_b32_e32 v133, 0x7fffffff, v131
	v_and_b32_e32 v145, 0x7fffffff, v143
	v_pk_fma_f32 v[134:135], v[132:133], v[174:175], v[176:177]
	v_pk_fma_f32 v[146:147], v[144:145], v[174:175], v[176:177]
	v_pk_fma_f32 v[134:135], v[132:133], v[134:135], v[178:179]
	v_pk_fma_f32 v[146:147], v[144:145], v[146:147], v[178:179]
	v_pk_fma_f32 v[134:135], v[132:133], v[134:135], v[180:181]
	v_pk_fma_f32 v[146:147], v[144:145], v[146:147], v[180:181]
	v_pk_fma_f32 v[134:135], v[132:133], v[134:135], v[186:187]
	v_pk_fma_f32 v[146:147], v[144:145], v[146:147], v[186:187]
	v_pk_fma_f32 v[134:135], v[132:133], v[134:135], v[188:189]
	v_pk_fma_f32 v[146:147], v[144:145], v[146:147], v[188:189]
	v_pk_fma_f32 v[134:135], v[132:133], v[134:135], v[190:191]
	v_pk_fma_f32 v[146:147], v[144:145], v[146:147], v[190:191]
	v_pk_fma_f32 v[134:135], v[132:133], v[134:135], v[132:133]
	v_pk_fma_f32 v[146:147], v[144:145], v[146:147], v[144:145]
	v_pk_mul_f32 v[134:135], v[134:135], v[172:173]
	v_pk_mul_f32 v[146:147], v[146:147], v[172:173]
	v_pk_mul_f32 v[136:137], v[130:131], v[130:131]
	v_pk_mul_f32 v[148:149], v[142:143], v[142:143]
	v_exp_f32_e32 v134, v134
	v_exp_f32_e32 v146, v146
	v_exp_f32_e32 v135, v135
	v_exp_f32_e32 v147, v147
	v_pk_fma_f32 v[138:139], v[136:137], v[192:193], v[194:195]
	v_pk_fma_f32 v[150:151], v[148:149], v[192:193], v[194:195]
	v_pk_fma_f32 v[138:139], v[136:137], v[138:139], v[196:197]
	v_pk_fma_f32 v[150:151], v[148:149], v[150:151], v[196:197]
	v_pk_fma_f32 v[138:139], v[136:137], v[138:139], v[224:225]
	v_pk_fma_f32 v[150:151], v[148:149], v[150:151], v[224:225]
	v_pk_fma_f32 v[138:139], v[136:137], v[138:139], v[226:227]
	v_pk_fma_f32 v[150:151], v[148:149], v[150:151], v[226:227]
	v_pk_fma_f32 v[138:139], v[136:137], v[138:139], v[228:229]
	v_pk_fma_f32 v[150:151], v[148:149], v[150:151], v[228:229]
	v_pk_fma_f32 v[134:135], v[134:135], v[234:235], v[230:231]
	v_pk_fma_f32 v[146:147], v[146:147], v[234:235], v[230:231]
	v_pk_fma_f32 v[138:139], v[132:133], v[138:139], v[132:133]
	v_pk_fma_f32 v[150:151], v[144:145], v[150:151], v[144:145]
	v_pk_mul_f32 v[140:141], v[56:57], v[232:233]
	v_pk_mul_f32 v[152:153], v[58:59], v[232:233]
	v_cmp_ngt_f32_e32 vcc, 1.0, v132
	v_cmp_ngt_f32_e64 s[8:9], 1.0, v133
	v_readlane_b32 s6, v252, 33
	v_readlane_b32 s7, v252, 34
	v_cndmask_b32_e32 v138, v138, v134, vcc
	v_cndmask_b32_e64 v139, v139, v135, s[8:9]
	v_cmp_ngt_f32_e32 vcc, 1.0, v144
	v_cmp_ngt_f32_e64 s[8:9], 1.0, v145
	v_bfi_b32 v138, s37, v138, v130
	v_bfi_b32 v139, s37, v139, v131
	v_cndmask_b32_e32 v150, v150, v146, vcc
	v_cndmask_b32_e64 v151, v151, v147, s[8:9]
	v_pk_add_f32 v[138:139], v[138:139], v[230:231]
	v_bfi_b32 v150, s37, v150, v142
	v_bfi_b32 v151, s37, v151, v143
	v_pk_add_f32 v[150:151], v[150:151], v[230:231]
	v_pk_mul_f32 v[138:139], v[140:141], v[138:139]
	v_lshl_add_u64 v[56:57], s[6:7], 0, v[62:63]
	v_pk_mul_f32 v[150:151], v[152:153], v[150:151]
	v_lshl_add_u64 v[56:57], v[182:183], 1, v[56:57]
	v_cvt_pk_bf16_f32 v58, v138, v139
	v_cvt_pk_bf16_f32 v59, v150, v151
	v_mov_b32_e32 v240, v58
	v_mov_b32_e32 v241, v59

; DI void st_bf4(u16* p, float a, float b, float c, float d) { *(uint2*)p = make_uint2(pk2(a, b), pk2(c, d)); }
;   template <int NT, int MT> DI void run(f32x4 (&acc)[NT][MT], int mb, int nb) const {
;     ...
;         if (n < 1024) {
;           st_bf4(abuf + (size_t)m * 1024 + n, v[0], v[1], v[2], v[3]);
;           float* dst = nullptr;
;           if (m < M_PROMPT) { int t = m & 8191; if (t >= 8177) dst = spp + ((size_t)((m >> 13) * 15 + (t - 8177))) * 1024 + n; }
;           else { int r = m - M_PROMPT; int s = r & 31; if (s >= 17) dst = sps + ((size_t)((r >> 5) * 15 + (s - 17))) * 1024 + n; }
;           if (dst) *(float4*)dst = make_float4(v[0], v[1], v[2], v[3]);
.LBB0_1361:
	s_andn2_saveexec_b64 s[46:47], s[46:47]
	s_cbranch_execz .LBB0_1369
	v_lshlrev_b64 v[62:63], 11, v[60:61]
	v_lshl_add_u64 v[62:63], s[96:97], 0, v[62:63]
	v_lshl_add_u64 v[62:63], v[66:67], 1, v[62:63]
	v_cvt_pk_bf16_f32 v70, v56, v57
	v_cvt_pk_bf16_f32 v71, v58, v59
	s_movk_i32 s5, 0x3fef
	v_mov_b32_e32 v240, v70
	v_mov_b32_e32 v241, v71
	v_cmp_lt_i32_e32 vcc, s5, v64
	v_mov_b64_e32 v[62:63], 0
	s_and_saveexec_b64 s[48:49], vcc
	s_cbranch_execz .LBB0_1366
	v_and_b32_e32 v69, 31, v60
	v_cmp_ne_u32_e32 vcc, 16, v69
	v_mov_b64_e32 v[62:63], 0
	s_and_saveexec_b64 s[50:51], vcc
	s_cbranch_execz .LBB0_1365
	v_add_u32_e32 v62, 0xffffc010, v68
	v_lshrrev_b32_e32 v62, 5, v62
	v_mul_lo_u32 v62, v62, 15
	s_movk_i32 s5, 0xffef
	v_add3_u32 v62, v69, v62, s5
	v_mov_b32_e32 v63, v183
	v_readlane_b32 s6, v253, 19
	v_lshlrev_b64 v[62:63], 12, v[62:63]
	v_readlane_b32 s7, v253, 20
	s_nop 1
	v_lshl_add_u64 v[62:63], s[6:7], 0, v[62:63]
	v_lshl_add_u64 v[62:63], v[66:67], 2, v[62:63]

; DI void st_bf4(u16* p, float a, float b, float c, float d) { *(uint2*)p = make_uint2(pk2(a, b), pk2(c, d)); }
; DI float gelu_f(float x) { return 0.5f * x * (1.f + erff(x * 0.70710678118654752f)); }
; DI float silu_f(float x) { return x * __builtin_amdgcn_rcpf(1.f + __expf(-x)); }
;   template <int NT, int MT> DI void run(f32x4 (&acc)[NT][MT], int mb, int nb) const {
;     ...
;         } else if (n < 3072) {
;           st_bf4(uvbuf + (size_t)m * 2048 + (n - 1024), gelu_f(v[0]), gelu_f(v[1]), gelu_f(v[2]), gelu_f(v[3]));
;         } else {
;           st_bf4(gatebuf + (size_t)m * 2048 + (n - 3072), silu_f(v[0]), silu_f(v[1]), silu_f(v[2]), silu_f(v[3]));
.LBB0_1369:
	s_or_b64 exec, exec, s[46:47]
	v_or_b32_e32 v56, 32, v64
	v_ashrrev_i32_e32 v57, 31, v56
	s_and_saveexec_b64 s[6:7], s[40:41]
	s_xor_b64 s[46:47], exec, s[6:7]
	s_cbranch_execz .LBB0_1391
	v_lshlrev_b64 v[58:59], 12, v[56:57]
	s_and_saveexec_b64 s[6:7], s[38:39]
	s_xor_b64 s[48:49], exec, s[6:7]
	s_cbranch_execz .LBB0_1372
	v_mul_f32_e32 v62, 0xbfb8aa3b, v52
	v_mul_f32_e32 v63, 0xbfb8aa3b, v53
	v_exp_f32_e32 v62, v62
	v_exp_f32_e32 v63, v63
	v_readlane_b32 s6, v252, 35
	v_readlane_b32 s7, v252, 36
	v_add_f32_e32 v62, 1.0, v62
	v_add_f32_e32 v63, 1.0, v63
	v_rcp_f32_e32 v62, v62
	v_rcp_f32_e32 v63, v63
	v_lshl_add_u64 v[58:59], s[6:7], 0, v[58:59]
	v_lshl_add_u64 v[58:59], v[182:183], 1, v[58:59]
	v_pk_mul_f32 v[52:53], v[52:53], v[62:63]
	v_mul_f32_e32 v62, 0xbfb8aa3b, v54
	v_mul_f32_e32 v63, 0xbfb8aa3b, v55
	v_exp_f32_e32 v62, v62
	v_exp_f32_e32 v63, v63
	v_cvt_pk_bf16_f32 v52, v52, v53
	v_add_f32_e32 v62, 1.0, v62
	v_add_f32_e32 v63, 1.0, v63
	v_rcp_f32_e32 v62, v62
	v_rcp_f32_e32 v63, v63
	s_nop 0
	v_pk_mul_f32 v[54:55], v[54:55], v[62:63]
	s_nop 0
	v_cvt_pk_bf16_f32 v53, v54, v55
	v_add_co_u32_e32 v54, vcc, 0xfffff000, v58
	s_nop 1
	v_addc_co_u32_e32 v55, vcc, -1, v59, vcc
	v_mov_b32_e32 v244, v52
	v_mov_b32_e32 v245, v53
.LBB0_1372:
	s_andn2_saveexec_b64 s[48:49], s[48:49]
	s_cbranch_execz .LBB0_1390
	v_pk_mul_f32 v[130:131], v[52:53], v[170:171]
	v_pk_mul_f32 v[142:143], v[54:55], v[170:171]
	v_and_b32_e32 v132, 0x7fffffff, v130
	v_and_b32_e32 v144, 0x7fffffff, v142
	v_and_b32_e32 v133, 0x7fffffff, v131
	v_and_b32_e32 v145, 0x7fffffff, v143
	v_pk_fma_f32 v[134:135], v[132:133], v[174:175], v[176:177]
	v_pk_fma_f32 v[146:147], v[144:145], v[174:175], v[176:177]
	v_pk_fma_f32 v[134:135], v[132:133], v[134:135], v[178:179]
	v_pk_fma_f32 v[146:147], v[144:145], v[146:147], v[178:179]
	v_pk_fma_f32 v[134:135], v[132:133], v[134:135], v[180:181]
	v_pk_fma_f32 v[146:147], v[144:145], v[146:147], v[180:181]
	v_pk_fma_f32 v[134:135], v[132:133], v[134:135], v[186:187]
	v_pk_fma_f32 v[146:147], v[144:145], v[146:147], v[186:187]
	v_pk_fma_f32 v[134:135], v[132:133], v[134:135], v[188:189]
	v_pk_fma_f32 v[146:147], v[144:145], v[146:147], v[188:189]
	v_pk_fma_f32 v[134:135], v[132:133], v[134:135], v[190:191]
	v_pk_fma_f32 v[146:147], v[144:145], v[146:147], v[190:191]
	v_pk_fma_f32 v[134:135], v[132:133], v[134:135], v[132:133]
	v_pk_fma_f32 v[146:147], v[144:145], v[146:147], v[144:145]
	v_pk_mul_f32 v[134:135], v[134:135], v[172:173]
	v_pk_mul_f32 v[146:147], v[146:147], v[172:173]
	v_pk_mul_f32 v[136:137], v[130:131], v[130:131]
	v_pk_mul_f32 v[148:149], v[142:143], v[142:143]
	v_exp_f32_e32 v134, v134
	v_exp_f32_e32 v146, v146
	v_exp_f32_e32 v135, v135
	v_exp_f32_e32 v147, v147
	v_pk_fma_f32 v[138:139], v[136:137], v[192:193], v[194:195]
	v_pk_fma_f32 v[150:151], v[148:149], v[192:193], v[194:195]
	v_pk_fma_f32 v[138:139], v[136:137], v[138:139], v[196:197]
	v_pk_fma_f32 v[150:151], v[148:149], v[150:151], v[196:197]
	v_pk_fma_f32 v[138:139], v[136:137], v[138:139], v[224:225]
	v_pk_fma_f32 v[150:151], v[148:149], v[150:151], v[224:225]
	v_pk_fma_f32 v[138:139], v[136:137], v[138:139], v[226:227]
	v_pk_fma_f32 v[150:151], v[148:149], v[150:151], v[226:227]
	v_pk_fma_f32 v[138:139], v[136:137], v[138:139], v[228:229]
	v_pk_fma_f32 v[150:151], v[148:149], v[150:151], v[228:229]
	v_pk_fma_f32 v[134:135], v[134:135], v[234:235], v[230:231]
	v_pk_fma_f32 v[146:147], v[146:147], v[234:235], v[230:231]
	v_pk_fma_f32 v[138:139], v[132:133], v[138:139], v[132:133]
	v_pk_fma_f32 v[150:151], v[144:145], v[150:151], v[144:145]
	v_pk_mul_f32 v[140:141], v[52:53], v[232:233]
	v_pk_mul_f32 v[152:153], v[54:55], v[232:233]
	v_cmp_ngt_f32_e32 vcc, 1.0, v132
	v_cmp_ngt_f32_e64 s[8:9], 1.0, v133
	v_readlane_b32 s6, v252, 33
	v_readlane_b32 s7, v252, 34
	v_cndmask_b32_e32 v138, v138, v134, vcc
	v_cndmask_b32_e64 v139, v139, v135, s[8:9]
	v_cmp_ngt_f32_e32 vcc, 1.0, v144
	v_cmp_ngt_f32_e64 s[8:9], 1.0, v145
	v_bfi_b32 v138, s37, v138, v130
	v_bfi_b32 v139, s37, v139, v131
	v_cndmask_b32_e32 v150, v150, v146, vcc
	v_cndmask_b32_e64 v151, v151, v147, s[8:9]
	v_pk_add_f32 v[138:139], v[138:139], v[230:231]
	v_bfi_b32 v150, s37, v150, v142
	v_bfi_b32 v151, s37, v151, v143
	v_pk_add_f32 v[150:151], v[150:151], v[230:231]
	v_pk_mul_f32 v[138:139], v[140:141], v[138:139]
	v_lshl_add_u64 v[52:53], s[6:7], 0, v[58:59]
	v_pk_mul_f32 v[150:151], v[152:153], v[150:151]
	v_lshl_add_u64 v[52:53], v[182:183], 1, v[52:53]
	v_cvt_pk_bf16_f32 v54, v138, v139
	v_cvt_pk_bf16_f32 v55, v150, v151
	v_mov_b32_e32 v244, v54
	v_mov_b32_e32 v245, v55

; DI void st_bf4(u16* p, float a, float b, float c, float d) { *(uint2*)p = make_uint2(pk2(a, b), pk2(c, d)); }
; DI float gelu_f(float x) { return 0.5f * x * (1.f + erff(x * 0.70710678118654752f)); }
; DI float silu_f(float x) { return x * __builtin_amdgcn_rcpf(1.f + __expf(-x)); }
;   template <int NT, int MT> DI void run(f32x4 (&acc)[NT][MT], int mb, int nb) const {
;     ...
;         if (n < 1024) {
;           st_bf4(abuf + (size_t)m * 1024 + n, v[0], v[1], v[2], v[3]);
;           float* dst = nullptr;
;           if (m < M_PROMPT) { int t = m & 8191; if (t >= 8177) dst = spp + ((size_t)((m >> 13) * 15 + (t - 8177))) * 1024 + n; }
;           else { int r = m - M_PROMPT; int s = r & 31; if (s >= 17) dst = sps + ((size_t)((r >> 5) * 15 + (s - 17))) * 1024 + n; }
;           if (dst) *(float4*)dst = make_float4(v[0], v[1], v[2], v[3]);
;         } else if (n < 3072) {
;           st_bf4(uvbuf + (size_t)m * 2048 + (n - 1024), gelu_f(v[0]), gelu_f(v[1]), gelu_f(v[2]), gelu_f(v[3]));
;         } else {
;           st_bf4(gatebuf + (size_t)m * 2048 + (n - 3072), silu_f(v[0]), silu_f(v[1]), silu_f(v[2]), silu_f(v[3]));
.LBB0_1391:
	s_andn2_saveexec_b64 s[46:47], s[46:47]
	s_cbranch_execz .LBB0_1393
	v_lshlrev_b64 v[58:59], 11, v[56:57]
	v_lshl_add_u64 v[58:59], s[96:97], 0, v[58:59]
	v_lshl_add_u64 v[58:59], v[66:67], 1, v[58:59]
	v_cvt_pk_bf16_f32 v52, v52, v53
	v_cvt_pk_bf16_f32 v53, v54, v55
	v_mov_b32_e32 v244, v52
	v_mov_b32_e32 v245, v53
.LBB0_1393:
	s_or_b64 exec, exec, s[46:47]
	v_or_b32_e32 v52, 48, v64
	v_ashrrev_i32_e32 v53, 31, v52
	s_and_saveexec_b64 s[6:7], s[40:41]
	s_xor_b64 s[40:41], exec, s[6:7]
	s_cbranch_execz .LBB0_1415
	v_lshlrev_b64 v[54:55], 12, v[52:53]
	s_and_saveexec_b64 s[6:7], s[38:39]
	s_xor_b64 s[46:47], exec, s[6:7]
	s_cbranch_execz .LBB0_1396
	v_mul_f32_e32 v58, 0xbfb8aa3b, v48
	v_mul_f32_e32 v59, 0xbfb8aa3b, v49
	v_exp_f32_e32 v58, v58
	v_exp_f32_e32 v59, v59
	v_readlane_b32 s6, v252, 35
	v_readlane_b32 s7, v252, 36
	v_add_f32_e32 v58, 1.0, v58
	v_add_f32_e32 v59, 1.0, v59
	v_rcp_f32_e32 v58, v58
	v_rcp_f32_e32 v59, v59
	v_lshl_add_u64 v[54:55], s[6:7], 0, v[54:55]
	v_lshl_add_u64 v[54:55], v[182:183], 1, v[54:55]
	v_pk_mul_f32 v[48:49], v[48:49], v[58:59]
	v_mul_f32_e32 v58, 0xbfb8aa3b, v50
	v_mul_f32_e32 v59, 0xbfb8aa3b, v51
	v_exp_f32_e32 v58, v58
	v_exp_f32_e32 v59, v59
	v_cvt_pk_bf16_f32 v48, v48, v49
	v_add_f32_e32 v58, 1.0, v58
	v_add_f32_e32 v59, 1.0, v59
	v_rcp_f32_e32 v58, v58
	v_rcp_f32_e32 v59, v59
	s_nop 0
	v_pk_mul_f32 v[50:51], v[50:51], v[58:59]
	s_nop 0
	v_cvt_pk_bf16_f32 v49, v50, v51
	v_add_co_u32_e32 v50, vcc, 0xfffff000, v54
	s_nop 1
	v_addc_co_u32_e32 v51, vcc, -1, v55, vcc
	v_mov_b32_e32 v248, v48
	v_mov_b32_e32 v249, v49
.LBB0_1396:
	s_andn2_saveexec_b64 s[46:47], s[46:47]
	s_cbranch_execz .LBB0_1414
	v_pk_mul_f32 v[130:131], v[48:49], v[170:171]
	v_pk_mul_f32 v[142:143], v[50:51], v[170:171]
	v_and_b32_e32 v132, 0x7fffffff, v130
	v_and_b32_e32 v144, 0x7fffffff, v142
	v_and_b32_e32 v133, 0x7fffffff, v131
	v_and_b32_e32 v145, 0x7fffffff, v143
	v_pk_fma_f32 v[134:135], v[132:133], v[174:175], v[176:177]
	v_pk_fma_f32 v[146:147], v[144:145], v[174:175], v[176:177]
	v_pk_fma_f32 v[134:135], v[132:133], v[134:135], v[178:179]
	v_pk_fma_f32 v[146:147], v[144:145], v[146:147], v[178:179]
	v_pk_fma_f32 v[134:135], v[132:133], v[134:135], v[180:181]
	v_pk_fma_f32 v[146:147], v[144:145], v[146:147], v[180:181]
	v_pk_fma_f32 v[134:135], v[132:133], v[134:135], v[186:187]
	v_pk_fma_f32 v[146:147], v[144:145], v[146:147], v[186:187]
	v_pk_fma_f32 v[134:135], v[132:133], v[134:135], v[188:189]
	v_pk_fma_f32 v[146:147], v[144:145], v[146:147], v[188:189]
	v_pk_fma_f32 v[134:135], v[132:133], v[134:135], v[190:191]
	v_pk_fma_f32 v[146:147], v[144:145], v[146:147], v[190:191]
	v_pk_fma_f32 v[134:135], v[132:133], v[134:135], v[132:133]
	v_pk_fma_f32 v[146:147], v[144:145], v[146:147], v[144:145]
	v_pk_mul_f32 v[134:135], v[134:135], v[172:173]
	v_pk_mul_f32 v[146:147], v[146:147], v[172:173]
	v_pk_mul_f32 v[136:137], v[130:131], v[130:131]
	v_pk_mul_f32 v[148:149], v[142:143], v[142:143]
	v_exp_f32_e32 v134, v134
	v_exp_f32_e32 v146, v146
	v_exp_f32_e32 v135, v135
	v_exp_f32_e32 v147, v147
	v_pk_fma_f32 v[138:139], v[136:137], v[192:193], v[194:195]
	v_pk_fma_f32 v[150:151], v[148:149], v[192:193], v[194:195]
	v_pk_fma_f32 v[138:139], v[136:137], v[138:139], v[196:197]
	v_pk_fma_f32 v[150:151], v[148:149], v[150:151], v[196:197]
	v_pk_fma_f32 v[138:139], v[136:137], v[138:139], v[224:225]
	v_pk_fma_f32 v[150:151], v[148:149], v[150:151], v[224:225]
	v_pk_fma_f32 v[138:139], v[136:137], v[138:139], v[226:227]
	v_pk_fma_f32 v[150:151], v[148:149], v[150:151], v[226:227]
	v_pk_fma_f32 v[138:139], v[136:137], v[138:139], v[228:229]
	v_pk_fma_f32 v[150:151], v[148:149], v[150:151], v[228:229]
	v_pk_fma_f32 v[134:135], v[134:135], v[234:235], v[230:231]
	v_pk_fma_f32 v[146:147], v[146:147], v[234:235], v[230:231]
	v_pk_fma_f32 v[138:139], v[132:133], v[138:139], v[132:133]
	v_pk_fma_f32 v[150:151], v[144:145], v[150:151], v[144:145]
	v_pk_mul_f32 v[140:141], v[48:49], v[232:233]
	v_pk_mul_f32 v[152:153], v[50:51], v[232:233]
	v_cmp_ngt_f32_e32 vcc, 1.0, v132
	v_cmp_ngt_f32_e64 s[8:9], 1.0, v133
	v_readlane_b32 s6, v252, 33
	v_readlane_b32 s7, v252, 34
	v_cndmask_b32_e32 v138, v138, v134, vcc
	v_cndmask_b32_e64 v139, v139, v135, s[8:9]
	v_cmp_ngt_f32_e32 vcc, 1.0, v144
	v_cmp_ngt_f32_e64 s[8:9], 1.0, v145
	v_bfi_b32 v138, s37, v138, v130
	v_bfi_b32 v139, s37, v139, v131
	v_cndmask_b32_e32 v150, v150, v146, vcc
	v_cndmask_b32_e64 v151, v151, v147, s[8:9]
	v_pk_add_f32 v[138:139], v[138:139], v[230:231]
	v_bfi_b32 v150, s37, v150, v142
	v_bfi_b32 v151, s37, v151, v143
	v_pk_add_f32 v[150:151], v[150:151], v[230:231]
	v_pk_mul_f32 v[138:139], v[140:141], v[138:139]
	v_lshl_add_u64 v[48:49], s[6:7], 0, v[54:55]
	v_pk_mul_f32 v[150:151], v[152:153], v[150:151]
	v_lshl_add_u64 v[48:49], v[182:183], 1, v[48:49]
	v_cvt_pk_bf16_f32 v50, v138, v139
	v_cvt_pk_bf16_f32 v51, v150, v151
	v_mov_b32_e32 v248, v50
	v_mov_b32_e32 v249, v51

; DI void st_bf4(u16* p, float a, float b, float c, float d) { *(uint2*)p = make_uint2(pk2(a, b), pk2(c, d)); }
;   template <int NT, int MT> DI void run(f32x4 (&acc)[NT][MT], int mb, int nb) const {
;     ...
;         if (n < 1024) {
;           st_bf4(abuf + (size_t)m * 1024 + n, v[0], v[1], v[2], v[3]);
;           float* dst = nullptr;
;           if (m < M_PROMPT) { int t = m & 8191; if (t >= 8177) dst = spp + ((size_t)((m >> 13) * 15 + (t - 8177))) * 1024 + n; }
;           else { int r = m - M_PROMPT; int s = r & 31; if (s >= 17) dst = sps + ((size_t)((r >> 5) * 15 + (s - 17))) * 1024 + n; }
;           if (dst) *(float4*)dst = make_float4(v[0], v[1], v[2], v[3]);
.LBB0_1415:
	s_andn2_saveexec_b64 s[40:41], s[40:41]
	s_cbranch_execz .LBB0_1423
	v_lshlrev_b64 v[54:55], 11, v[52:53]
	v_lshl_add_u64 v[54:55], s[96:97], 0, v[54:55]
	s_movk_i32 s5, 0x3fcf
	v_lshl_add_u64 v[54:55], v[66:67], 1, v[54:55]
	v_cvt_pk_bf16_f32 v58, v48, v49
	v_cvt_pk_bf16_f32 v59, v50, v51
	v_cmp_lt_i32_e32 vcc, s5, v64
	v_mov_b32_e32 v248, v58
	v_mov_b32_e32 v249, v59
	s_and_saveexec_b64 s[6:7], vcc
	s_xor_b64 s[46:47], exec, s[6:7]
	s_cbranch_execz .LBB0_1745
	v_and_b32_e32 v58, 31, v52
	v_cmp_ne_u32_e32 vcc, 16, v58
	v_mov_b64_e32 v[54:55], 0
	s_and_saveexec_b64 s[48:49], vcc
	s_cbranch_execz .LBB0_1419
	v_add_u32_e32 v54, 0xffffc030, v68
	v_lshrrev_b32_e32 v54, 5, v54
	v_mul_lo_u32 v54, v54, 15
	s_movk_i32 s5, 0xffef
	v_add3_u32 v54, v58, v54, s5
	v_mov_b32_e32 v55, v183
	v_readlane_b32 s6, v253, 19
	v_lshlrev_b64 v[54:55], 12, v[54:55]
	v_readlane_b32 s7, v253, 20
	s_nop 1
	v_lshl_add_u64 v[54:55], s[6:7], 0, v[54:55]
	v_lshl_add_u64 v[54:55], v[66:67], 2, v[54:55]

; DI void st_bf4(u16* p, float a, float b, float c, float d) { *(uint2*)p = make_uint2(pk2(a, b), pk2(c, d)); }
; DI float gelu_f(float x) { return 0.5f * x * (1.f + erff(x * 0.70710678118654752f)); }
; DI float silu_f(float x) { return x * __builtin_amdgcn_rcpf(1.f + __expf(-x)); }
;   template <int NT, int MT> DI void run(f32x4 (&acc)[NT][MT], int mb, int nb) const {
;     ...
;         } else if (n < 3072) {
;           st_bf4(uvbuf + (size_t)m * 2048 + (n - 1024), gelu_f(v[0]), gelu_f(v[1]), gelu_f(v[2]), gelu_f(v[3]));
;         } else {
;           st_bf4(gatebuf + (size_t)m * 2048 + (n - 3072), silu_f(v[0]), silu_f(v[1]), silu_f(v[2]), silu_f(v[3]));
.LBB0_1423:
	s_or_b64 exec, exec, s[40:41]
	s_movk_i32 s5, 0x3ef
	v_cmp_lt_i32_e64 s[40:41], s5, v182
	s_and_saveexec_b64 s[6:7], s[40:41]
	s_xor_b64 s[46:47], exec, s[6:7]
	s_cbranch_execz .LBB0_1445
	v_lshlrev_b64 v[48:49], 12, v[64:65]
	s_and_saveexec_b64 s[6:7], s[38:39]
	s_xor_b64 s[48:49], exec, s[6:7]
	s_cbranch_execz .LBB0_1426
	v_mul_f32_e32 v50, 0xbfb8aa3b, v44
	v_mul_f32_e32 v51, 0xbfb8aa3b, v45
	v_exp_f32_e32 v50, v50
	v_exp_f32_e32 v51, v51
	v_readlane_b32 s6, v252, 35
	v_readlane_b32 s7, v252, 36
	v_add_f32_e32 v50, 1.0, v50
	v_add_f32_e32 v51, 1.0, v51
	v_rcp_f32_e32 v50, v50
	v_rcp_f32_e32 v51, v51
	v_lshl_add_u64 v[48:49], s[6:7], 0, v[48:49]
	v_lshl_add_u64 v[48:49], v[182:183], 1, v[48:49]
	v_pk_mul_f32 v[44:45], v[44:45], v[50:51]
	v_mul_f32_e32 v50, 0xbfb8aa3b, v46
	v_mul_f32_e32 v51, 0xbfb8aa3b, v47
	v_exp_f32_e32 v50, v50
	v_exp_f32_e32 v51, v51
	v_cvt_pk_bf16_f32 v44, v44, v45
	v_add_f32_e32 v50, 1.0, v50
	v_add_f32_e32 v51, 1.0, v51
	v_rcp_f32_e32 v50, v50
	v_rcp_f32_e32 v51, v51
	s_nop 0
	v_pk_mul_f32 v[46:47], v[46:47], v[50:51]
	s_nop 0
	v_cvt_pk_bf16_f32 v45, v46, v47
	v_add_co_u32_e32 v46, vcc, 0xfffff000, v48
	s_nop 1
	v_addc_co_u32_e32 v47, vcc, -1, v49, vcc
	v_mov_b32_e32 v238, v44
	v_mov_b32_e32 v239, v45
	v_lshl_add_u64 v[156:157], v[46:47], 0, v[154:155]
	s_nop 0
	v_permlane16_swap_b32_e32 v236, v238
	v_permlane16_swap_b32_e32 v237, v239
	global_store_dwordx4 v[156:157], v[236:239], off offset:-2048
.LBB0_1426:
	s_andn2_saveexec_b64 s[48:49], s[48:49]
	s_cbranch_execz .LBB0_1444
	v_pk_mul_f32 v[130:131], v[44:45], v[170:171]
	v_pk_mul_f32 v[142:143], v[46:47], v[170:171]
	v_and_b32_e32 v132, 0x7fffffff, v130
	v_and_b32_e32 v144, 0x7fffffff, v142
	v_and_b32_e32 v133, 0x7fffffff, v131
	v_and_b32_e32 v145, 0x7fffffff, v143
	v_pk_fma_f32 v[134:135], v[132:133], v[174:175], v[176:177]
	v_pk_fma_f32 v[146:147], v[144:145], v[174:175], v[176:177]
	v_pk_fma_f32 v[134:135], v[132:133], v[134:135], v[178:179]
	v_pk_fma_f32 v[146:147], v[144:145], v[146:147], v[178:179]
	v_pk_fma_f32 v[134:135], v[132:133], v[134:135], v[180:181]
	v_pk_fma_f32 v[146:147], v[144:145], v[146:147], v[180:181]
	v_pk_fma_f32 v[134:135], v[132:133], v[134:135], v[186:187]
	v_pk_fma_f32 v[146:147], v[144:145], v[146:147], v[186:187]
	v_pk_fma_f32 v[134:135], v[132:133], v[134:135], v[188:189]
	v_pk_fma_f32 v[146:147], v[144:145], v[146:147], v[188:189]
	v_pk_fma_f32 v[134:135], v[132:133], v[134:135], v[190:191]
	v_pk_fma_f32 v[146:147], v[144:145], v[146:147], v[190:191]
	v_pk_fma_f32 v[134:135], v[132:133], v[134:135], v[132:133]
	v_pk_fma_f32 v[146:147], v[144:145], v[146:147], v[144:145]
	v_pk_mul_f32 v[134:135], v[134:135], v[172:173]
	v_pk_mul_f32 v[146:147], v[146:147], v[172:173]
	v_pk_mul_f32 v[136:137], v[130:131], v[130:131]
	v_pk_mul_f32 v[148:149], v[142:143], v[142:143]
	v_exp_f32_e32 v134, v134
	v_exp_f32_e32 v146, v146
	v_exp_f32_e32 v135, v135
	v_exp_f32_e32 v147, v147
	v_pk_fma_f32 v[138:139], v[136:137], v[192:193], v[194:195]
	v_pk_fma_f32 v[150:151], v[148:149], v[192:193], v[194:195]
	v_pk_fma_f32 v[138:139], v[136:137], v[138:139], v[196:197]
	v_pk_fma_f32 v[150:151], v[148:149], v[150:151], v[196:197]
	v_pk_fma_f32 v[138:139], v[136:137], v[138:139], v[224:225]
	v_pk_fma_f32 v[150:151], v[148:149], v[150:151], v[224:225]
	v_pk_fma_f32 v[138:139], v[136:137], v[138:139], v[226:227]
	v_pk_fma_f32 v[150:151], v[148:149], v[150:151], v[226:227]
	v_pk_fma_f32 v[138:139], v[136:137], v[138:139], v[228:229]
	v_pk_fma_f32 v[150:151], v[148:149], v[150:151], v[228:229]
	v_pk_fma_f32 v[134:135], v[134:135], v[234:235], v[230:231]
	v_pk_fma_f32 v[146:147], v[146:147], v[234:235], v[230:231]
	v_pk_fma_f32 v[138:139], v[132:133], v[138:139], v[132:133]
	v_pk_fma_f32 v[150:151], v[144:145], v[150:151], v[144:145]
	v_pk_mul_f32 v[140:141], v[44:45], v[232:233]
	v_pk_mul_f32 v[152:153], v[46:47], v[232:233]
	v_cmp_ngt_f32_e32 vcc, 1.0, v132
	v_cmp_ngt_f32_e64 s[8:9], 1.0, v133
	v_readlane_b32 s6, v252, 33
	v_readlane_b32 s7, v252, 34
	v_cndmask_b32_e32 v138, v138, v134, vcc
	v_cndmask_b32_e64 v139, v139, v135, s[8:9]
	v_cmp_ngt_f32_e32 vcc, 1.0, v144
	v_cmp_ngt_f32_e64 s[8:9], 1.0, v145
	v_bfi_b32 v138, s37, v138, v130
	v_bfi_b32 v139, s37, v139, v131
	v_cndmask_b32_e32 v150, v150, v146, vcc
	v_cndmask_b32_e64 v151, v151, v147, s[8:9]
	v_pk_add_f32 v[138:139], v[138:139], v[230:231]
	v_bfi_b32 v150, s37, v150, v142
	v_bfi_b32 v151, s37, v151, v143
	v_pk_add_f32 v[150:151], v[150:151], v[230:231]
	v_pk_mul_f32 v[138:139], v[140:141], v[138:139]
	v_lshl_add_u64 v[44:45], s[6:7], 0, v[48:49]
	v_pk_mul_f32 v[150:151], v[152:153], v[150:151]
	v_lshl_add_u64 v[44:45], v[182:183], 1, v[44:45]
	v_cvt_pk_bf16_f32 v46, v138, v139
	v_cvt_pk_bf16_f32 v47, v150, v151
	v_mov_b32_e32 v238, v46
	v_mov_b32_e32 v239, v47
	v_lshl_add_u64 v[156:157], v[44:45], 0, v[154:155]
	s_nop 0
	v_permlane16_swap_b32_e32 v236, v238
	v_permlane16_swap_b32_e32 v237, v239
	global_store_dwordx4 v[156:157], v[236:239], off offset:-2048

; DI void st_bf4(u16* p, float a, float b, float c, float d) { *(uint2*)p = make_uint2(pk2(a, b), pk2(c, d)); }
; DI float gelu_f(float x) { return 0.5f * x * (1.f + erff(x * 0.70710678118654752f)); }
; DI float silu_f(float x) { return x * __builtin_amdgcn_rcpf(1.f + __expf(-x)); }
;   template <int NT, int MT> DI void run(f32x4 (&acc)[NT][MT], int mb, int nb) const {
;     ...
;         if (n < 1024) {
;           st_bf4(abuf + (size_t)m * 1024 + n, v[0], v[1], v[2], v[3]);
;           float* dst = nullptr;
;           if (m < M_PROMPT) { int t = m & 8191; if (t >= 8177) dst = spp + ((size_t)((m >> 13) * 15 + (t - 8177))) * 1024 + n; }
;           else { int r = m - M_PROMPT; int s = r & 31; if (s >= 17) dst = sps + ((size_t)((r >> 5) * 15 + (s - 17))) * 1024 + n; }
;           if (dst) *(float4*)dst = make_float4(v[0], v[1], v[2], v[3]);
;         } else if (n < 3072) {
;           st_bf4(uvbuf + (size_t)m * 2048 + (n - 1024), gelu_f(v[0]), gelu_f(v[1]), gelu_f(v[2]), gelu_f(v[3]));
;         } else {
;           st_bf4(gatebuf + (size_t)m * 2048 + (n - 3072), silu_f(v[0]), silu_f(v[1]), silu_f(v[2]), silu_f(v[3]));
.LBB0_1445:
	s_andn2_saveexec_b64 s[46:47], s[46:47]
	s_cbranch_execz .LBB0_1447
	v_lshlrev_b64 v[48:49], 11, v[64:65]
	v_lshl_add_u64 v[48:49], s[96:97], 0, v[48:49]
	v_lshl_add_u64 v[48:49], v[66:67], 1, v[48:49]
	v_cvt_pk_bf16_f32 v44, v44, v45
	v_cvt_pk_bf16_f32 v45, v46, v47
	v_mov_b32_e32 v238, v44
	v_mov_b32_e32 v239, v45
	v_lshl_add_u64 v[156:157], v[48:49], 0, v[154:155]
	s_nop 0
	v_permlane16_swap_b32_e32 v236, v238
	v_permlane16_swap_b32_e32 v237, v239
	global_store_dwordx4 v[156:157], v[236:239], off offset:0
.LBB0_1447:
	s_or_b64 exec, exec, s[46:47]
	s_and_saveexec_b64 s[6:7], s[40:41]
	s_xor_b64 s[46:47], exec, s[6:7]
	s_cbranch_execz .LBB0_1469
	v_lshlrev_b64 v[44:45], 12, v[60:61]
	s_and_saveexec_b64 s[6:7], s[38:39]
	s_xor_b64 s[48:49], exec, s[6:7]
	s_cbranch_execz .LBB0_1450
	v_mul_f32_e32 v46, 0xbfb8aa3b, v40
	v_mul_f32_e32 v47, 0xbfb8aa3b, v41
	v_exp_f32_e32 v46, v46
	v_exp_f32_e32 v47, v47
	v_readlane_b32 s6, v252, 35
	v_readlane_b32 s7, v252, 36
	v_add_f32_e32 v46, 1.0, v46
	v_add_f32_e32 v47, 1.0, v47
	v_rcp_f32_e32 v46, v46
	v_rcp_f32_e32 v47, v47
	v_lshl_add_u64 v[44:45], s[6:7], 0, v[44:45]
	v_lshl_add_u64 v[44:45], v[182:183], 1, v[44:45]
	v_pk_mul_f32 v[40:41], v[40:41], v[46:47]
	v_mul_f32_e32 v46, 0xbfb8aa3b, v42
	v_mul_f32_e32 v47, 0xbfb8aa3b, v43
	v_exp_f32_e32 v46, v46
	v_exp_f32_e32 v47, v47
	v_cvt_pk_bf16_f32 v40, v40, v41
	v_add_f32_e32 v46, 1.0, v46
	v_add_f32_e32 v47, 1.0, v47
	v_rcp_f32_e32 v46, v46
	v_rcp_f32_e32 v47, v47
	s_nop 0
	v_pk_mul_f32 v[42:43], v[42:43], v[46:47]
	s_nop 0
	v_cvt_pk_bf16_f32 v41, v42, v43
	v_add_co_u32_e32 v42, vcc, 0xfffff000, v44
	s_nop 1
	v_addc_co_u32_e32 v43, vcc, -1, v45, vcc
	v_mov_b32_e32 v242, v40
	v_mov_b32_e32 v243, v41
	v_lshl_add_u64 v[156:157], v[42:43], 0, v[154:155]
	s_nop 0
	v_permlane16_swap_b32_e32 v240, v242
	v_permlane16_swap_b32_e32 v241, v243
	global_store_dwordx4 v[156:157], v[240:243], off offset:-2048
.LBB0_1450:
	s_andn2_saveexec_b64 s[48:49], s[48:49]
	s_cbranch_execz .LBB0_1468
	v_pk_mul_f32 v[130:131], v[40:41], v[170:171]
	v_pk_mul_f32 v[142:143], v[42:43], v[170:171]
	v_and_b32_e32 v132, 0x7fffffff, v130
	v_and_b32_e32 v144, 0x7fffffff, v142
	v_and_b32_e32 v133, 0x7fffffff, v131
	v_and_b32_e32 v145, 0x7fffffff, v143
	v_pk_fma_f32 v[134:135], v[132:133], v[174:175], v[176:177]
	v_pk_fma_f32 v[146:147], v[144:145], v[174:175], v[176:177]
	v_pk_fma_f32 v[134:135], v[132:133], v[134:135], v[178:179]
	v_pk_fma_f32 v[146:147], v[144:145], v[146:147], v[178:179]
	v_pk_fma_f32 v[134:135], v[132:133], v[134:135], v[180:181]
	v_pk_fma_f32 v[146:147], v[144:145], v[146:147], v[180:181]
	v_pk_fma_f32 v[134:135], v[132:133], v[134:135], v[186:187]
	v_pk_fma_f32 v[146:147], v[144:145], v[146:147], v[186:187]
	v_pk_fma_f32 v[134:135], v[132:133], v[134:135], v[188:189]
	v_pk_fma_f32 v[146:147], v[144:145], v[146:147], v[188:189]
	v_pk_fma_f32 v[134:135], v[132:133], v[134:135], v[190:191]
	v_pk_fma_f32 v[146:147], v[144:145], v[146:147], v[190:191]
	v_pk_fma_f32 v[134:135], v[132:133], v[134:135], v[132:133]
	v_pk_fma_f32 v[146:147], v[144:145], v[146:147], v[144:145]
	v_pk_mul_f32 v[134:135], v[134:135], v[172:173]
	v_pk_mul_f32 v[146:147], v[146:147], v[172:173]
	v_pk_mul_f32 v[136:137], v[130:131], v[130:131]
	v_pk_mul_f32 v[148:149], v[142:143], v[142:143]
	v_exp_f32_e32 v134, v134
	v_exp_f32_e32 v146, v146
	v_exp_f32_e32 v135, v135
	v_exp_f32_e32 v147, v147
	v_pk_fma_f32 v[138:139], v[136:137], v[192:193], v[194:195]
	v_pk_fma_f32 v[150:151], v[148:149], v[192:193], v[194:195]
	v_pk_fma_f32 v[138:139], v[136:137], v[138:139], v[196:197]
	v_pk_fma_f32 v[150:151], v[148:149], v[150:151], v[196:197]
	v_pk_fma_f32 v[138:139], v[136:137], v[138:139], v[224:225]
	v_pk_fma_f32 v[150:151], v[148:149], v[150:151], v[224:225]
	v_pk_fma_f32 v[138:139], v[136:137], v[138:139], v[226:227]
	v_pk_fma_f32 v[150:151], v[148:149], v[150:151], v[226:227]
	v_pk_fma_f32 v[138:139], v[136:137], v[138:139], v[228:229]
	v_pk_fma_f32 v[150:151], v[148:149], v[150:151], v[228:229]
	v_pk_fma_f32 v[134:135], v[134:135], v[234:235], v[230:231]
	v_pk_fma_f32 v[146:147], v[146:147], v[234:235], v[230:231]
	v_pk_fma_f32 v[138:139], v[132:133], v[138:139], v[132:133]
	v_pk_fma_f32 v[150:151], v[144:145], v[150:151], v[144:145]
	v_pk_mul_f32 v[140:141], v[40:41], v[232:233]
	v_pk_mul_f32 v[152:153], v[42:43], v[232:233]
	v_cmp_ngt_f32_e32 vcc, 1.0, v132
	v_cmp_ngt_f32_e64 s[8:9], 1.0, v133
	v_readlane_b32 s6, v252, 33
	v_readlane_b32 s7, v252, 34
	v_cndmask_b32_e32 v138, v138, v134, vcc
	v_cndmask_b32_e64 v139, v139, v135, s[8:9]
	v_cmp_ngt_f32_e32 vcc, 1.0, v144
	v_cmp_ngt_f32_e64 s[8:9], 1.0, v145
	v_bfi_b32 v138, s37, v138, v130
	v_bfi_b32 v139, s37, v139, v131
	v_cndmask_b32_e32 v150, v150, v146, vcc
	v_cndmask_b32_e64 v151, v151, v147, s[8:9]
	v_pk_add_f32 v[138:139], v[138:139], v[230:231]
	v_bfi_b32 v150, s37, v150, v142
	v_bfi_b32 v151, s37, v151, v143
	v_pk_add_f32 v[150:151], v[150:151], v[230:231]
	v_pk_mul_f32 v[138:139], v[140:141], v[138:139]
	v_lshl_add_u64 v[40:41], s[6:7], 0, v[44:45]
	v_pk_mul_f32 v[150:151], v[152:153], v[150:151]
	v_lshl_add_u64 v[40:41], v[182:183], 1, v[40:41]
	v_cvt_pk_bf16_f32 v42, v138, v139
	v_cvt_pk_bf16_f32 v43, v150, v151
	v_mov_b32_e32 v242, v42
	v_mov_b32_e32 v243, v43
	v_lshl_add_u64 v[156:157], v[40:41], 0, v[154:155]
	s_nop 0
	v_permlane16_swap_b32_e32 v240, v242
	v_permlane16_swap_b32_e32 v241, v243
	global_store_dwordx4 v[156:157], v[240:243], off offset:-2048

; DI void st_bf4(u16* p, float a, float b, float c, float d) { *(uint2*)p = make_uint2(pk2(a, b), pk2(c, d)); }
;   template <int NT, int MT> DI void run(f32x4 (&acc)[NT][MT], int mb, int nb) const {
;     ...
;         if (n < 1024) {
;           st_bf4(abuf + (size_t)m * 1024 + n, v[0], v[1], v[2], v[3]);
;           float* dst = nullptr;
;           if (m < M_PROMPT) { int t = m & 8191; if (t >= 8177) dst = spp + ((size_t)((m >> 13) * 15 + (t - 8177))) * 1024 + n; }
;           else { int r = m - M_PROMPT; int s = r & 31; if (s >= 17) dst = sps + ((size_t)((r >> 5) * 15 + (s - 17))) * 1024 + n; }
;           if (dst) *(float4*)dst = make_float4(v[0], v[1], v[2], v[3]);
.LBB0_1469:
	s_andn2_saveexec_b64 s[46:47], s[46:47]
	s_cbranch_execz .LBB0_1477
	v_lshlrev_b64 v[44:45], 11, v[60:61]
	v_lshl_add_u64 v[44:45], s[96:97], 0, v[44:45]
	v_lshl_add_u64 v[44:45], v[66:67], 1, v[44:45]
	v_cvt_pk_bf16_f32 v46, v40, v41
	v_cvt_pk_bf16_f32 v47, v42, v43
	s_movk_i32 s5, 0x3fef
	v_mov_b32_e32 v242, v46
	v_mov_b32_e32 v243, v47
	v_lshl_add_u64 v[156:157], v[44:45], 0, v[154:155]
	s_nop 0
	v_permlane16_swap_b32_e32 v240, v242
	v_permlane16_swap_b32_e32 v241, v243
	global_store_dwordx4 v[156:157], v[240:243], off offset:0
	v_cmp_lt_i32_e32 vcc, s5, v64
	v_mov_b64_e32 v[44:45], 0
	s_and_saveexec_b64 s[48:49], vcc
	s_cbranch_execz .LBB0_1474
	v_and_b32_e32 v46, 31, v60
	v_cmp_ne_u32_e32 vcc, 16, v46
	v_mov_b64_e32 v[44:45], 0
	s_and_saveexec_b64 s[50:51], vcc
	s_cbranch_execz .LBB0_1473
	v_add_u32_e32 v44, 0xffffc010, v68
	v_lshrrev_b32_e32 v44, 5, v44
	v_mul_lo_u32 v44, v44, 15
	s_movk_i32 s5, 0xffef
	v_add3_u32 v44, v46, v44, s5
	v_mov_b32_e32 v45, v183
	v_readlane_b32 s6, v253, 19
	v_lshlrev_b64 v[44:45], 12, v[44:45]
	v_readlane_b32 s7, v253, 20
	s_nop 1
	v_lshl_add_u64 v[44:45], s[6:7], 0, v[44:45]
	v_lshl_add_u64 v[44:45], v[66:67], 2, v[44:45]
	v_lshl_add_u64 v[44:45], v[44:45], 0, 64

; DI void st_bf4(u16* p, float a, float b, float c, float d) { *(uint2*)p = make_uint2(pk2(a, b), pk2(c, d)); }
; DI float gelu_f(float x) { return 0.5f * x * (1.f + erff(x * 0.70710678118654752f)); }
; DI float silu_f(float x) { return x * __builtin_amdgcn_rcpf(1.f + __expf(-x)); }
;   template <int NT, int MT> DI void run(f32x4 (&acc)[NT][MT], int mb, int nb) const {
;     ...
;         } else if (n < 3072) {
;           st_bf4(uvbuf + (size_t)m * 2048 + (n - 1024), gelu_f(v[0]), gelu_f(v[1]), gelu_f(v[2]), gelu_f(v[3]));
;         } else {
;           st_bf4(gatebuf + (size_t)m * 2048 + (n - 3072), silu_f(v[0]), silu_f(v[1]), silu_f(v[2]), silu_f(v[3]));
.LBB0_1477:
	s_or_b64 exec, exec, s[46:47]
	s_and_saveexec_b64 s[6:7], s[40:41]
	s_xor_b64 s[46:47], exec, s[6:7]
	s_cbranch_execz .LBB0_1499
	v_lshlrev_b64 v[40:41], 12, v[56:57]
	s_and_saveexec_b64 s[6:7], s[38:39]
	s_xor_b64 s[48:49], exec, s[6:7]
	s_cbranch_execz .LBB0_1480
	v_mul_f32_e32 v42, 0xbfb8aa3b, v36
	v_mul_f32_e32 v43, 0xbfb8aa3b, v37
	v_exp_f32_e32 v42, v42
	v_exp_f32_e32 v43, v43
	v_readlane_b32 s6, v252, 35
	v_readlane_b32 s7, v252, 36
	v_add_f32_e32 v42, 1.0, v42
	v_add_f32_e32 v43, 1.0, v43
	v_rcp_f32_e32 v42, v42
	v_rcp_f32_e32 v43, v43
	v_lshl_add_u64 v[40:41], s[6:7], 0, v[40:41]
	v_lshl_add_u64 v[40:41], v[182:183], 1, v[40:41]
	v_pk_mul_f32 v[36:37], v[36:37], v[42:43]
	v_mul_f32_e32 v42, 0xbfb8aa3b, v38
	v_mul_f32_e32 v43, 0xbfb8aa3b, v39
	v_exp_f32_e32 v42, v42
	v_exp_f32_e32 v43, v43
	v_cvt_pk_bf16_f32 v36, v36, v37
	v_add_f32_e32 v42, 1.0, v42
	v_add_f32_e32 v43, 1.0, v43
	v_rcp_f32_e32 v42, v42
	v_rcp_f32_e32 v43, v43
	s_nop 0
	v_pk_mul_f32 v[38:39], v[38:39], v[42:43]
	s_nop 0
	v_cvt_pk_bf16_f32 v37, v38, v39
	v_add_co_u32_e32 v38, vcc, 0xfffff000, v40
	s_nop 1
	v_addc_co_u32_e32 v39, vcc, -1, v41, vcc
	v_mov_b32_e32 v246, v36
	v_mov_b32_e32 v247, v37
	v_lshl_add_u64 v[156:157], v[38:39], 0, v[154:155]
	s_nop 0
	v_permlane16_swap_b32_e32 v244, v246
	v_permlane16_swap_b32_e32 v245, v247
	global_store_dwordx4 v[156:157], v[244:247], off offset:-2048
.LBB0_1480:
	s_andn2_saveexec_b64 s[48:49], s[48:49]
	s_cbranch_execz .LBB0_1498
	v_pk_mul_f32 v[130:131], v[36:37], v[170:171]
	v_pk_mul_f32 v[142:143], v[38:39], v[170:171]
	v_and_b32_e32 v132, 0x7fffffff, v130
	v_and_b32_e32 v144, 0x7fffffff, v142
	v_and_b32_e32 v133, 0x7fffffff, v131
	v_and_b32_e32 v145, 0x7fffffff, v143
	v_pk_fma_f32 v[134:135], v[132:133], v[174:175], v[176:177]
	v_pk_fma_f32 v[146:147], v[144:145], v[174:175], v[176:177]
	v_pk_fma_f32 v[134:135], v[132:133], v[134:135], v[178:179]
	v_pk_fma_f32 v[146:147], v[144:145], v[146:147], v[178:179]
	v_pk_fma_f32 v[134:135], v[132:133], v[134:135], v[180:181]
	v_pk_fma_f32 v[146:147], v[144:145], v[146:147], v[180:181]
	v_pk_fma_f32 v[134:135], v[132:133], v[134:135], v[186:187]
	v_pk_fma_f32 v[146:147], v[144:145], v[146:147], v[186:187]
	v_pk_fma_f32 v[134:135], v[132:133], v[134:135], v[188:189]
	v_pk_fma_f32 v[146:147], v[144:145], v[146:147], v[188:189]
	v_pk_fma_f32 v[134:135], v[132:133], v[134:135], v[190:191]
	v_pk_fma_f32 v[146:147], v[144:145], v[146:147], v[190:191]
	v_pk_fma_f32 v[134:135], v[132:133], v[134:135], v[132:133]
	v_pk_fma_f32 v[146:147], v[144:145], v[146:147], v[144:145]
	v_pk_mul_f32 v[134:135], v[134:135], v[172:173]
	v_pk_mul_f32 v[146:147], v[146:147], v[172:173]
	v_pk_mul_f32 v[136:137], v[130:131], v[130:131]
	v_pk_mul_f32 v[148:149], v[142:143], v[142:143]
	v_exp_f32_e32 v134, v134
	v_exp_f32_e32 v146, v146
	v_exp_f32_e32 v135, v135
	v_exp_f32_e32 v147, v147
	v_pk_fma_f32 v[138:139], v[136:137], v[192:193], v[194:195]
	v_pk_fma_f32 v[150:151], v[148:149], v[192:193], v[194:195]
	v_pk_fma_f32 v[138:139], v[136:137], v[138:139], v[196:197]
	v_pk_fma_f32 v[150:151], v[148:149], v[150:151], v[196:197]
	v_pk_fma_f32 v[138:139], v[136:137], v[138:139], v[224:225]
	v_pk_fma_f32 v[150:151], v[148:149], v[150:151], v[224:225]
	v_pk_fma_f32 v[138:139], v[136:137], v[138:139], v[226:227]
	v_pk_fma_f32 v[150:151], v[148:149], v[150:151], v[226:227]
	v_pk_fma_f32 v[138:139], v[136:137], v[138:139], v[228:229]
	v_pk_fma_f32 v[150:151], v[148:149], v[150:151], v[228:229]
	v_pk_fma_f32 v[134:135], v[134:135], v[234:235], v[230:231]
	v_pk_fma_f32 v[146:147], v[146:147], v[234:235], v[230:231]
	v_pk_fma_f32 v[138:139], v[132:133], v[138:139], v[132:133]
	v_pk_fma_f32 v[150:151], v[144:145], v[150:151], v[144:145]
	v_pk_mul_f32 v[140:141], v[36:37], v[232:233]
	v_pk_mul_f32 v[152:153], v[38:39], v[232:233]
	v_cmp_ngt_f32_e32 vcc, 1.0, v132
	v_cmp_ngt_f32_e64 s[8:9], 1.0, v133
	v_readlane_b32 s6, v252, 33
	v_readlane_b32 s7, v252, 34
	v_cndmask_b32_e32 v138, v138, v134, vcc
	v_cndmask_b32_e64 v139, v139, v135, s[8:9]
	v_cmp_ngt_f32_e32 vcc, 1.0, v144
	v_cmp_ngt_f32_e64 s[8:9], 1.0, v145
	v_bfi_b32 v138, s37, v138, v130
	v_bfi_b32 v139, s37, v139, v131
	v_cndmask_b32_e32 v150, v150, v146, vcc
	v_cndmask_b32_e64 v151, v151, v147, s[8:9]
	v_pk_add_f32 v[138:139], v[138:139], v[230:231]
	v_bfi_b32 v150, s37, v150, v142
	v_bfi_b32 v151, s37, v151, v143
	v_pk_add_f32 v[150:151], v[150:151], v[230:231]
	v_pk_mul_f32 v[138:139], v[140:141], v[138:139]
	v_lshl_add_u64 v[36:37], s[6:7], 0, v[40:41]
	v_pk_mul_f32 v[150:151], v[152:153], v[150:151]
	v_lshl_add_u64 v[36:37], v[182:183], 1, v[36:37]
	v_cvt_pk_bf16_f32 v38, v138, v139
	v_cvt_pk_bf16_f32 v39, v150, v151
	v_mov_b32_e32 v246, v38
	v_mov_b32_e32 v247, v39
	v_lshl_add_u64 v[156:157], v[36:37], 0, v[154:155]
	s_nop 0
	v_permlane16_swap_b32_e32 v244, v246
	v_permlane16_swap_b32_e32 v245, v247
	global_store_dwordx4 v[156:157], v[244:247], off offset:-2048

; DI void st_bf4(u16* p, float a, float b, float c, float d) { *(uint2*)p = make_uint2(pk2(a, b), pk2(c, d)); }
; DI float gelu_f(float x) { return 0.5f * x * (1.f + erff(x * 0.70710678118654752f)); }
; DI float silu_f(float x) { return x * __builtin_amdgcn_rcpf(1.f + __expf(-x)); }
;   template <int NT, int MT> DI void run(f32x4 (&acc)[NT][MT], int mb, int nb) const {
;     ...
;         if (n < 1024) {
;           st_bf4(abuf + (size_t)m * 1024 + n, v[0], v[1], v[2], v[3]);
;           float* dst = nullptr;
;           if (m < M_PROMPT) { int t = m & 8191; if (t >= 8177) dst = spp + ((size_t)((m >> 13) * 15 + (t - 8177))) * 1024 + n; }
;           else { int r = m - M_PROMPT; int s = r & 31; if (s >= 17) dst = sps + ((size_t)((r >> 5) * 15 + (s - 17))) * 1024 + n; }
;           if (dst) *(float4*)dst = make_float4(v[0], v[1], v[2], v[3]);
;         } else if (n < 3072) {
;           st_bf4(uvbuf + (size_t)m * 2048 + (n - 1024), gelu_f(v[0]), gelu_f(v[1]), gelu_f(v[2]), gelu_f(v[3]));
;         } else {
;           st_bf4(gatebuf + (size_t)m * 2048 + (n - 3072), silu_f(v[0]), silu_f(v[1]), silu_f(v[2]), silu_f(v[3]));
.LBB0_1499:
	s_andn2_saveexec_b64 s[46:47], s[46:47]
	s_cbranch_execz .LBB0_1501
	v_lshlrev_b64 v[40:41], 11, v[56:57]
	v_lshl_add_u64 v[40:41], s[96:97], 0, v[40:41]
	v_lshl_add_u64 v[40:41], v[66:67], 1, v[40:41]
	v_cvt_pk_bf16_f32 v36, v36, v37
	v_cvt_pk_bf16_f32 v37, v38, v39
	v_mov_b32_e32 v246, v36
	v_mov_b32_e32 v247, v37
	v_lshl_add_u64 v[156:157], v[40:41], 0, v[154:155]
	s_nop 0
	v_permlane16_swap_b32_e32 v244, v246
	v_permlane16_swap_b32_e32 v245, v247
	global_store_dwordx4 v[156:157], v[244:247], off offset:0
.LBB0_1501:
	s_or_b64 exec, exec, s[46:47]
	s_and_saveexec_b64 s[6:7], s[40:41]
	s_xor_b64 s[40:41], exec, s[6:7]
	s_cbranch_execz .LBB0_1523
	v_lshlrev_b64 v[36:37], 12, v[52:53]
	s_and_saveexec_b64 s[6:7], s[38:39]
	s_xor_b64 s[46:47], exec, s[6:7]
	s_cbranch_execz .LBB0_1504
	v_mul_f32_e32 v38, 0xbfb8aa3b, v32
	v_mul_f32_e32 v39, 0xbfb8aa3b, v33
	v_exp_f32_e32 v38, v38
	v_exp_f32_e32 v39, v39
	v_readlane_b32 s6, v252, 35
	v_readlane_b32 s7, v252, 36
	v_add_f32_e32 v38, 1.0, v38
	v_add_f32_e32 v39, 1.0, v39
	v_rcp_f32_e32 v38, v38
	v_rcp_f32_e32 v39, v39
	v_lshl_add_u64 v[36:37], s[6:7], 0, v[36:37]
	v_lshl_add_u64 v[36:37], v[182:183], 1, v[36:37]
	v_pk_mul_f32 v[32:33], v[32:33], v[38:39]
	v_mul_f32_e32 v38, 0xbfb8aa3b, v34
	v_mul_f32_e32 v39, 0xbfb8aa3b, v35
	v_exp_f32_e32 v38, v38
	v_exp_f32_e32 v39, v39
	v_cvt_pk_bf16_f32 v32, v32, v33
	v_add_f32_e32 v38, 1.0, v38
	v_add_f32_e32 v39, 1.0, v39
	v_rcp_f32_e32 v38, v38
	v_rcp_f32_e32 v39, v39
	s_nop 0
	v_pk_mul_f32 v[34:35], v[34:35], v[38:39]
	s_nop 0
	v_cvt_pk_bf16_f32 v33, v34, v35
	v_add_co_u32_e32 v34, vcc, 0xfffff000, v36
	s_nop 1
	v_addc_co_u32_e32 v35, vcc, -1, v37, vcc
	v_mov_b32_e32 v250, v32
	v_mov_b32_e32 v251, v33
	v_lshl_add_u64 v[156:157], v[34:35], 0, v[154:155]
	s_nop 0
	v_permlane16_swap_b32_e32 v248, v250
	v_permlane16_swap_b32_e32 v249, v251
	global_store_dwordx4 v[156:157], v[248:251], off offset:-2048
.LBB0_1504:
	s_andn2_saveexec_b64 s[46:47], s[46:47]
	s_cbranch_execz .LBB0_1522
	v_pk_mul_f32 v[130:131], v[32:33], v[170:171]
	v_pk_mul_f32 v[142:143], v[34:35], v[170:171]
	v_and_b32_e32 v132, 0x7fffffff, v130
	v_and_b32_e32 v144, 0x7fffffff, v142
	v_and_b32_e32 v133, 0x7fffffff, v131
	v_and_b32_e32 v145, 0x7fffffff, v143
	v_pk_fma_f32 v[134:135], v[132:133], v[174:175], v[176:177]
	v_pk_fma_f32 v[146:147], v[144:145], v[174:175], v[176:177]
	v_pk_fma_f32 v[134:135], v[132:133], v[134:135], v[178:179]
	v_pk_fma_f32 v[146:147], v[144:145], v[146:147], v[178:179]
	v_pk_fma_f32 v[134:135], v[132:133], v[134:135], v[180:181]
	v_pk_fma_f32 v[146:147], v[144:145], v[146:147], v[180:181]
	v_pk_fma_f32 v[134:135], v[132:133], v[134:135], v[186:187]
	v_pk_fma_f32 v[146:147], v[144:145], v[146:147], v[186:187]
	v_pk_fma_f32 v[134:135], v[132:133], v[134:135], v[188:189]
	v_pk_fma_f32 v[146:147], v[144:145], v[146:147], v[188:189]
	v_pk_fma_f32 v[134:135], v[132:133], v[134:135], v[190:191]
	v_pk_fma_f32 v[146:147], v[144:145], v[146:147], v[190:191]
	v_pk_fma_f32 v[134:135], v[132:133], v[134:135], v[132:133]
	v_pk_fma_f32 v[146:147], v[144:145], v[146:147], v[144:145]
	v_pk_mul_f32 v[134:135], v[134:135], v[172:173]
	v_pk_mul_f32 v[146:147], v[146:147], v[172:173]
	v_pk_mul_f32 v[136:137], v[130:131], v[130:131]
	v_pk_mul_f32 v[148:149], v[142:143], v[142:143]
	v_exp_f32_e32 v134, v134
	v_exp_f32_e32 v146, v146
	v_exp_f32_e32 v135, v135
	v_exp_f32_e32 v147, v147
	v_pk_fma_f32 v[138:139], v[136:137], v[192:193], v[194:195]
	v_pk_fma_f32 v[150:151], v[148:149], v[192:193], v[194:195]
	v_pk_fma_f32 v[138:139], v[136:137], v[138:139], v[196:197]
	v_pk_fma_f32 v[150:151], v[148:149], v[150:151], v[196:197]
	v_pk_fma_f32 v[138:139], v[136:137], v[138:139], v[224:225]
	v_pk_fma_f32 v[150:151], v[148:149], v[150:151], v[224:225]
	v_pk_fma_f32 v[138:139], v[136:137], v[138:139], v[226:227]
	v_pk_fma_f32 v[150:151], v[148:149], v[150:151], v[226:227]
	v_pk_fma_f32 v[138:139], v[136:137], v[138:139], v[228:229]
	v_pk_fma_f32 v[150:151], v[148:149], v[150:151], v[228:229]
	v_pk_fma_f32 v[134:135], v[134:135], v[234:235], v[230:231]
	v_pk_fma_f32 v[146:147], v[146:147], v[234:235], v[230:231]
	v_pk_fma_f32 v[138:139], v[132:133], v[138:139], v[132:133]
	v_pk_fma_f32 v[150:151], v[144:145], v[150:151], v[144:145]
	v_pk_mul_f32 v[140:141], v[32:33], v[232:233]
	v_pk_mul_f32 v[152:153], v[34:35], v[232:233]
	v_cmp_ngt_f32_e32 vcc, 1.0, v132
	v_cmp_ngt_f32_e64 s[8:9], 1.0, v133
	v_readlane_b32 s6, v252, 33
	v_readlane_b32 s7, v252, 34
	v_cndmask_b32_e32 v138, v138, v134, vcc
	v_cndmask_b32_e64 v139, v139, v135, s[8:9]
	v_cmp_ngt_f32_e32 vcc, 1.0, v144
	v_cmp_ngt_f32_e64 s[8:9], 1.0, v145
	v_bfi_b32 v138, s37, v138, v130
	v_bfi_b32 v139, s37, v139, v131
	v_cndmask_b32_e32 v150, v150, v146, vcc
	v_cndmask_b32_e64 v151, v151, v147, s[8:9]
	v_pk_add_f32 v[138:139], v[138:139], v[230:231]
	v_bfi_b32 v150, s37, v150, v142
	v_bfi_b32 v151, s37, v151, v143
	v_pk_add_f32 v[150:151], v[150:151], v[230:231]
	v_pk_mul_f32 v[138:139], v[140:141], v[138:139]
	v_lshl_add_u64 v[32:33], s[6:7], 0, v[36:37]
	v_pk_mul_f32 v[150:151], v[152:153], v[150:151]
	v_lshl_add_u64 v[32:33], v[182:183], 1, v[32:33]
	v_cvt_pk_bf16_f32 v34, v138, v139
	v_cvt_pk_bf16_f32 v35, v150, v151
	v_mov_b32_e32 v250, v34
	v_mov_b32_e32 v251, v35
	v_lshl_add_u64 v[156:157], v[32:33], 0, v[154:155]
	s_nop 0
	v_permlane16_swap_b32_e32 v248, v250
	v_permlane16_swap_b32_e32 v249, v251
	global_store_dwordx4 v[156:157], v[248:251], off offset:-2048

; DI void st_bf4(u16* p, float a, float b, float c, float d) { *(uint2*)p = make_uint2(pk2(a, b), pk2(c, d)); }
;   template <int NT, int MT> DI void run(f32x4 (&acc)[NT][MT], int mb, int nb) const {
;     ...
;         if (n < 1024) {
;           st_bf4(abuf + (size_t)m * 1024 + n, v[0], v[1], v[2], v[3]);
;           float* dst = nullptr;
;           if (m < M_PROMPT) { int t = m & 8191; if (t >= 8177) dst = spp + ((size_t)((m >> 13) * 15 + (t - 8177))) * 1024 + n; }
;           else { int r = m - M_PROMPT; int s = r & 31; if (s >= 17) dst = sps + ((size_t)((r >> 5) * 15 + (s - 17))) * 1024 + n; }
;           if (dst) *(float4*)dst = make_float4(v[0], v[1], v[2], v[3]);
.LBB0_1523:
	s_andn2_saveexec_b64 s[40:41], s[40:41]
	s_cbranch_execz .LBB0_1531
	v_lshlrev_b64 v[36:37], 11, v[52:53]
	v_lshl_add_u64 v[36:37], s[96:97], 0, v[36:37]
	s_movk_i32 s5, 0x3fcf
	v_lshl_add_u64 v[36:37], v[66:67], 1, v[36:37]
	v_cvt_pk_bf16_f32 v38, v32, v33
	v_cvt_pk_bf16_f32 v39, v34, v35
	v_cmp_lt_i32_e32 vcc, s5, v64
	v_mov_b32_e32 v250, v38
	v_mov_b32_e32 v251, v39
	v_lshl_add_u64 v[156:157], v[36:37], 0, v[154:155]
	s_nop 0
	v_permlane16_swap_b32_e32 v248, v250
	v_permlane16_swap_b32_e32 v249, v251
	global_store_dwordx4 v[156:157], v[248:251], off offset:0
	s_and_saveexec_b64 s[6:7], vcc
	s_xor_b64 s[46:47], exec, s[6:7]
	s_cbranch_execz .LBB0_1749
	v_and_b32_e32 v38, 31, v52
	v_cmp_ne_u32_e32 vcc, 16, v38
	v_mov_b64_e32 v[36:37], 0
	s_and_saveexec_b64 s[48:49], vcc
	s_cbranch_execz .LBB0_1527
	v_add_u32_e32 v36, 0xffffc030, v68
	v_lshrrev_b32_e32 v36, 5, v36
	v_mul_lo_u32 v36, v36, 15
	s_movk_i32 s5, 0xffef
	v_add3_u32 v36, v38, v36, s5
	v_mov_b32_e32 v37, v183
	v_readlane_b32 s6, v253, 19
	v_lshlrev_b64 v[36:37], 12, v[36:37]
	v_readlane_b32 s7, v253, 20
	s_nop 1
	v_lshl_add_u64 v[36:37], s[6:7], 0, v[36:37]
	v_lshl_add_u64 v[36:37], v[66:67], 2, v[36:37]
	v_lshl_add_u64 v[36:37], v[36:37], 0, 64

; DI void st_bf4(u16* p, float a, float b, float c, float d) { *(uint2*)p = make_uint2(pk2(a, b), pk2(c, d)); }
; DI float gelu_f(float x) { return 0.5f * x * (1.f + erff(x * 0.70710678118654752f)); }
; DI float silu_f(float x) { return x * __builtin_amdgcn_rcpf(1.f + __expf(-x)); }
;   template <int NT, int MT> DI void run(f32x4 (&acc)[NT][MT], int mb, int nb) const {
;     ...
;         } else if (n < 3072) {
;           st_bf4(uvbuf + (size_t)m * 2048 + (n - 1024), gelu_f(v[0]), gelu_f(v[1]), gelu_f(v[2]), gelu_f(v[3]));
;         } else {
;           st_bf4(gatebuf + (size_t)m * 2048 + (n - 3072), silu_f(v[0]), silu_f(v[1]), silu_f(v[2]), silu_f(v[3]));
.LBB0_1531:
	s_or_b64 exec, exec, s[40:41]
	s_movk_i32 s5, 0x3df
	v_cmp_lt_i32_e64 s[40:41], s5, v66
	s_and_saveexec_b64 s[6:7], s[40:41]
	s_xor_b64 s[46:47], exec, s[6:7]
	s_cbranch_execz .LBB0_1553
	v_lshlrev_b64 v[32:33], 12, v[64:65]
	s_and_saveexec_b64 s[6:7], s[38:39]
	s_xor_b64 s[48:49], exec, s[6:7]
	s_cbranch_execz .LBB0_1534
	v_mul_f32_e32 v34, 0xbfb8aa3b, v28
	v_mul_f32_e32 v35, 0xbfb8aa3b, v29
	v_exp_f32_e32 v34, v34
	v_exp_f32_e32 v35, v35
	v_readlane_b32 s6, v252, 35
	v_readlane_b32 s7, v252, 36
	v_add_f32_e32 v34, 1.0, v34
	v_add_f32_e32 v35, 1.0, v35
	v_rcp_f32_e32 v34, v34
	v_rcp_f32_e32 v35, v35
	v_lshl_add_u64 v[32:33], s[6:7], 0, v[32:33]
	v_lshl_add_u64 v[32:33], v[182:183], 1, v[32:33]
	v_pk_mul_f32 v[28:29], v[28:29], v[34:35]
	v_mul_f32_e32 v34, 0xbfb8aa3b, v30
	v_mul_f32_e32 v35, 0xbfb8aa3b, v31
	v_exp_f32_e32 v34, v34
	v_exp_f32_e32 v35, v35
	v_cvt_pk_bf16_f32 v28, v28, v29
	v_add_f32_e32 v34, 1.0, v34
	v_add_f32_e32 v35, 1.0, v35
	v_rcp_f32_e32 v34, v34
	v_rcp_f32_e32 v35, v35
	s_nop 0
	v_pk_mul_f32 v[30:31], v[30:31], v[34:35]
	s_nop 0
	v_cvt_pk_bf16_f32 v29, v30, v31
	v_add_co_u32_e32 v30, vcc, 0xfffff000, v32
	s_nop 1
	v_addc_co_u32_e32 v31, vcc, -1, v33, vcc
	v_mov_b32_e32 v236, v28
	v_mov_b32_e32 v237, v29
.LBB0_1534:
	s_andn2_saveexec_b64 s[48:49], s[48:49]
	s_cbranch_execz .LBB0_1552
	v_pk_mul_f32 v[130:131], v[28:29], v[170:171]
	v_pk_mul_f32 v[142:143], v[30:31], v[170:171]
	v_and_b32_e32 v132, 0x7fffffff, v130
	v_and_b32_e32 v144, 0x7fffffff, v142
	v_and_b32_e32 v133, 0x7fffffff, v131
	v_and_b32_e32 v145, 0x7fffffff, v143
	v_pk_fma_f32 v[134:135], v[132:133], v[174:175], v[176:177]
	v_pk_fma_f32 v[146:147], v[144:145], v[174:175], v[176:177]
	v_pk_fma_f32 v[134:135], v[132:133], v[134:135], v[178:179]
	v_pk_fma_f32 v[146:147], v[144:145], v[146:147], v[178:179]
	v_pk_fma_f32 v[134:135], v[132:133], v[134:135], v[180:181]
	v_pk_fma_f32 v[146:147], v[144:145], v[146:147], v[180:181]
	v_pk_fma_f32 v[134:135], v[132:133], v[134:135], v[186:187]
	v_pk_fma_f32 v[146:147], v[144:145], v[146:147], v[186:187]
	v_pk_fma_f32 v[134:135], v[132:133], v[134:135], v[188:189]
	v_pk_fma_f32 v[146:147], v[144:145], v[146:147], v[188:189]
	v_pk_fma_f32 v[134:135], v[132:133], v[134:135], v[190:191]
	v_pk_fma_f32 v[146:147], v[144:145], v[146:147], v[190:191]
	v_pk_fma_f32 v[134:135], v[132:133], v[134:135], v[132:133]
	v_pk_fma_f32 v[146:147], v[144:145], v[146:147], v[144:145]
	v_pk_mul_f32 v[134:135], v[134:135], v[172:173]
	v_pk_mul_f32 v[146:147], v[146:147], v[172:173]
	v_pk_mul_f32 v[136:137], v[130:131], v[130:131]
	v_pk_mul_f32 v[148:149], v[142:143], v[142:143]
	v_exp_f32_e32 v134, v134
	v_exp_f32_e32 v146, v146
	v_exp_f32_e32 v135, v135
	v_exp_f32_e32 v147, v147
	v_pk_fma_f32 v[138:139], v[136:137], v[192:193], v[194:195]
	v_pk_fma_f32 v[150:151], v[148:149], v[192:193], v[194:195]
	v_pk_fma_f32 v[138:139], v[136:137], v[138:139], v[196:197]
	v_pk_fma_f32 v[150:151], v[148:149], v[150:151], v[196:197]
	v_pk_fma_f32 v[138:139], v[136:137], v[138:139], v[224:225]
	v_pk_fma_f32 v[150:151], v[148:149], v[150:151], v[224:225]
	v_pk_fma_f32 v[138:139], v[136:137], v[138:139], v[226:227]
	v_pk_fma_f32 v[150:151], v[148:149], v[150:151], v[226:227]
	v_pk_fma_f32 v[138:139], v[136:137], v[138:139], v[228:229]
	v_pk_fma_f32 v[150:151], v[148:149], v[150:151], v[228:229]
	v_pk_fma_f32 v[134:135], v[134:135], v[234:235], v[230:231]
	v_pk_fma_f32 v[146:147], v[146:147], v[234:235], v[230:231]
	v_pk_fma_f32 v[138:139], v[132:133], v[138:139], v[132:133]
	v_pk_fma_f32 v[150:151], v[144:145], v[150:151], v[144:145]
	v_pk_mul_f32 v[140:141], v[28:29], v[232:233]
	v_pk_mul_f32 v[152:153], v[30:31], v[232:233]
	v_cmp_ngt_f32_e32 vcc, 1.0, v132
	v_cmp_ngt_f32_e64 s[8:9], 1.0, v133
	v_readlane_b32 s6, v252, 33
	v_readlane_b32 s7, v252, 34
	v_cndmask_b32_e32 v138, v138, v134, vcc
	v_cndmask_b32_e64 v139, v139, v135, s[8:9]
	v_cmp_ngt_f32_e32 vcc, 1.0, v144
	v_cmp_ngt_f32_e64 s[8:9], 1.0, v145
	v_bfi_b32 v138, s37, v138, v130
	v_bfi_b32 v139, s37, v139, v131
	v_cndmask_b32_e32 v150, v150, v146, vcc
	v_cndmask_b32_e64 v151, v151, v147, s[8:9]
	v_pk_add_f32 v[138:139], v[138:139], v[230:231]
	v_bfi_b32 v150, s37, v150, v142
	v_bfi_b32 v151, s37, v151, v143
	v_pk_add_f32 v[150:151], v[150:151], v[230:231]
	v_pk_mul_f32 v[138:139], v[140:141], v[138:139]
	v_lshl_add_u64 v[28:29], s[6:7], 0, v[32:33]
	v_pk_mul_f32 v[150:151], v[152:153], v[150:151]
	v_lshl_add_u64 v[28:29], v[182:183], 1, v[28:29]
	v_cvt_pk_bf16_f32 v30, v138, v139
	v_cvt_pk_bf16_f32 v31, v150, v151
	v_mov_b32_e32 v236, v30
	v_mov_b32_e32 v237, v31

; DI void st_bf4(u16* p, float a, float b, float c, float d) { *(uint2*)p = make_uint2(pk2(a, b), pk2(c, d)); }
; DI float gelu_f(float x) { return 0.5f * x * (1.f + erff(x * 0.70710678118654752f)); }
; DI float silu_f(float x) { return x * __builtin_amdgcn_rcpf(1.f + __expf(-x)); }
;   template <int NT, int MT> DI void run(f32x4 (&acc)[NT][MT], int mb, int nb) const {
;     ...
;         if (n < 1024) {
;           st_bf4(abuf + (size_t)m * 1024 + n, v[0], v[1], v[2], v[3]);
;           float* dst = nullptr;
;           if (m < M_PROMPT) { int t = m & 8191; if (t >= 8177) dst = spp + ((size_t)((m >> 13) * 15 + (t - 8177))) * 1024 + n; }
;           else { int r = m - M_PROMPT; int s = r & 31; if (s >= 17) dst = sps + ((size_t)((r >> 5) * 15 + (s - 17))) * 1024 + n; }
;           if (dst) *(float4*)dst = make_float4(v[0], v[1], v[2], v[3]);
;         } else if (n < 3072) {
;           st_bf4(uvbuf + (size_t)m * 2048 + (n - 1024), gelu_f(v[0]), gelu_f(v[1]), gelu_f(v[2]), gelu_f(v[3]));
;         } else {
;           st_bf4(gatebuf + (size_t)m * 2048 + (n - 3072), silu_f(v[0]), silu_f(v[1]), silu_f(v[2]), silu_f(v[3]));
.LBB0_1553:
	s_andn2_saveexec_b64 s[46:47], s[46:47]
	s_cbranch_execz .LBB0_1555
	v_lshlrev_b64 v[32:33], 11, v[64:65]
	v_lshl_add_u64 v[32:33], s[96:97], 0, v[32:33]
	v_lshl_add_u64 v[32:33], v[66:67], 1, v[32:33]
	v_cvt_pk_bf16_f32 v28, v28, v29
	v_cvt_pk_bf16_f32 v29, v30, v31
	v_mov_b32_e32 v236, v28
	v_mov_b32_e32 v237, v29
.LBB0_1555:
	s_or_b64 exec, exec, s[46:47]
	s_and_saveexec_b64 s[6:7], s[40:41]
	s_xor_b64 s[46:47], exec, s[6:7]
	s_cbranch_execz .LBB0_1577
	v_lshlrev_b64 v[28:29], 12, v[60:61]
	s_and_saveexec_b64 s[6:7], s[38:39]
	s_xor_b64 s[48:49], exec, s[6:7]
	s_cbranch_execz .LBB0_1558
	v_mul_f32_e32 v30, 0xbfb8aa3b, v24
	v_mul_f32_e32 v31, 0xbfb8aa3b, v25
	v_exp_f32_e32 v30, v30
	v_exp_f32_e32 v31, v31
	v_readlane_b32 s6, v252, 35
	v_readlane_b32 s7, v252, 36
	v_add_f32_e32 v30, 1.0, v30
	v_add_f32_e32 v31, 1.0, v31
	v_rcp_f32_e32 v30, v30
	v_rcp_f32_e32 v31, v31
	v_lshl_add_u64 v[28:29], s[6:7], 0, v[28:29]
	v_lshl_add_u64 v[28:29], v[182:183], 1, v[28:29]
	v_pk_mul_f32 v[24:25], v[24:25], v[30:31]
	v_mul_f32_e32 v30, 0xbfb8aa3b, v26
	v_mul_f32_e32 v31, 0xbfb8aa3b, v27
	v_exp_f32_e32 v30, v30
	v_exp_f32_e32 v31, v31
	v_cvt_pk_bf16_f32 v24, v24, v25
	v_add_f32_e32 v30, 1.0, v30
	v_add_f32_e32 v31, 1.0, v31
	v_rcp_f32_e32 v30, v30
	v_rcp_f32_e32 v31, v31
	s_nop 0
	v_pk_mul_f32 v[26:27], v[26:27], v[30:31]
	s_nop 0
	v_cvt_pk_bf16_f32 v25, v26, v27
	v_add_co_u32_e32 v26, vcc, 0xfffff000, v28
	s_nop 1
	v_addc_co_u32_e32 v27, vcc, -1, v29, vcc
	v_mov_b32_e32 v240, v24
	v_mov_b32_e32 v241, v25
.LBB0_1558:
	s_andn2_saveexec_b64 s[48:49], s[48:49]
	s_cbranch_execz .LBB0_1576
	v_pk_mul_f32 v[130:131], v[24:25], v[170:171]
	v_pk_mul_f32 v[142:143], v[26:27], v[170:171]
	v_and_b32_e32 v132, 0x7fffffff, v130
	v_and_b32_e32 v144, 0x7fffffff, v142
	v_and_b32_e32 v133, 0x7fffffff, v131
	v_and_b32_e32 v145, 0x7fffffff, v143
	v_pk_fma_f32 v[134:135], v[132:133], v[174:175], v[176:177]
	v_pk_fma_f32 v[146:147], v[144:145], v[174:175], v[176:177]
	v_pk_fma_f32 v[134:135], v[132:133], v[134:135], v[178:179]
	v_pk_fma_f32 v[146:147], v[144:145], v[146:147], v[178:179]
	v_pk_fma_f32 v[134:135], v[132:133], v[134:135], v[180:181]
	v_pk_fma_f32 v[146:147], v[144:145], v[146:147], v[180:181]
	v_pk_fma_f32 v[134:135], v[132:133], v[134:135], v[186:187]
	v_pk_fma_f32 v[146:147], v[144:145], v[146:147], v[186:187]
	v_pk_fma_f32 v[134:135], v[132:133], v[134:135], v[188:189]
	v_pk_fma_f32 v[146:147], v[144:145], v[146:147], v[188:189]
	v_pk_fma_f32 v[134:135], v[132:133], v[134:135], v[190:191]
	v_pk_fma_f32 v[146:147], v[144:145], v[146:147], v[190:191]
	v_pk_fma_f32 v[134:135], v[132:133], v[134:135], v[132:133]
	v_pk_fma_f32 v[146:147], v[144:145], v[146:147], v[144:145]
	v_pk_mul_f32 v[134:135], v[134:135], v[172:173]
	v_pk_mul_f32 v[146:147], v[146:147], v[172:173]
	v_pk_mul_f32 v[136:137], v[130:131], v[130:131]
	v_pk_mul_f32 v[148:149], v[142:143], v[142:143]
	v_exp_f32_e32 v134, v134
	v_exp_f32_e32 v146, v146
	v_exp_f32_e32 v135, v135
	v_exp_f32_e32 v147, v147
	v_pk_fma_f32 v[138:139], v[136:137], v[192:193], v[194:195]
	v_pk_fma_f32 v[150:151], v[148:149], v[192:193], v[194:195]
	v_pk_fma_f32 v[138:139], v[136:137], v[138:139], v[196:197]
	v_pk_fma_f32 v[150:151], v[148:149], v[150:151], v[196:197]
	v_pk_fma_f32 v[138:139], v[136:137], v[138:139], v[224:225]
	v_pk_fma_f32 v[150:151], v[148:149], v[150:151], v[224:225]
	v_pk_fma_f32 v[138:139], v[136:137], v[138:139], v[226:227]
	v_pk_fma_f32 v[150:151], v[148:149], v[150:151], v[226:227]
	v_pk_fma_f32 v[138:139], v[136:137], v[138:139], v[228:229]
	v_pk_fma_f32 v[150:151], v[148:149], v[150:151], v[228:229]
	v_pk_fma_f32 v[134:135], v[134:135], v[234:235], v[230:231]
	v_pk_fma_f32 v[146:147], v[146:147], v[234:235], v[230:231]
	v_pk_fma_f32 v[138:139], v[132:133], v[138:139], v[132:133]
	v_pk_fma_f32 v[150:151], v[144:145], v[150:151], v[144:145]
	v_pk_mul_f32 v[140:141], v[24:25], v[232:233]
	v_pk_mul_f32 v[152:153], v[26:27], v[232:233]
	v_cmp_ngt_f32_e32 vcc, 1.0, v132
	v_cmp_ngt_f32_e64 s[8:9], 1.0, v133
	v_readlane_b32 s6, v252, 33
	v_readlane_b32 s7, v252, 34
	v_cndmask_b32_e32 v138, v138, v134, vcc
	v_cndmask_b32_e64 v139, v139, v135, s[8:9]
	v_cmp_ngt_f32_e32 vcc, 1.0, v144
	v_cmp_ngt_f32_e64 s[8:9], 1.0, v145
	v_bfi_b32 v138, s37, v138, v130
	v_bfi_b32 v139, s37, v139, v131
	v_cndmask_b32_e32 v150, v150, v146, vcc
	v_cndmask_b32_e64 v151, v151, v147, s[8:9]
	v_pk_add_f32 v[138:139], v[138:139], v[230:231]
	v_bfi_b32 v150, s37, v150, v142
	v_bfi_b32 v151, s37, v151, v143
	v_pk_add_f32 v[150:151], v[150:151], v[230:231]
	v_pk_mul_f32 v[138:139], v[140:141], v[138:139]
	v_lshl_add_u64 v[24:25], s[6:7], 0, v[28:29]
	v_pk_mul_f32 v[150:151], v[152:153], v[150:151]
	v_lshl_add_u64 v[24:25], v[182:183], 1, v[24:25]
	v_cvt_pk_bf16_f32 v26, v138, v139
	v_cvt_pk_bf16_f32 v27, v150, v151
	v_mov_b32_e32 v240, v26
	v_mov_b32_e32 v241, v27

; DI void st_bf4(u16* p, float a, float b, float c, float d) { *(uint2*)p = make_uint2(pk2(a, b), pk2(c, d)); }
;   template <int NT, int MT> DI void run(f32x4 (&acc)[NT][MT], int mb, int nb) const {
;     ...
;         if (n < 1024) {
;           st_bf4(abuf + (size_t)m * 1024 + n, v[0], v[1], v[2], v[3]);
;           float* dst = nullptr;
;           if (m < M_PROMPT) { int t = m & 8191; if (t >= 8177) dst = spp + ((size_t)((m >> 13) * 15 + (t - 8177))) * 1024 + n; }
;           else { int r = m - M_PROMPT; int s = r & 31; if (s >= 17) dst = sps + ((size_t)((r >> 5) * 15 + (s - 17))) * 1024 + n; }
;           if (dst) *(float4*)dst = make_float4(v[0], v[1], v[2], v[3]);
.LBB0_1577:
	s_andn2_saveexec_b64 s[46:47], s[46:47]
	s_cbranch_execz .LBB0_1585
	v_lshlrev_b64 v[28:29], 11, v[60:61]
	v_lshl_add_u64 v[28:29], s[96:97], 0, v[28:29]
	v_lshl_add_u64 v[28:29], v[66:67], 1, v[28:29]
	v_cvt_pk_bf16_f32 v30, v24, v25
	v_cvt_pk_bf16_f32 v31, v26, v27
	s_movk_i32 s5, 0x3fef
	v_mov_b32_e32 v240, v30
	v_mov_b32_e32 v241, v31
	v_cmp_lt_i32_e32 vcc, s5, v64
	v_mov_b64_e32 v[28:29], 0
	s_and_saveexec_b64 s[48:49], vcc
	s_cbranch_execz .LBB0_1582
	v_and_b32_e32 v30, 31, v60
	v_cmp_ne_u32_e32 vcc, 16, v30
	v_mov_b64_e32 v[28:29], 0
	s_and_saveexec_b64 s[50:51], vcc
	s_cbranch_execz .LBB0_1581
	v_add_u32_e32 v28, 0xffffc010, v68
	v_lshrrev_b32_e32 v28, 5, v28
	v_mul_lo_u32 v28, v28, 15
	s_movk_i32 s5, 0xffef
	v_add3_u32 v28, v30, v28, s5
	v_mov_b32_e32 v29, v183
	v_readlane_b32 s6, v253, 19
	v_lshlrev_b64 v[28:29], 12, v[28:29]
	v_readlane_b32 s7, v253, 20
	s_nop 1
	v_lshl_add_u64 v[28:29], s[6:7], 0, v[28:29]
	v_lshl_add_u64 v[28:29], v[66:67], 2, v[28:29]
	v_lshl_add_u64 v[28:29], v[28:29], 0, s[28:29]

; DI void st_bf4(u16* p, float a, float b, float c, float d) { *(uint2*)p = make_uint2(pk2(a, b), pk2(c, d)); }
; DI float gelu_f(float x) { return 0.5f * x * (1.f + erff(x * 0.70710678118654752f)); }
; DI float silu_f(float x) { return x * __builtin_amdgcn_rcpf(1.f + __expf(-x)); }
;   template <int NT, int MT> DI void run(f32x4 (&acc)[NT][MT], int mb, int nb) const {
;     ...
;         } else if (n < 3072) {
;           st_bf4(uvbuf + (size_t)m * 2048 + (n - 1024), gelu_f(v[0]), gelu_f(v[1]), gelu_f(v[2]), gelu_f(v[3]));
;         } else {
;           st_bf4(gatebuf + (size_t)m * 2048 + (n - 3072), silu_f(v[0]), silu_f(v[1]), silu_f(v[2]), silu_f(v[3]));
.LBB0_1585:
	s_or_b64 exec, exec, s[46:47]
	s_and_saveexec_b64 s[6:7], s[40:41]
	s_xor_b64 s[46:47], exec, s[6:7]
	s_cbranch_execz .LBB0_1607
	v_lshlrev_b64 v[24:25], 12, v[56:57]
	s_and_saveexec_b64 s[6:7], s[38:39]
	s_xor_b64 s[48:49], exec, s[6:7]
	s_cbranch_execz .LBB0_1588
	v_mul_f32_e32 v26, 0xbfb8aa3b, v20
	v_mul_f32_e32 v27, 0xbfb8aa3b, v21
	v_exp_f32_e32 v26, v26
	v_exp_f32_e32 v27, v27
	v_readlane_b32 s6, v252, 35
	v_readlane_b32 s7, v252, 36
	v_add_f32_e32 v26, 1.0, v26
	v_add_f32_e32 v27, 1.0, v27
	v_rcp_f32_e32 v26, v26
	v_rcp_f32_e32 v27, v27
	v_lshl_add_u64 v[24:25], s[6:7], 0, v[24:25]
	v_lshl_add_u64 v[24:25], v[182:183], 1, v[24:25]
	v_pk_mul_f32 v[20:21], v[20:21], v[26:27]
	v_mul_f32_e32 v26, 0xbfb8aa3b, v22
	v_mul_f32_e32 v27, 0xbfb8aa3b, v23
	v_exp_f32_e32 v26, v26
	v_exp_f32_e32 v27, v27
	v_cvt_pk_bf16_f32 v20, v20, v21
	v_add_f32_e32 v26, 1.0, v26
	v_add_f32_e32 v27, 1.0, v27
	v_rcp_f32_e32 v26, v26
	v_rcp_f32_e32 v27, v27
	s_nop 0
	v_pk_mul_f32 v[22:23], v[22:23], v[26:27]
	s_nop 0
	v_cvt_pk_bf16_f32 v21, v22, v23
	v_add_co_u32_e32 v22, vcc, 0xfffff000, v24
	s_nop 1
	v_addc_co_u32_e32 v23, vcc, -1, v25, vcc
	v_mov_b32_e32 v244, v20
	v_mov_b32_e32 v245, v21
.LBB0_1588:
	s_andn2_saveexec_b64 s[48:49], s[48:49]
	s_cbranch_execz .LBB0_1606
	v_pk_mul_f32 v[130:131], v[20:21], v[170:171]
	v_pk_mul_f32 v[142:143], v[22:23], v[170:171]
	v_and_b32_e32 v132, 0x7fffffff, v130
	v_and_b32_e32 v144, 0x7fffffff, v142
	v_and_b32_e32 v133, 0x7fffffff, v131
	v_and_b32_e32 v145, 0x7fffffff, v143
	v_pk_fma_f32 v[134:135], v[132:133], v[174:175], v[176:177]
	v_pk_fma_f32 v[146:147], v[144:145], v[174:175], v[176:177]
	v_pk_fma_f32 v[134:135], v[132:133], v[134:135], v[178:179]
	v_pk_fma_f32 v[146:147], v[144:145], v[146:147], v[178:179]
	v_pk_fma_f32 v[134:135], v[132:133], v[134:135], v[180:181]
	v_pk_fma_f32 v[146:147], v[144:145], v[146:147], v[180:181]
	v_pk_fma_f32 v[134:135], v[132:133], v[134:135], v[186:187]
	v_pk_fma_f32 v[146:147], v[144:145], v[146:147], v[186:187]
	v_pk_fma_f32 v[134:135], v[132:133], v[134:135], v[188:189]
	v_pk_fma_f32 v[146:147], v[144:145], v[146:147], v[188:189]
	v_pk_fma_f32 v[134:135], v[132:133], v[134:135], v[190:191]
	v_pk_fma_f32 v[146:147], v[144:145], v[146:147], v[190:191]
	v_pk_fma_f32 v[134:135], v[132:133], v[134:135], v[132:133]
	v_pk_fma_f32 v[146:147], v[144:145], v[146:147], v[144:145]
	v_pk_mul_f32 v[134:135], v[134:135], v[172:173]
	v_pk_mul_f32 v[146:147], v[146:147], v[172:173]
	v_pk_mul_f32 v[136:137], v[130:131], v[130:131]
	v_pk_mul_f32 v[148:149], v[142:143], v[142:143]
	v_exp_f32_e32 v134, v134
	v_exp_f32_e32 v146, v146
	v_exp_f32_e32 v135, v135
	v_exp_f32_e32 v147, v147
	v_pk_fma_f32 v[138:139], v[136:137], v[192:193], v[194:195]
	v_pk_fma_f32 v[150:151], v[148:149], v[192:193], v[194:195]
	v_pk_fma_f32 v[138:139], v[136:137], v[138:139], v[196:197]
	v_pk_fma_f32 v[150:151], v[148:149], v[150:151], v[196:197]
	v_pk_fma_f32 v[138:139], v[136:137], v[138:139], v[224:225]
	v_pk_fma_f32 v[150:151], v[148:149], v[150:151], v[224:225]
	v_pk_fma_f32 v[138:139], v[136:137], v[138:139], v[226:227]
	v_pk_fma_f32 v[150:151], v[148:149], v[150:151], v[226:227]
	v_pk_fma_f32 v[138:139], v[136:137], v[138:139], v[228:229]
	v_pk_fma_f32 v[150:151], v[148:149], v[150:151], v[228:229]
	v_pk_fma_f32 v[134:135], v[134:135], v[234:235], v[230:231]
	v_pk_fma_f32 v[146:147], v[146:147], v[234:235], v[230:231]
	v_pk_fma_f32 v[138:139], v[132:133], v[138:139], v[132:133]
	v_pk_fma_f32 v[150:151], v[144:145], v[150:151], v[144:145]
	v_pk_mul_f32 v[140:141], v[20:21], v[232:233]
	v_pk_mul_f32 v[152:153], v[22:23], v[232:233]
	v_cmp_ngt_f32_e32 vcc, 1.0, v132
	v_cmp_ngt_f32_e64 s[8:9], 1.0, v133
	v_readlane_b32 s6, v252, 33
	v_readlane_b32 s7, v252, 34
	v_cndmask_b32_e32 v138, v138, v134, vcc
	v_cndmask_b32_e64 v139, v139, v135, s[8:9]
	v_cmp_ngt_f32_e32 vcc, 1.0, v144
	v_cmp_ngt_f32_e64 s[8:9], 1.0, v145
	v_bfi_b32 v138, s37, v138, v130
	v_bfi_b32 v139, s37, v139, v131
	v_cndmask_b32_e32 v150, v150, v146, vcc
	v_cndmask_b32_e64 v151, v151, v147, s[8:9]
	v_pk_add_f32 v[138:139], v[138:139], v[230:231]
	v_bfi_b32 v150, s37, v150, v142
	v_bfi_b32 v151, s37, v151, v143
	v_pk_add_f32 v[150:151], v[150:151], v[230:231]
	v_pk_mul_f32 v[138:139], v[140:141], v[138:139]
	v_lshl_add_u64 v[20:21], s[6:7], 0, v[24:25]
	v_pk_mul_f32 v[150:151], v[152:153], v[150:151]
	v_lshl_add_u64 v[20:21], v[182:183], 1, v[20:21]
	v_cvt_pk_bf16_f32 v22, v138, v139
	v_cvt_pk_bf16_f32 v23, v150, v151
	v_mov_b32_e32 v244, v22
	v_mov_b32_e32 v245, v23

; DI void st_bf4(u16* p, float a, float b, float c, float d) { *(uint2*)p = make_uint2(pk2(a, b), pk2(c, d)); }
; DI float gelu_f(float x) { return 0.5f * x * (1.f + erff(x * 0.70710678118654752f)); }
; DI float silu_f(float x) { return x * __builtin_amdgcn_rcpf(1.f + __expf(-x)); }
;   template <int NT, int MT> DI void run(f32x4 (&acc)[NT][MT], int mb, int nb) const {
;     ...
;         if (n < 1024) {
;           st_bf4(abuf + (size_t)m * 1024 + n, v[0], v[1], v[2], v[3]);
;           float* dst = nullptr;
;           if (m < M_PROMPT) { int t = m & 8191; if (t >= 8177) dst = spp + ((size_t)((m >> 13) * 15 + (t - 8177))) * 1024 + n; }
;           else { int r = m - M_PROMPT; int s = r & 31; if (s >= 17) dst = sps + ((size_t)((r >> 5) * 15 + (s - 17))) * 1024 + n; }
;           if (dst) *(float4*)dst = make_float4(v[0], v[1], v[2], v[3]);
;         } else if (n < 3072) {
;           st_bf4(uvbuf + (size_t)m * 2048 + (n - 1024), gelu_f(v[0]), gelu_f(v[1]), gelu_f(v[2]), gelu_f(v[3]));
;         } else {
;           st_bf4(gatebuf + (size_t)m * 2048 + (n - 3072), silu_f(v[0]), silu_f(v[1]), silu_f(v[2]), silu_f(v[3]));
.LBB0_1607:
	s_andn2_saveexec_b64 s[46:47], s[46:47]
	s_cbranch_execz .LBB0_1609
	v_lshlrev_b64 v[24:25], 11, v[56:57]
	v_lshl_add_u64 v[24:25], s[96:97], 0, v[24:25]
	v_lshl_add_u64 v[24:25], v[66:67], 1, v[24:25]
	v_cvt_pk_bf16_f32 v20, v20, v21
	v_cvt_pk_bf16_f32 v21, v22, v23
	v_mov_b32_e32 v244, v20
	v_mov_b32_e32 v245, v21
.LBB0_1609:
	s_or_b64 exec, exec, s[46:47]
	s_and_saveexec_b64 s[6:7], s[40:41]
	s_xor_b64 s[40:41], exec, s[6:7]
	s_cbranch_execz .LBB0_1631
	v_lshlrev_b64 v[20:21], 12, v[52:53]
	s_and_saveexec_b64 s[6:7], s[38:39]
	s_xor_b64 s[46:47], exec, s[6:7]
	s_cbranch_execz .LBB0_1612
	v_mul_f32_e32 v22, 0xbfb8aa3b, v16
	v_mul_f32_e32 v23, 0xbfb8aa3b, v17
	v_exp_f32_e32 v22, v22
	v_exp_f32_e32 v23, v23
	v_readlane_b32 s6, v252, 35
	v_readlane_b32 s7, v252, 36
	v_add_f32_e32 v22, 1.0, v22
	v_add_f32_e32 v23, 1.0, v23
	v_rcp_f32_e32 v22, v22
	v_rcp_f32_e32 v23, v23
	v_lshl_add_u64 v[20:21], s[6:7], 0, v[20:21]
	v_lshl_add_u64 v[20:21], v[182:183], 1, v[20:21]
	v_pk_mul_f32 v[16:17], v[16:17], v[22:23]
	v_mul_f32_e32 v22, 0xbfb8aa3b, v18
	v_mul_f32_e32 v23, 0xbfb8aa3b, v19
	v_exp_f32_e32 v22, v22
	v_exp_f32_e32 v23, v23
	v_cvt_pk_bf16_f32 v16, v16, v17
	v_add_f32_e32 v22, 1.0, v22
	v_add_f32_e32 v23, 1.0, v23
	v_rcp_f32_e32 v22, v22
	v_rcp_f32_e32 v23, v23
	s_nop 0
	v_pk_mul_f32 v[18:19], v[18:19], v[22:23]
	s_nop 0
	v_cvt_pk_bf16_f32 v17, v18, v19
	v_add_co_u32_e32 v18, vcc, 0xfffff000, v20
	s_nop 1
	v_addc_co_u32_e32 v19, vcc, -1, v21, vcc
	v_mov_b32_e32 v248, v16
	v_mov_b32_e32 v249, v17
.LBB0_1612:
	s_andn2_saveexec_b64 s[46:47], s[46:47]
	s_cbranch_execz .LBB0_1630
	v_pk_mul_f32 v[130:131], v[16:17], v[170:171]
	v_pk_mul_f32 v[142:143], v[18:19], v[170:171]
	v_and_b32_e32 v132, 0x7fffffff, v130
	v_and_b32_e32 v144, 0x7fffffff, v142
	v_and_b32_e32 v133, 0x7fffffff, v131
	v_and_b32_e32 v145, 0x7fffffff, v143
	v_pk_fma_f32 v[134:135], v[132:133], v[174:175], v[176:177]
	v_pk_fma_f32 v[146:147], v[144:145], v[174:175], v[176:177]
	v_pk_fma_f32 v[134:135], v[132:133], v[134:135], v[178:179]
	v_pk_fma_f32 v[146:147], v[144:145], v[146:147], v[178:179]
	v_pk_fma_f32 v[134:135], v[132:133], v[134:135], v[180:181]
	v_pk_fma_f32 v[146:147], v[144:145], v[146:147], v[180:181]
	v_pk_fma_f32 v[134:135], v[132:133], v[134:135], v[186:187]
	v_pk_fma_f32 v[146:147], v[144:145], v[146:147], v[186:187]
	v_pk_fma_f32 v[134:135], v[132:133], v[134:135], v[188:189]
	v_pk_fma_f32 v[146:147], v[144:145], v[146:147], v[188:189]
	v_pk_fma_f32 v[134:135], v[132:133], v[134:135], v[190:191]
	v_pk_fma_f32 v[146:147], v[144:145], v[146:147], v[190:191]
	v_pk_fma_f32 v[134:135], v[132:133], v[134:135], v[132:133]
	v_pk_fma_f32 v[146:147], v[144:145], v[146:147], v[144:145]
	v_pk_mul_f32 v[134:135], v[134:135], v[172:173]
	v_pk_mul_f32 v[146:147], v[146:147], v[172:173]
	v_pk_mul_f32 v[136:137], v[130:131], v[130:131]
	v_pk_mul_f32 v[148:149], v[142:143], v[142:143]
	v_exp_f32_e32 v134, v134
	v_exp_f32_e32 v146, v146
	v_exp_f32_e32 v135, v135
	v_exp_f32_e32 v147, v147
	v_pk_fma_f32 v[138:139], v[136:137], v[192:193], v[194:195]
	v_pk_fma_f32 v[150:151], v[148:149], v[192:193], v[194:195]
	v_pk_fma_f32 v[138:139], v[136:137], v[138:139], v[196:197]
	v_pk_fma_f32 v[150:151], v[148:149], v[150:151], v[196:197]
	v_pk_fma_f32 v[138:139], v[136:137], v[138:139], v[224:225]
	v_pk_fma_f32 v[150:151], v[148:149], v[150:151], v[224:225]
	v_pk_fma_f32 v[138:139], v[136:137], v[138:139], v[226:227]
	v_pk_fma_f32 v[150:151], v[148:149], v[150:151], v[226:227]
	v_pk_fma_f32 v[138:139], v[136:137], v[138:139], v[228:229]
	v_pk_fma_f32 v[150:151], v[148:149], v[150:151], v[228:229]
	v_pk_fma_f32 v[134:135], v[134:135], v[234:235], v[230:231]
	v_pk_fma_f32 v[146:147], v[146:147], v[234:235], v[230:231]
	v_pk_fma_f32 v[138:139], v[132:133], v[138:139], v[132:133]
	v_pk_fma_f32 v[150:151], v[144:145], v[150:151], v[144:145]
	v_pk_mul_f32 v[140:141], v[16:17], v[232:233]
	v_pk_mul_f32 v[152:153], v[18:19], v[232:233]
	v_cmp_ngt_f32_e32 vcc, 1.0, v132
	v_cmp_ngt_f32_e64 s[8:9], 1.0, v133
	v_readlane_b32 s6, v252, 33
	v_readlane_b32 s7, v252, 34
	v_cndmask_b32_e32 v138, v138, v134, vcc
	v_cndmask_b32_e64 v139, v139, v135, s[8:9]
	v_cmp_ngt_f32_e32 vcc, 1.0, v144
	v_cmp_ngt_f32_e64 s[8:9], 1.0, v145
	v_bfi_b32 v138, s37, v138, v130
	v_bfi_b32 v139, s37, v139, v131
	v_cndmask_b32_e32 v150, v150, v146, vcc
	v_cndmask_b32_e64 v151, v151, v147, s[8:9]
	v_pk_add_f32 v[138:139], v[138:139], v[230:231]
	v_bfi_b32 v150, s37, v150, v142
	v_bfi_b32 v151, s37, v151, v143
	v_pk_add_f32 v[150:151], v[150:151], v[230:231]
	v_pk_mul_f32 v[138:139], v[140:141], v[138:139]
	v_lshl_add_u64 v[16:17], s[6:7], 0, v[20:21]
	v_pk_mul_f32 v[150:151], v[152:153], v[150:151]
	v_lshl_add_u64 v[16:17], v[182:183], 1, v[16:17]
	v_cvt_pk_bf16_f32 v18, v138, v139
	v_cvt_pk_bf16_f32 v19, v150, v151
	v_mov_b32_e32 v248, v18
	v_mov_b32_e32 v249, v19

; DI void st_bf4(u16* p, float a, float b, float c, float d) { *(uint2*)p = make_uint2(pk2(a, b), pk2(c, d)); }
;   template <int NT, int MT> DI void run(f32x4 (&acc)[NT][MT], int mb, int nb) const {
;     ...
;         if (n < 1024) {
;           st_bf4(abuf + (size_t)m * 1024 + n, v[0], v[1], v[2], v[3]);
;           float* dst = nullptr;
;           if (m < M_PROMPT) { int t = m & 8191; if (t >= 8177) dst = spp + ((size_t)((m >> 13) * 15 + (t - 8177))) * 1024 + n; }
;           else { int r = m - M_PROMPT; int s = r & 31; if (s >= 17) dst = sps + ((size_t)((r >> 5) * 15 + (s - 17))) * 1024 + n; }
;           if (dst) *(float4*)dst = make_float4(v[0], v[1], v[2], v[3]);
.LBB0_1631:
	s_andn2_saveexec_b64 s[40:41], s[40:41]
	s_cbranch_execz .LBB0_1639
	v_lshlrev_b64 v[20:21], 11, v[52:53]
	v_lshl_add_u64 v[20:21], s[96:97], 0, v[20:21]
	s_movk_i32 s5, 0x3fcf
	v_lshl_add_u64 v[20:21], v[66:67], 1, v[20:21]
	v_cvt_pk_bf16_f32 v22, v16, v17
	v_cvt_pk_bf16_f32 v23, v18, v19
	v_cmp_lt_i32_e32 vcc, s5, v64
	v_mov_b32_e32 v248, v22
	v_mov_b32_e32 v249, v23
	s_and_saveexec_b64 s[6:7], vcc
	s_xor_b64 s[46:47], exec, s[6:7]
	s_cbranch_execz .LBB0_1753
	v_and_b32_e32 v22, 31, v52
	v_cmp_ne_u32_e32 vcc, 16, v22
	v_mov_b64_e32 v[20:21], 0
	s_and_saveexec_b64 s[48:49], vcc
	s_cbranch_execz .LBB0_1635
	v_add_u32_e32 v20, 0xffffc030, v68
	v_lshrrev_b32_e32 v20, 5, v20
	v_mul_lo_u32 v20, v20, 15
	s_movk_i32 s5, 0xffef
	v_add3_u32 v20, v22, v20, s5
	v_mov_b32_e32 v21, v183
	v_readlane_b32 s6, v253, 19
	v_lshlrev_b64 v[20:21], 12, v[20:21]
	v_readlane_b32 s7, v253, 20
	s_nop 1
	v_lshl_add_u64 v[20:21], s[6:7], 0, v[20:21]
	v_lshl_add_u64 v[20:21], v[66:67], 2, v[20:21]
	v_lshl_add_u64 v[20:21], v[20:21], 0, s[28:29]

; DI void st_bf4(u16* p, float a, float b, float c, float d) { *(uint2*)p = make_uint2(pk2(a, b), pk2(c, d)); }
; DI float gelu_f(float x) { return 0.5f * x * (1.f + erff(x * 0.70710678118654752f)); }
; DI float silu_f(float x) { return x * __builtin_amdgcn_rcpf(1.f + __expf(-x)); }
;   template <int NT, int MT> DI void run(f32x4 (&acc)[NT][MT], int mb, int nb) const {
;     ...
;         } else if (n < 3072) {
;           st_bf4(uvbuf + (size_t)m * 2048 + (n - 1024), gelu_f(v[0]), gelu_f(v[1]), gelu_f(v[2]), gelu_f(v[3]));
;         } else {
;           st_bf4(gatebuf + (size_t)m * 2048 + (n - 3072), silu_f(v[0]), silu_f(v[1]), silu_f(v[2]), silu_f(v[3]));
.LBB0_1639:
	s_or_b64 exec, exec, s[40:41]
	s_movk_i32 s5, 0x3cf
	v_cmp_lt_i32_e64 s[40:41], s5, v182
	s_and_saveexec_b64 s[6:7], s[40:41]
	s_xor_b64 s[46:47], exec, s[6:7]
	s_cbranch_execz .LBB0_1661
	v_lshlrev_b64 v[16:17], 12, v[64:65]
	s_and_saveexec_b64 s[6:7], s[38:39]
	s_xor_b64 s[48:49], exec, s[6:7]
	s_cbranch_execz .LBB0_1642
	v_mul_f32_e32 v18, 0xbfb8aa3b, v12
	v_mul_f32_e32 v19, 0xbfb8aa3b, v13
	v_exp_f32_e32 v18, v18
	v_exp_f32_e32 v19, v19
	v_readlane_b32 s6, v252, 35
	v_readlane_b32 s7, v252, 36
	v_add_f32_e32 v18, 1.0, v18
	v_add_f32_e32 v19, 1.0, v19
	v_rcp_f32_e32 v18, v18
	v_rcp_f32_e32 v19, v19
	v_lshl_add_u64 v[16:17], s[6:7], 0, v[16:17]
	v_lshl_add_u64 v[16:17], v[182:183], 1, v[16:17]
	v_pk_mul_f32 v[12:13], v[12:13], v[18:19]
	v_mul_f32_e32 v18, 0xbfb8aa3b, v14
	v_mul_f32_e32 v19, 0xbfb8aa3b, v15
	v_exp_f32_e32 v18, v18
	v_exp_f32_e32 v19, v19
	v_cvt_pk_bf16_f32 v12, v12, v13
	v_add_f32_e32 v18, 1.0, v18
	v_add_f32_e32 v19, 1.0, v19
	v_rcp_f32_e32 v18, v18
	v_rcp_f32_e32 v19, v19
	s_nop 0
	v_pk_mul_f32 v[14:15], v[14:15], v[18:19]
	s_nop 0
	v_cvt_pk_bf16_f32 v13, v14, v15
	v_add_co_u32_e32 v14, vcc, 0xfffff000, v16
	s_nop 1
	v_addc_co_u32_e32 v15, vcc, -1, v17, vcc
	v_mov_b32_e32 v238, v12
	v_mov_b32_e32 v239, v13
	v_lshl_add_u64 v[156:157], v[14:15], 0, v[154:155]
	s_nop 0
	v_permlane16_swap_b32_e32 v236, v238
	v_permlane16_swap_b32_e32 v237, v239
	global_store_dwordx4 v[156:157], v[236:239], off offset:-1984
.LBB0_1642:
	s_andn2_saveexec_b64 s[48:49], s[48:49]
	s_cbranch_execz .LBB0_1660
	v_pk_mul_f32 v[130:131], v[12:13], v[170:171]
	v_pk_mul_f32 v[142:143], v[14:15], v[170:171]
	v_and_b32_e32 v132, 0x7fffffff, v130
	v_and_b32_e32 v144, 0x7fffffff, v142
	v_and_b32_e32 v133, 0x7fffffff, v131
	v_and_b32_e32 v145, 0x7fffffff, v143
	v_pk_fma_f32 v[134:135], v[132:133], v[174:175], v[176:177]
	v_pk_fma_f32 v[146:147], v[144:145], v[174:175], v[176:177]
	v_pk_fma_f32 v[134:135], v[132:133], v[134:135], v[178:179]
	v_pk_fma_f32 v[146:147], v[144:145], v[146:147], v[178:179]
	v_pk_fma_f32 v[134:135], v[132:133], v[134:135], v[180:181]
	v_pk_fma_f32 v[146:147], v[144:145], v[146:147], v[180:181]
	v_pk_fma_f32 v[134:135], v[132:133], v[134:135], v[186:187]
	v_pk_fma_f32 v[146:147], v[144:145], v[146:147], v[186:187]
	v_pk_fma_f32 v[134:135], v[132:133], v[134:135], v[188:189]
	v_pk_fma_f32 v[146:147], v[144:145], v[146:147], v[188:189]
	v_pk_fma_f32 v[134:135], v[132:133], v[134:135], v[190:191]
	v_pk_fma_f32 v[146:147], v[144:145], v[146:147], v[190:191]
	v_pk_fma_f32 v[134:135], v[132:133], v[134:135], v[132:133]
	v_pk_fma_f32 v[146:147], v[144:145], v[146:147], v[144:145]
	v_pk_mul_f32 v[134:135], v[134:135], v[172:173]
	v_pk_mul_f32 v[146:147], v[146:147], v[172:173]
	v_pk_mul_f32 v[136:137], v[130:131], v[130:131]
	v_pk_mul_f32 v[148:149], v[142:143], v[142:143]
	v_exp_f32_e32 v134, v134
	v_exp_f32_e32 v146, v146
	v_exp_f32_e32 v135, v135
	v_exp_f32_e32 v147, v147
	v_pk_fma_f32 v[138:139], v[136:137], v[192:193], v[194:195]
	v_pk_fma_f32 v[150:151], v[148:149], v[192:193], v[194:195]
	v_pk_fma_f32 v[138:139], v[136:137], v[138:139], v[196:197]
	v_pk_fma_f32 v[150:151], v[148:149], v[150:151], v[196:197]
	v_pk_fma_f32 v[138:139], v[136:137], v[138:139], v[224:225]
	v_pk_fma_f32 v[150:151], v[148:149], v[150:151], v[224:225]
	v_pk_fma_f32 v[138:139], v[136:137], v[138:139], v[226:227]
	v_pk_fma_f32 v[150:151], v[148:149], v[150:151], v[226:227]
	v_pk_fma_f32 v[138:139], v[136:137], v[138:139], v[228:229]
	v_pk_fma_f32 v[150:151], v[148:149], v[150:151], v[228:229]
	v_pk_fma_f32 v[134:135], v[134:135], v[234:235], v[230:231]
	v_pk_fma_f32 v[146:147], v[146:147], v[234:235], v[230:231]
	v_pk_fma_f32 v[138:139], v[132:133], v[138:139], v[132:133]
	v_pk_fma_f32 v[150:151], v[144:145], v[150:151], v[144:145]
	v_pk_mul_f32 v[140:141], v[12:13], v[232:233]
	v_pk_mul_f32 v[152:153], v[14:15], v[232:233]
	v_cmp_ngt_f32_e32 vcc, 1.0, v132
	v_cmp_ngt_f32_e64 s[8:9], 1.0, v133
	v_readlane_b32 s6, v252, 33
	v_readlane_b32 s7, v252, 34
	v_cndmask_b32_e32 v138, v138, v134, vcc
	v_cndmask_b32_e64 v139, v139, v135, s[8:9]
	v_cmp_ngt_f32_e32 vcc, 1.0, v144
	v_cmp_ngt_f32_e64 s[8:9], 1.0, v145
	v_bfi_b32 v138, s37, v138, v130
	v_bfi_b32 v139, s37, v139, v131
	v_cndmask_b32_e32 v150, v150, v146, vcc
	v_cndmask_b32_e64 v151, v151, v147, s[8:9]
	v_pk_add_f32 v[138:139], v[138:139], v[230:231]
	v_bfi_b32 v150, s37, v150, v142
	v_bfi_b32 v151, s37, v151, v143
	v_pk_add_f32 v[150:151], v[150:151], v[230:231]
	v_pk_mul_f32 v[138:139], v[140:141], v[138:139]
	v_lshl_add_u64 v[12:13], s[6:7], 0, v[16:17]
	v_pk_mul_f32 v[150:151], v[152:153], v[150:151]
	v_lshl_add_u64 v[12:13], v[182:183], 1, v[12:13]
	v_cvt_pk_bf16_f32 v14, v138, v139
	v_cvt_pk_bf16_f32 v15, v150, v151
	v_mov_b32_e32 v238, v14
	v_mov_b32_e32 v239, v15
	v_lshl_add_u64 v[156:157], v[12:13], 0, v[154:155]
	s_nop 0
	v_permlane16_swap_b32_e32 v236, v238
	v_permlane16_swap_b32_e32 v237, v239
	global_store_dwordx4 v[156:157], v[236:239], off offset:-1984

; DI void st_bf4(u16* p, float a, float b, float c, float d) { *(uint2*)p = make_uint2(pk2(a, b), pk2(c, d)); }
; DI float gelu_f(float x) { return 0.5f * x * (1.f + erff(x * 0.70710678118654752f)); }
; DI float silu_f(float x) { return x * __builtin_amdgcn_rcpf(1.f + __expf(-x)); }
;   template <int NT, int MT> DI void run(f32x4 (&acc)[NT][MT], int mb, int nb) const {
;     ...
;         if (n < 1024) {
;           st_bf4(abuf + (size_t)m * 1024 + n, v[0], v[1], v[2], v[3]);
;           float* dst = nullptr;
;           if (m < M_PROMPT) { int t = m & 8191; if (t >= 8177) dst = spp + ((size_t)((m >> 13) * 15 + (t - 8177))) * 1024 + n; }
;           else { int r = m - M_PROMPT; int s = r & 31; if (s >= 17) dst = sps + ((size_t)((r >> 5) * 15 + (s - 17))) * 1024 + n; }
;           if (dst) *(float4*)dst = make_float4(v[0], v[1], v[2], v[3]);
;         } else if (n < 3072) {
;           st_bf4(uvbuf + (size_t)m * 2048 + (n - 1024), gelu_f(v[0]), gelu_f(v[1]), gelu_f(v[2]), gelu_f(v[3]));
;         } else {
;           st_bf4(gatebuf + (size_t)m * 2048 + (n - 3072), silu_f(v[0]), silu_f(v[1]), silu_f(v[2]), silu_f(v[3]));
.LBB0_1661:
	s_andn2_saveexec_b64 s[46:47], s[46:47]
	s_cbranch_execz .LBB0_1663
	v_lshlrev_b64 v[16:17], 11, v[64:65]
	v_lshl_add_u64 v[16:17], s[96:97], 0, v[16:17]
	v_lshl_add_u64 v[16:17], v[66:67], 1, v[16:17]
	v_cvt_pk_bf16_f32 v12, v12, v13
	v_cvt_pk_bf16_f32 v13, v14, v15
	v_mov_b32_e32 v238, v12
	v_mov_b32_e32 v239, v13
	v_lshl_add_u64 v[156:157], v[16:17], 0, v[154:155]
	s_nop 0
	v_permlane16_swap_b32_e32 v236, v238
	v_permlane16_swap_b32_e32 v237, v239
	global_store_dwordx4 v[156:157], v[236:239], off offset:64
.LBB0_1663:
	s_or_b64 exec, exec, s[46:47]
	s_and_saveexec_b64 s[6:7], s[40:41]
	s_xor_b64 s[46:47], exec, s[6:7]
	s_cbranch_execz .LBB0_1685
	v_lshlrev_b64 v[12:13], 12, v[60:61]
	s_and_saveexec_b64 s[6:7], s[38:39]
	s_xor_b64 s[48:49], exec, s[6:7]
	s_cbranch_execz .LBB0_1666
	v_mul_f32_e32 v14, 0xbfb8aa3b, v8
	v_mul_f32_e32 v15, 0xbfb8aa3b, v9
	v_exp_f32_e32 v14, v14
	v_exp_f32_e32 v15, v15
	v_readlane_b32 s6, v252, 35
	v_readlane_b32 s7, v252, 36
	v_add_f32_e32 v14, 1.0, v14
	v_add_f32_e32 v15, 1.0, v15
	v_rcp_f32_e32 v14, v14
	v_rcp_f32_e32 v15, v15
	v_lshl_add_u64 v[12:13], s[6:7], 0, v[12:13]
	v_lshl_add_u64 v[12:13], v[182:183], 1, v[12:13]
	v_pk_mul_f32 v[8:9], v[8:9], v[14:15]
	v_mul_f32_e32 v14, 0xbfb8aa3b, v10
	v_mul_f32_e32 v15, 0xbfb8aa3b, v11
	v_exp_f32_e32 v14, v14
	v_exp_f32_e32 v15, v15
	v_cvt_pk_bf16_f32 v8, v8, v9
	v_add_f32_e32 v14, 1.0, v14
	v_add_f32_e32 v15, 1.0, v15
	v_rcp_f32_e32 v14, v14
	v_rcp_f32_e32 v15, v15
	s_nop 0
	v_pk_mul_f32 v[10:11], v[10:11], v[14:15]
	s_nop 0
	v_cvt_pk_bf16_f32 v9, v10, v11
	v_add_co_u32_e32 v10, vcc, 0xfffff000, v12
	s_nop 1
	v_addc_co_u32_e32 v11, vcc, -1, v13, vcc
	v_mov_b32_e32 v242, v8
	v_mov_b32_e32 v243, v9
	v_lshl_add_u64 v[156:157], v[10:11], 0, v[154:155]
	s_nop 0
	v_permlane16_swap_b32_e32 v240, v242
	v_permlane16_swap_b32_e32 v241, v243
	global_store_dwordx4 v[156:157], v[240:243], off offset:-1984
.LBB0_1666:
	s_andn2_saveexec_b64 s[48:49], s[48:49]
	s_cbranch_execz .LBB0_1684
	v_pk_mul_f32 v[130:131], v[8:9], v[170:171]
	v_pk_mul_f32 v[142:143], v[10:11], v[170:171]
	v_and_b32_e32 v132, 0x7fffffff, v130
	v_and_b32_e32 v144, 0x7fffffff, v142
	v_and_b32_e32 v133, 0x7fffffff, v131
	v_and_b32_e32 v145, 0x7fffffff, v143
	v_pk_fma_f32 v[134:135], v[132:133], v[174:175], v[176:177]
	v_pk_fma_f32 v[146:147], v[144:145], v[174:175], v[176:177]
	v_pk_fma_f32 v[134:135], v[132:133], v[134:135], v[178:179]
	v_pk_fma_f32 v[146:147], v[144:145], v[146:147], v[178:179]
	v_pk_fma_f32 v[134:135], v[132:133], v[134:135], v[180:181]
	v_pk_fma_f32 v[146:147], v[144:145], v[146:147], v[180:181]
	v_pk_fma_f32 v[134:135], v[132:133], v[134:135], v[186:187]
	v_pk_fma_f32 v[146:147], v[144:145], v[146:147], v[186:187]
	v_pk_fma_f32 v[134:135], v[132:133], v[134:135], v[188:189]
	v_pk_fma_f32 v[146:147], v[144:145], v[146:147], v[188:189]
	v_pk_fma_f32 v[134:135], v[132:133], v[134:135], v[190:191]
	v_pk_fma_f32 v[146:147], v[144:145], v[146:147], v[190:191]
	v_pk_fma_f32 v[134:135], v[132:133], v[134:135], v[132:133]
	v_pk_fma_f32 v[146:147], v[144:145], v[146:147], v[144:145]
	v_pk_mul_f32 v[134:135], v[134:135], v[172:173]
	v_pk_mul_f32 v[146:147], v[146:147], v[172:173]
	v_pk_mul_f32 v[136:137], v[130:131], v[130:131]
	v_pk_mul_f32 v[148:149], v[142:143], v[142:143]
	v_exp_f32_e32 v134, v134
	v_exp_f32_e32 v146, v146
	v_exp_f32_e32 v135, v135
	v_exp_f32_e32 v147, v147
	v_pk_fma_f32 v[138:139], v[136:137], v[192:193], v[194:195]
	v_pk_fma_f32 v[150:151], v[148:149], v[192:193], v[194:195]
	v_pk_fma_f32 v[138:139], v[136:137], v[138:139], v[196:197]
	v_pk_fma_f32 v[150:151], v[148:149], v[150:151], v[196:197]
	v_pk_fma_f32 v[138:139], v[136:137], v[138:139], v[224:225]
	v_pk_fma_f32 v[150:151], v[148:149], v[150:151], v[224:225]
	v_pk_fma_f32 v[138:139], v[136:137], v[138:139], v[226:227]
	v_pk_fma_f32 v[150:151], v[148:149], v[150:151], v[226:227]
	v_pk_fma_f32 v[138:139], v[136:137], v[138:139], v[228:229]
	v_pk_fma_f32 v[150:151], v[148:149], v[150:151], v[228:229]
	v_pk_fma_f32 v[134:135], v[134:135], v[234:235], v[230:231]
	v_pk_fma_f32 v[146:147], v[146:147], v[234:235], v[230:231]
	v_pk_fma_f32 v[138:139], v[132:133], v[138:139], v[132:133]
	v_pk_fma_f32 v[150:151], v[144:145], v[150:151], v[144:145]
	v_pk_mul_f32 v[140:141], v[8:9], v[232:233]
	v_pk_mul_f32 v[152:153], v[10:11], v[232:233]
	v_cmp_ngt_f32_e32 vcc, 1.0, v132
	v_cmp_ngt_f32_e64 s[8:9], 1.0, v133
	v_readlane_b32 s6, v252, 33
	v_readlane_b32 s7, v252, 34
	v_cndmask_b32_e32 v138, v138, v134, vcc
	v_cndmask_b32_e64 v139, v139, v135, s[8:9]
	v_cmp_ngt_f32_e32 vcc, 1.0, v144
	v_cmp_ngt_f32_e64 s[8:9], 1.0, v145
	v_bfi_b32 v138, s37, v138, v130
	v_bfi_b32 v139, s37, v139, v131
	v_cndmask_b32_e32 v150, v150, v146, vcc
	v_cndmask_b32_e64 v151, v151, v147, s[8:9]
	v_pk_add_f32 v[138:139], v[138:139], v[230:231]
	v_bfi_b32 v150, s37, v150, v142
	v_bfi_b32 v151, s37, v151, v143
	v_pk_add_f32 v[150:151], v[150:151], v[230:231]
	v_pk_mul_f32 v[138:139], v[140:141], v[138:139]
	v_lshl_add_u64 v[8:9], s[6:7], 0, v[12:13]
	v_pk_mul_f32 v[150:151], v[152:153], v[150:151]
	v_lshl_add_u64 v[8:9], v[182:183], 1, v[8:9]
	v_cvt_pk_bf16_f32 v10, v138, v139
	v_cvt_pk_bf16_f32 v11, v150, v151
	v_mov_b32_e32 v242, v10
	v_mov_b32_e32 v243, v11
	v_lshl_add_u64 v[156:157], v[8:9], 0, v[154:155]
	s_nop 0
	v_permlane16_swap_b32_e32 v240, v242
	v_permlane16_swap_b32_e32 v241, v243
	global_store_dwordx4 v[156:157], v[240:243], off offset:-1984

; DI void st_bf4(u16* p, float a, float b, float c, float d) { *(uint2*)p = make_uint2(pk2(a, b), pk2(c, d)); }
;   template <int NT, int MT> DI void run(f32x4 (&acc)[NT][MT], int mb, int nb) const {
;     ...
;         if (n < 1024) {
;           st_bf4(abuf + (size_t)m * 1024 + n, v[0], v[1], v[2], v[3]);
;           float* dst = nullptr;
;           if (m < M_PROMPT) { int t = m & 8191; if (t >= 8177) dst = spp + ((size_t)((m >> 13) * 15 + (t - 8177))) * 1024 + n; }
;           else { int r = m - M_PROMPT; int s = r & 31; if (s >= 17) dst = sps + ((size_t)((r >> 5) * 15 + (s - 17))) * 1024 + n; }
;           if (dst) *(float4*)dst = make_float4(v[0], v[1], v[2], v[3]);
.LBB0_1685:
	s_andn2_saveexec_b64 s[46:47], s[46:47]
	s_cbranch_execz .LBB0_1693
	v_lshlrev_b64 v[12:13], 11, v[60:61]
	v_lshl_add_u64 v[12:13], s[96:97], 0, v[12:13]
	v_lshl_add_u64 v[12:13], v[66:67], 1, v[12:13]
	v_cvt_pk_bf16_f32 v14, v8, v9
	v_cvt_pk_bf16_f32 v15, v10, v11
	s_movk_i32 s5, 0x3fef
	v_mov_b32_e32 v242, v14
	v_mov_b32_e32 v243, v15
	v_lshl_add_u64 v[156:157], v[12:13], 0, v[154:155]
	s_nop 0
	v_permlane16_swap_b32_e32 v240, v242
	v_permlane16_swap_b32_e32 v241, v243
	global_store_dwordx4 v[156:157], v[240:243], off offset:64
	v_cmp_lt_i32_e32 vcc, s5, v64
	v_mov_b64_e32 v[12:13], 0
	s_and_saveexec_b64 s[48:49], vcc
	s_cbranch_execz .LBB0_1690
	v_and_b32_e32 v14, 31, v60
	v_cmp_ne_u32_e32 vcc, 16, v14
	v_mov_b64_e32 v[12:13], 0
	s_and_saveexec_b64 s[50:51], vcc
	s_cbranch_execz .LBB0_1689
	v_add_u32_e32 v12, 0xffffc010, v68
	v_lshrrev_b32_e32 v12, 5, v12
	v_mul_lo_u32 v12, v12, 15
	s_movk_i32 s5, 0xffef
	v_add3_u32 v12, v14, v12, s5
	v_mov_b32_e32 v13, v183
	v_readlane_b32 s6, v253, 19
	v_lshlrev_b64 v[12:13], 12, v[12:13]
	v_readlane_b32 s7, v253, 20
	s_nop 1
	v_lshl_add_u64 v[12:13], s[6:7], 0, v[12:13]
	v_lshl_add_u64 v[12:13], v[66:67], 2, v[12:13]
	s_mov_b64 s[6:7], 0xc0
	v_lshl_add_u64 v[12:13], v[12:13], 0, s[6:7]

; DI void st_bf4(u16* p, float a, float b, float c, float d) { *(uint2*)p = make_uint2(pk2(a, b), pk2(c, d)); }
; DI float gelu_f(float x) { return 0.5f * x * (1.f + erff(x * 0.70710678118654752f)); }
; DI float silu_f(float x) { return x * __builtin_amdgcn_rcpf(1.f + __expf(-x)); }
;   template <int NT, int MT> DI void run(f32x4 (&acc)[NT][MT], int mb, int nb) const {
;     ...
;         } else if (n < 3072) {
;           st_bf4(uvbuf + (size_t)m * 2048 + (n - 1024), gelu_f(v[0]), gelu_f(v[1]), gelu_f(v[2]), gelu_f(v[3]));
;         } else {
;           st_bf4(gatebuf + (size_t)m * 2048 + (n - 3072), silu_f(v[0]), silu_f(v[1]), silu_f(v[2]), silu_f(v[3]));
.LBB0_1693:
	s_or_b64 exec, exec, s[46:47]
	s_and_saveexec_b64 s[6:7], s[40:41]
	s_xor_b64 s[46:47], exec, s[6:7]
	s_cbranch_execz .LBB0_1715
	v_lshlrev_b64 v[8:9], 12, v[56:57]
	s_and_saveexec_b64 s[6:7], s[38:39]
	s_xor_b64 s[48:49], exec, s[6:7]
	s_cbranch_execz .LBB0_1696
	v_mul_f32_e32 v10, 0xbfb8aa3b, v4
	v_mul_f32_e32 v11, 0xbfb8aa3b, v5
	v_exp_f32_e32 v10, v10
	v_exp_f32_e32 v11, v11
	v_readlane_b32 s6, v252, 35
	v_readlane_b32 s7, v252, 36
	v_add_f32_e32 v10, 1.0, v10
	v_add_f32_e32 v11, 1.0, v11
	v_rcp_f32_e32 v10, v10
	v_rcp_f32_e32 v11, v11
	v_lshl_add_u64 v[8:9], s[6:7], 0, v[8:9]
	v_lshl_add_u64 v[8:9], v[182:183], 1, v[8:9]
	v_pk_mul_f32 v[4:5], v[4:5], v[10:11]
	v_mul_f32_e32 v10, 0xbfb8aa3b, v6
	v_mul_f32_e32 v11, 0xbfb8aa3b, v7
	v_exp_f32_e32 v10, v10
	v_exp_f32_e32 v11, v11
	v_cvt_pk_bf16_f32 v4, v4, v5
	v_add_f32_e32 v10, 1.0, v10
	v_add_f32_e32 v11, 1.0, v11
	v_rcp_f32_e32 v10, v10
	v_rcp_f32_e32 v11, v11
	s_nop 0
	v_pk_mul_f32 v[6:7], v[6:7], v[10:11]
	s_nop 0
	v_cvt_pk_bf16_f32 v5, v6, v7
	v_add_co_u32_e32 v6, vcc, 0xfffff000, v8
	s_nop 1
	v_addc_co_u32_e32 v7, vcc, -1, v9, vcc
	v_mov_b32_e32 v246, v4
	v_mov_b32_e32 v247, v5
	v_lshl_add_u64 v[156:157], v[6:7], 0, v[154:155]
	s_nop 0
	v_permlane16_swap_b32_e32 v244, v246
	v_permlane16_swap_b32_e32 v245, v247
	global_store_dwordx4 v[156:157], v[244:247], off offset:-1984
.LBB0_1696:
	s_andn2_saveexec_b64 s[48:49], s[48:49]
	s_cbranch_execz .LBB0_1714
	v_pk_mul_f32 v[130:131], v[4:5], v[170:171]
	v_pk_mul_f32 v[142:143], v[6:7], v[170:171]
	v_and_b32_e32 v132, 0x7fffffff, v130
	v_and_b32_e32 v144, 0x7fffffff, v142
	v_and_b32_e32 v133, 0x7fffffff, v131
	v_and_b32_e32 v145, 0x7fffffff, v143
	v_pk_fma_f32 v[134:135], v[132:133], v[174:175], v[176:177]
	v_pk_fma_f32 v[146:147], v[144:145], v[174:175], v[176:177]
	v_pk_fma_f32 v[134:135], v[132:133], v[134:135], v[178:179]
	v_pk_fma_f32 v[146:147], v[144:145], v[146:147], v[178:179]
	v_pk_fma_f32 v[134:135], v[132:133], v[134:135], v[180:181]
	v_pk_fma_f32 v[146:147], v[144:145], v[146:147], v[180:181]
	v_pk_fma_f32 v[134:135], v[132:133], v[134:135], v[186:187]
	v_pk_fma_f32 v[146:147], v[144:145], v[146:147], v[186:187]
	v_pk_fma_f32 v[134:135], v[132:133], v[134:135], v[188:189]
	v_pk_fma_f32 v[146:147], v[144:145], v[146:147], v[188:189]
	v_pk_fma_f32 v[134:135], v[132:133], v[134:135], v[190:191]
	v_pk_fma_f32 v[146:147], v[144:145], v[146:147], v[190:191]
	v_pk_fma_f32 v[134:135], v[132:133], v[134:135], v[132:133]
	v_pk_fma_f32 v[146:147], v[144:145], v[146:147], v[144:145]
	v_pk_mul_f32 v[134:135], v[134:135], v[172:173]
	v_pk_mul_f32 v[146:147], v[146:147], v[172:173]
	v_pk_mul_f32 v[136:137], v[130:131], v[130:131]
	v_pk_mul_f32 v[148:149], v[142:143], v[142:143]
	v_exp_f32_e32 v134, v134
	v_exp_f32_e32 v146, v146
	v_exp_f32_e32 v135, v135
	v_exp_f32_e32 v147, v147
	v_pk_fma_f32 v[138:139], v[136:137], v[192:193], v[194:195]
	v_pk_fma_f32 v[150:151], v[148:149], v[192:193], v[194:195]
	v_pk_fma_f32 v[138:139], v[136:137], v[138:139], v[196:197]
	v_pk_fma_f32 v[150:151], v[148:149], v[150:151], v[196:197]
	v_pk_fma_f32 v[138:139], v[136:137], v[138:139], v[224:225]
	v_pk_fma_f32 v[150:151], v[148:149], v[150:151], v[224:225]
	v_pk_fma_f32 v[138:139], v[136:137], v[138:139], v[226:227]
	v_pk_fma_f32 v[150:151], v[148:149], v[150:151], v[226:227]
	v_pk_fma_f32 v[138:139], v[136:137], v[138:139], v[228:229]
	v_pk_fma_f32 v[150:151], v[148:149], v[150:151], v[228:229]
	v_pk_fma_f32 v[134:135], v[134:135], v[234:235], v[230:231]
	v_pk_fma_f32 v[146:147], v[146:147], v[234:235], v[230:231]
	v_pk_fma_f32 v[138:139], v[132:133], v[138:139], v[132:133]
	v_pk_fma_f32 v[150:151], v[144:145], v[150:151], v[144:145]
	v_pk_mul_f32 v[140:141], v[4:5], v[232:233]
	v_pk_mul_f32 v[152:153], v[6:7], v[232:233]
	v_cmp_ngt_f32_e32 vcc, 1.0, v132
	v_cmp_ngt_f32_e64 s[8:9], 1.0, v133
	v_readlane_b32 s6, v252, 33
	v_readlane_b32 s7, v252, 34
	v_cndmask_b32_e32 v138, v138, v134, vcc
	v_cndmask_b32_e64 v139, v139, v135, s[8:9]
	v_cmp_ngt_f32_e32 vcc, 1.0, v144
	v_cmp_ngt_f32_e64 s[8:9], 1.0, v145
	v_bfi_b32 v138, s37, v138, v130
	v_bfi_b32 v139, s37, v139, v131
	v_cndmask_b32_e32 v150, v150, v146, vcc
	v_cndmask_b32_e64 v151, v151, v147, s[8:9]
	v_pk_add_f32 v[138:139], v[138:139], v[230:231]
	v_bfi_b32 v150, s37, v150, v142
	v_bfi_b32 v151, s37, v151, v143
	v_pk_add_f32 v[150:151], v[150:151], v[230:231]
	v_pk_mul_f32 v[138:139], v[140:141], v[138:139]
	v_lshl_add_u64 v[4:5], s[6:7], 0, v[8:9]
	v_pk_mul_f32 v[150:151], v[152:153], v[150:151]
	v_lshl_add_u64 v[4:5], v[182:183], 1, v[4:5]
	v_cvt_pk_bf16_f32 v6, v138, v139
	v_cvt_pk_bf16_f32 v7, v150, v151
	v_mov_b32_e32 v246, v6
	v_mov_b32_e32 v247, v7
	v_lshl_add_u64 v[156:157], v[4:5], 0, v[154:155]
	s_nop 0
	v_permlane16_swap_b32_e32 v244, v246
	v_permlane16_swap_b32_e32 v245, v247
	global_store_dwordx4 v[156:157], v[244:247], off offset:-1984

; DI void st_bf4(u16* p, float a, float b, float c, float d) { *(uint2*)p = make_uint2(pk2(a, b), pk2(c, d)); }
; DI float gelu_f(float x) { return 0.5f * x * (1.f + erff(x * 0.70710678118654752f)); }
; DI float silu_f(float x) { return x * __builtin_amdgcn_rcpf(1.f + __expf(-x)); }
;   template <int NT, int MT> DI void run(f32x4 (&acc)[NT][MT], int mb, int nb) const {
;     ...
;         if (n < 1024) {
;           st_bf4(abuf + (size_t)m * 1024 + n, v[0], v[1], v[2], v[3]);
;           float* dst = nullptr;
;           if (m < M_PROMPT) { int t = m & 8191; if (t >= 8177) dst = spp + ((size_t)((m >> 13) * 15 + (t - 8177))) * 1024 + n; }
;           else { int r = m - M_PROMPT; int s = r & 31; if (s >= 17) dst = sps + ((size_t)((r >> 5) * 15 + (s - 17))) * 1024 + n; }
;           if (dst) *(float4*)dst = make_float4(v[0], v[1], v[2], v[3]);
;         } else if (n < 3072) {
;           st_bf4(uvbuf + (size_t)m * 2048 + (n - 1024), gelu_f(v[0]), gelu_f(v[1]), gelu_f(v[2]), gelu_f(v[3]));
;         } else {
;           st_bf4(gatebuf + (size_t)m * 2048 + (n - 3072), silu_f(v[0]), silu_f(v[1]), silu_f(v[2]), silu_f(v[3]));
.LBB0_1715:
	s_andn2_saveexec_b64 s[46:47], s[46:47]
	s_cbranch_execz .LBB0_1717
	v_lshlrev_b64 v[8:9], 11, v[56:57]
	v_lshl_add_u64 v[8:9], s[96:97], 0, v[8:9]
	v_lshl_add_u64 v[8:9], v[66:67], 1, v[8:9]
	v_cvt_pk_bf16_f32 v4, v4, v5
	v_cvt_pk_bf16_f32 v5, v6, v7
	v_mov_b32_e32 v246, v4
	v_mov_b32_e32 v247, v5
	v_lshl_add_u64 v[156:157], v[8:9], 0, v[154:155]
	s_nop 0
	v_permlane16_swap_b32_e32 v244, v246
	v_permlane16_swap_b32_e32 v245, v247
	global_store_dwordx4 v[156:157], v[244:247], off offset:64
.LBB0_1717:
	s_or_b64 exec, exec, s[46:47]
	s_and_saveexec_b64 s[6:7], s[40:41]
	s_xor_b64 s[40:41], exec, s[6:7]
	s_cbranch_execz .LBB0_1739
	v_lshlrev_b64 v[4:5], 12, v[52:53]
	s_and_saveexec_b64 s[6:7], s[38:39]
	s_xor_b64 s[38:39], exec, s[6:7]
	s_cbranch_execz .LBB0_1720
	v_mul_f32_e32 v6, 0xbfb8aa3b, v0
	v_mul_f32_e32 v7, 0xbfb8aa3b, v1
	v_exp_f32_e32 v6, v6
	v_exp_f32_e32 v7, v7
	v_readlane_b32 s6, v252, 35
	v_readlane_b32 s7, v252, 36
	v_add_f32_e32 v6, 1.0, v6
	v_add_f32_e32 v7, 1.0, v7
	v_rcp_f32_e32 v6, v6
	v_rcp_f32_e32 v7, v7
	v_lshl_add_u64 v[4:5], s[6:7], 0, v[4:5]
	v_lshl_add_u64 v[4:5], v[182:183], 1, v[4:5]
	v_pk_mul_f32 v[0:1], v[0:1], v[6:7]
	v_mul_f32_e32 v6, 0xbfb8aa3b, v2
	v_mul_f32_e32 v7, 0xbfb8aa3b, v3
	v_exp_f32_e32 v6, v6
	v_exp_f32_e32 v7, v7
	v_cvt_pk_bf16_f32 v0, v0, v1
	v_add_f32_e32 v6, 1.0, v6
	v_add_f32_e32 v7, 1.0, v7
	v_rcp_f32_e32 v6, v6
	v_rcp_f32_e32 v7, v7
	s_nop 0
	v_pk_mul_f32 v[2:3], v[2:3], v[6:7]
	s_nop 0
	v_cvt_pk_bf16_f32 v1, v2, v3
	v_add_co_u32_e32 v2, vcc, 0xfffff000, v4
	s_nop 1
	v_addc_co_u32_e32 v3, vcc, -1, v5, vcc
	v_mov_b32_e32 v250, v0
	v_mov_b32_e32 v251, v1
	v_lshl_add_u64 v[156:157], v[2:3], 0, v[154:155]
	s_nop 0
	v_permlane16_swap_b32_e32 v248, v250
	v_permlane16_swap_b32_e32 v249, v251
	global_store_dwordx4 v[156:157], v[248:251], off offset:-1984
.LBB0_1720:
	s_andn2_saveexec_b64 s[38:39], s[38:39]
	s_cbranch_execz .LBB0_1738
	v_pk_mul_f32 v[130:131], v[0:1], v[170:171]
	v_pk_mul_f32 v[142:143], v[2:3], v[170:171]
	v_and_b32_e32 v132, 0x7fffffff, v130
	v_and_b32_e32 v144, 0x7fffffff, v142
	v_and_b32_e32 v133, 0x7fffffff, v131
	v_and_b32_e32 v145, 0x7fffffff, v143
	v_pk_fma_f32 v[134:135], v[132:133], v[174:175], v[176:177]
	v_pk_fma_f32 v[146:147], v[144:145], v[174:175], v[176:177]
	v_pk_fma_f32 v[134:135], v[132:133], v[134:135], v[178:179]
	v_pk_fma_f32 v[146:147], v[144:145], v[146:147], v[178:179]
	v_pk_fma_f32 v[134:135], v[132:133], v[134:135], v[180:181]
	v_pk_fma_f32 v[146:147], v[144:145], v[146:147], v[180:181]
	v_pk_fma_f32 v[134:135], v[132:133], v[134:135], v[186:187]
	v_pk_fma_f32 v[146:147], v[144:145], v[146:147], v[186:187]
	v_pk_fma_f32 v[134:135], v[132:133], v[134:135], v[188:189]
	v_pk_fma_f32 v[146:147], v[144:145], v[146:147], v[188:189]
	v_pk_fma_f32 v[134:135], v[132:133], v[134:135], v[190:191]
	v_pk_fma_f32 v[146:147], v[144:145], v[146:147], v[190:191]
	v_pk_fma_f32 v[134:135], v[132:133], v[134:135], v[132:133]
	v_pk_fma_f32 v[146:147], v[144:145], v[146:147], v[144:145]
	v_pk_mul_f32 v[134:135], v[134:135], v[172:173]
	v_pk_mul_f32 v[146:147], v[146:147], v[172:173]
	v_pk_mul_f32 v[136:137], v[130:131], v[130:131]
	v_pk_mul_f32 v[148:149], v[142:143], v[142:143]
	v_exp_f32_e32 v134, v134
	v_exp_f32_e32 v146, v146
	v_exp_f32_e32 v135, v135
	v_exp_f32_e32 v147, v147
	v_pk_fma_f32 v[138:139], v[136:137], v[192:193], v[194:195]
	v_pk_fma_f32 v[150:151], v[148:149], v[192:193], v[194:195]
	v_pk_fma_f32 v[138:139], v[136:137], v[138:139], v[196:197]
	v_pk_fma_f32 v[150:151], v[148:149], v[150:151], v[196:197]
	v_pk_fma_f32 v[138:139], v[136:137], v[138:139], v[224:225]
	v_pk_fma_f32 v[150:151], v[148:149], v[150:151], v[224:225]
	v_pk_fma_f32 v[138:139], v[136:137], v[138:139], v[226:227]
	v_pk_fma_f32 v[150:151], v[148:149], v[150:151], v[226:227]
	v_pk_fma_f32 v[138:139], v[136:137], v[138:139], v[228:229]
	v_pk_fma_f32 v[150:151], v[148:149], v[150:151], v[228:229]
	v_pk_fma_f32 v[134:135], v[134:135], v[234:235], v[230:231]
	v_pk_fma_f32 v[146:147], v[146:147], v[234:235], v[230:231]
	v_pk_fma_f32 v[138:139], v[132:133], v[138:139], v[132:133]
	v_pk_fma_f32 v[150:151], v[144:145], v[150:151], v[144:145]
	v_pk_mul_f32 v[140:141], v[0:1], v[232:233]
	v_pk_mul_f32 v[152:153], v[2:3], v[232:233]
	v_cmp_ngt_f32_e32 vcc, 1.0, v132
	v_cmp_ngt_f32_e64 s[8:9], 1.0, v133
	v_readlane_b32 s6, v252, 33
	v_readlane_b32 s7, v252, 34
	v_cndmask_b32_e32 v138, v138, v134, vcc
	v_cndmask_b32_e64 v139, v139, v135, s[8:9]
	v_cmp_ngt_f32_e32 vcc, 1.0, v144
	v_cmp_ngt_f32_e64 s[8:9], 1.0, v145
	v_bfi_b32 v138, s37, v138, v130
	v_bfi_b32 v139, s37, v139, v131
	v_cndmask_b32_e32 v150, v150, v146, vcc
	v_cndmask_b32_e64 v151, v151, v147, s[8:9]
	v_pk_add_f32 v[138:139], v[138:139], v[230:231]
	v_bfi_b32 v150, s37, v150, v142
	v_bfi_b32 v151, s37, v151, v143
	v_pk_add_f32 v[150:151], v[150:151], v[230:231]
	v_pk_mul_f32 v[138:139], v[140:141], v[138:139]
	v_lshl_add_u64 v[0:1], s[6:7], 0, v[4:5]
	v_pk_mul_f32 v[150:151], v[152:153], v[150:151]
	v_lshl_add_u64 v[0:1], v[182:183], 1, v[0:1]
	v_cvt_pk_bf16_f32 v2, v138, v139
	v_cvt_pk_bf16_f32 v3, v150, v151
	v_mov_b32_e32 v250, v2
	v_mov_b32_e32 v251, v3
	v_lshl_add_u64 v[156:157], v[0:1], 0, v[154:155]
	s_nop 0
	v_permlane16_swap_b32_e32 v248, v250
	v_permlane16_swap_b32_e32 v249, v251
	global_store_dwordx4 v[156:157], v[248:251], off offset:-1984

; DI void st_bf4(u16* p, float a, float b, float c, float d) { *(uint2*)p = make_uint2(pk2(a, b), pk2(c, d)); }
;   template <int NT, int MT> DI void run(f32x4 (&acc)[NT][MT], int mb, int nb) const {
;     ...
;         if (n < 1024) {
;           st_bf4(abuf + (size_t)m * 1024 + n, v[0], v[1], v[2], v[3]);
;           float* dst = nullptr;
;           if (m < M_PROMPT) { int t = m & 8191; if (t >= 8177) dst = spp + ((size_t)((m >> 13) * 15 + (t - 8177))) * 1024 + n; }
;           else { int r = m - M_PROMPT; int s = r & 31; if (s >= 17) dst = sps + ((size_t)((r >> 5) * 15 + (s - 17))) * 1024 + n; }
;           if (dst) *(float4*)dst = make_float4(v[0], v[1], v[2], v[3]);
.LBB0_1739:
	s_andn2_saveexec_b64 s[38:39], s[40:41]
	s_cbranch_execz .LBB0_1308
	v_lshlrev_b64 v[4:5], 11, v[52:53]
	v_lshl_add_u64 v[4:5], s[96:97], 0, v[4:5]
	s_movk_i32 s5, 0x3fcf
	v_lshl_add_u64 v[4:5], v[66:67], 1, v[4:5]
	v_cvt_pk_bf16_f32 v6, v0, v1
	v_cvt_pk_bf16_f32 v7, v2, v3
	v_cmp_lt_i32_e32 vcc, s5, v64
	v_mov_b32_e32 v250, v6
	v_mov_b32_e32 v251, v7
	v_lshl_add_u64 v[156:157], v[4:5], 0, v[154:155]
	s_nop 0
	v_permlane16_swap_b32_e32 v248, v250
	v_permlane16_swap_b32_e32 v249, v251
	global_store_dwordx4 v[156:157], v[248:251], off offset:64
	s_and_saveexec_b64 s[6:7], vcc
	s_xor_b64 s[40:41], exec, s[6:7]
	s_cbranch_execz .LBB0_1757
	v_and_b32_e32 v6, 31, v52
	v_cmp_ne_u32_e32 vcc, 16, v6
	v_mov_b64_e32 v[4:5], 0
	s_and_saveexec_b64 s[46:47], vcc
	s_cbranch_execz .LBB0_1743
	v_add_u32_e32 v4, 0xffffc030, v68
	v_lshrrev_b32_e32 v4, 5, v4
	v_mul_lo_u32 v4, v4, 15
	s_movk_i32 s5, 0xffef
	v_add3_u32 v182, v6, v4, s5
	v_readlane_b32 s6, v253, 19
	v_lshlrev_b64 v[4:5], 12, v[182:183]
	v_readlane_b32 s7, v253, 20
	s_nop 1
	v_lshl_add_u64 v[4:5], s[6:7], 0, v[4:5]
	v_lshl_add_u64 v[4:5], v[66:67], 2, v[4:5]
	s_mov_b64 s[6:7], 0xc0
	v_lshl_add_u64 v[4:5], v[4:5], 0, s[6:7]
